# gate GEMM K part: s_setprio 1 as the m0-write wait state before the second DMA (s_nop removed), as in the K-loops
# baseline (speedup 1.0000x reference)
; #define PG8_STAGE(bufoff, gbase, voff) do { _Pragma("unroll") for (int _i = 0; _i < 2; ++_i) \
;         __builtin_amdgcn_global_load_lds((const unsigned*)((const char*)(gbase) + (voff)[_i]), (LAS unsigned*)(lds + (bufoff) + ldsw + _i * 8192), 16, 0, 0); } while (0)
; #define PG8_LDA(dst, b, h) do { _Pragma("unroll") for (int m = 0; m < 4; ++m) _Pragma("unroll") for (int k = 0; k < 2; ++k) dst[m][k] = *(const LAS bf16x8*)(lds + PG8_SA(b, h) + aoff + m * 2048 + k * 1024); } while (0)
; #define PG8_LDB(dst, b, h) do { _Pragma("unroll") for (int n = 0; n < 2; ++n) _Pragma("unroll") for (int k = 0; k < 2; ++k) dst[n][k] = *(const LAS bf16x8*)(lds + PG8_SB(b, h) + boff + n * 2048 + k * 1024); } while (0)
; #define PG8_WAIT_V(n) asm volatile("s_waitcnt vmcnt(" #n ")" ::: "memory")
; #define PG8_WAIT_L(n) asm volatile("s_waitcnt lgkmcnt(" #n ")" ::: "memory")
; #define PG8_BAR __builtin_amdgcn_s_barrier()
; #define PG8_SCHED __builtin_amdgcn_sched_barrier(0)
; template <class Epi>
; __device__ __forceinline__ void gemm_phase(LAS unsigned char* lds, const bf16_t* A, int lda, const bf16_t* Bt, int ldb, int M, int N, int K, int asel, const Epi& E, const int fixed_round = -1) {
;     ...
;         const bool has_next = (fixed_round < 0) && S.next(ui + 1, nxt);
;         const char* nA = has_next ? PG8_ABASE(nxt) : cA; const char* nB = has_next ? (const char*)Bt + (size_t)nxt.pn * tstepB : cB;
;         for (int t = 0; t < nt; t += 2) {
;             const bool last = (t == nt - 2);
;             const char* a1 = cA + (size_t)(t + 1) * kstep;
;             const char* a2 = last ? nA : cA + (size_t)(t + 2) * kstep; const char* b2 = last ? nB : cB + (size_t)(t + 2) * kstep;
;             const char* a3 = a2 + kstep; const char* b3 = b2 + kstep;
;             PG8_LDB(B0, 0, 0); PG8_SCHED; PG8_LDA(At, 0, 0); PG8_STAGE(PG8_SA(1, 1), a1 + hstepA, voffA);
;             PG8_WAIT_L(8); PG8_BAR; PG8_WAIT_L(0); PG8_MMA(0, 0, At, B0); PG8_BAR; PG8_SCHED;
;             PG8_LDB(B1, 0, 1); PG8_STAGE(PG8_SB(0, 0), b2, voffB);
;             PG8_BAR; PG8_WAIT_L(0); PG8_MMA(0, 1, At, B1); PG8_BAR;
;             PG8_LDA(At, 0, 1); PG8_STAGE(PG8_SA(0, 0), a2, voffA);
;             PG8_BAR; PG8_WAIT_L(0); PG8_MMA(1, 0, At, B0); PG8_BAR; PG8_SCHED;
;             PG8_STAGE(PG8_SB(0, 1), b2 + hstepB, voffB);
;             PG8_WAIT_V(6); PG8_BAR; PG8_MMA(1, 1, At, B1); PG8_BAR;
.LBB0_938:
	s_ashr_i32 s57, s56, 31
	s_lshl_b64 s[2:3], s[56:57], 20
	s_add_u32 s28, s6, s2
	s_addc_u32 s29, s7, s3
	s_ashr_i32 s2, s54, 1
	s_ashr_i32 s3, s2, 31
	s_lshl_b64 s[2:3], s[2:3], 9
	s_add_u32 s58, s28, s2
	s_addc_u32 s59, s29, s3
	ds_read_b128 v[0:3], v215
	ds_read_b128 v[4:7], v215 offset:1024
	ds_read_b128 v[8:11], v215 offset:2048
	ds_read_b128 v[12:15], v215 offset:3072
	s_and_b64 s[2:3], exec, s[0:1]
	s_cselect_b32 s3, s59, s65
	s_cselect_b32 s2, s58, s64
	s_ashr_i32 s55, s54, 31
	s_lshl_b64 s[28:29], s[54:55], 17
	s_add_u32 s60, s68, s28
	s_addc_u32 s61, s69, s29
	s_and_b64 s[0:1], exec, s[0:1]
	s_cselect_b32 s1, s61, s67
	s_cselect_b32 s0, s60, s66
	s_add_u32 s28, s64, 0x80080
	s_addc_u32 s29, s65, 0
	s_add_i32 vcc_hi, s63, 0xc000
	v_lshl_add_u64 v[48:49], s[28:29], 0, v[140:141]
	s_mov_b32 m0, vcc_hi
	s_add_i32 s55, s63, 0xe000
	ds_read_b128 v[16:19], v216
	ds_read_b128 v[20:23], v216 offset:1024
	ds_read_b128 v[24:27], v216 offset:2048
	ds_read_b128 v[28:31], v216 offset:3072
	ds_read_b128 v[32:35], v216 offset:4096
	ds_read_b128 v[36:39], v216 offset:5120
	ds_read_b128 v[40:43], v216 offset:6144
	ds_read_b128 v[44:47], v216 offset:7168
	global_load_lds_dwordx4 v[48:49], off
	v_lshl_add_u64 v[48:49], s[28:29], 0, v[144:145]
	s_mov_b32 m0, s55
	s_setprio 1
	global_load_lds_dwordx4 v[48:49], off
	s_waitcnt lgkmcnt(8)
	s_barrier
	s_waitcnt lgkmcnt(0)
	v_mfma_f32_16x16x32_bf16 v[48:51], v[0:3], v[16:19], 0
	v_mfma_f32_16x16x32_bf16 v[52:55], v[8:11], v[16:19], 0
	v_mfma_f32_16x16x32_bf16 v[56:59], v[0:3], v[24:27], 0
	v_mfma_f32_16x16x32_bf16 v[60:63], v[8:11], v[24:27], 0
	v_mfma_f32_16x16x32_bf16 v[64:67], v[0:3], v[32:35], 0
	v_mfma_f32_16x16x32_bf16 v[68:71], v[8:11], v[32:35], 0
	v_mfma_f32_16x16x32_bf16 v[72:75], v[0:3], v[40:43], 0
	v_mfma_f32_16x16x32_bf16 v[76:79], v[8:11], v[40:43], 0
	v_mfma_f32_16x16x32_bf16 v[48:51], v[4:7], v[20:23], v[48:51]
	v_mfma_f32_16x16x32_bf16 v[52:55], v[12:15], v[20:23], v[52:55]
	v_mfma_f32_16x16x32_bf16 v[56:59], v[4:7], v[28:31], v[56:59]
	v_mfma_f32_16x16x32_bf16 v[60:63], v[12:15], v[28:31], v[60:63]
	v_mfma_f32_16x16x32_bf16 v[64:67], v[4:7], v[36:39], v[64:67]
	v_mfma_f32_16x16x32_bf16 v[68:71], v[12:15], v[36:39], v[68:71]
	v_mfma_f32_16x16x32_bf16 v[72:75], v[4:7], v[44:47], v[72:75]
	v_mfma_f32_16x16x32_bf16 v[76:79], v[12:15], v[44:47], v[76:79]
	s_barrier
	s_setprio 0
	v_lshl_add_u64 v[198:199], s[66:67], 0, v[142:143]
	s_add_i32 s96, s81, s70
	v_lshl_add_u64 v[96:97], v[198:199], 0, s[46:47]
	s_mov_b32 m0, s96
	v_lshl_add_u64 v[210:211], s[66:67], 0, v[146:147]
	s_add_i32 s57, s96, 0x2000
	ds_read_b128 v[80:83], v217
	ds_read_b128 v[84:87], v217 offset:1024
	ds_read_b128 v[88:91], v217 offset:2048
	ds_read_b128 v[92:95], v217 offset:3072
	global_load_lds_dwordx4 v[96:97], off
	v_lshl_add_u64 v[96:97], v[210:211], 0, s[46:47]
	s_mov_b32 m0, s57
	s_setprio 1
	global_load_lds_dwordx4 v[96:97], off
	s_barrier
	s_waitcnt lgkmcnt(0)
	v_mfma_f32_16x16x32_bf16 v[96:99], v[80:83], v[16:19], 0
	v_mfma_f32_16x16x32_bf16 v[16:19], v[88:91], v[16:19], 0
	v_mfma_f32_16x16x32_bf16 v[96:99], v[84:87], v[20:23], v[96:99]
	v_mfma_f32_16x16x32_bf16 v[16:19], v[92:95], v[20:23], v[16:19]
	v_mfma_f32_16x16x32_bf16 v[20:23], v[80:83], v[24:27], 0
	v_mfma_f32_16x16x32_bf16 v[24:27], v[88:91], v[24:27], 0
	v_mfma_f32_16x16x32_bf16 v[20:23], v[84:87], v[28:31], v[20:23]
	v_mfma_f32_16x16x32_bf16 v[24:27], v[92:95], v[28:31], v[24:27]
	v_mfma_f32_16x16x32_bf16 v[28:31], v[80:83], v[32:35], 0
	v_mfma_f32_16x16x32_bf16 v[32:35], v[88:91], v[32:35], 0
	v_mfma_f32_16x16x32_bf16 v[28:31], v[84:87], v[36:39], v[28:31]
	v_mfma_f32_16x16x32_bf16 v[32:35], v[92:95], v[36:39], v[32:35]
	v_mfma_f32_16x16x32_bf16 v[36:39], v[80:83], v[40:43], 0
	v_mfma_f32_16x16x32_bf16 v[40:43], v[88:91], v[40:43], 0
	v_mfma_f32_16x16x32_bf16 v[36:39], v[84:87], v[44:47], v[36:39]
	v_mfma_f32_16x16x32_bf16 v[40:43], v[92:95], v[44:47], v[40:43]
	s_setprio 0
	v_lshl_add_u64 v[224:225], s[64:65], 0, v[140:141]
	s_mov_b32 m0, s63
	v_lshl_add_u64 v[128:129], v[224:225], 0, s[46:47]
	v_lshl_add_u64 v[226:227], s[64:65], 0, v[144:145]
	s_barrier
	ds_read_b128 v[44:47], v216 offset:16384
	ds_read_b128 v[100:103], v216 offset:17408
	ds_read_b128 v[104:107], v216 offset:18432
	ds_read_b128 v[108:111], v216 offset:19456
	ds_read_b128 v[112:115], v216 offset:20480
	ds_read_b128 v[116:119], v216 offset:21504
	ds_read_b128 v[120:123], v216 offset:22528
	ds_read_b128 v[124:127], v216 offset:23552
	global_load_lds_dwordx4 v[128:129], off
	v_lshl_add_u64 v[128:129], v[226:227], 0, s[46:47]
	s_mov_b32 m0, s71
	s_setprio 1
	global_load_lds_dwordx4 v[128:129], off
	s_barrier
	s_waitcnt lgkmcnt(0)
	v_mfma_f32_16x16x32_bf16 v[128:131], v[0:3], v[44:47], 0
	v_mfma_f32_16x16x32_bf16 v[136:139], v[0:3], v[104:107], 0
	v_mfma_f32_16x16x32_bf16 v[158:161], v[0:3], v[112:115], 0
	v_mfma_f32_16x16x32_bf16 v[0:3], v[0:3], v[120:123], 0
	v_mfma_f32_16x16x32_bf16 v[128:131], v[4:7], v[100:103], v[128:131]
	v_mfma_f32_16x16x32_bf16 v[132:135], v[8:11], v[44:47], 0
	v_mfma_f32_16x16x32_bf16 v[136:139], v[4:7], v[108:111], v[136:139]
	v_mfma_f32_16x16x32_bf16 v[154:157], v[8:11], v[104:107], 0
	v_mfma_f32_16x16x32_bf16 v[158:161], v[4:7], v[116:119], v[158:161]
	v_mfma_f32_16x16x32_bf16 v[162:165], v[8:11], v[112:115], 0
	v_mfma_f32_16x16x32_bf16 v[0:3], v[4:7], v[124:127], v[0:3]
	v_mfma_f32_16x16x32_bf16 v[4:7], v[8:11], v[120:123], 0
	v_mfma_f32_16x16x32_bf16 v[132:135], v[12:15], v[100:103], v[132:135]
	v_mfma_f32_16x16x32_bf16 v[154:157], v[12:15], v[108:111], v[154:157]
	v_mfma_f32_16x16x32_bf16 v[162:165], v[12:15], v[116:119], v[162:165]
	v_mfma_f32_16x16x32_bf16 v[4:7], v[12:15], v[124:127], v[4:7]
	s_barrier
; #define PG8_STAGE(bufoff, gbase, voff) do { _Pragma("unroll") for (int _i = 0; _i < 2; ++_i) \
;         __builtin_amdgcn_global_load_lds((const unsigned*)((const char*)(gbase) + (voff)[_i]), (LAS unsigned*)(lds + (bufoff) + ldsw + _i * 8192), 16, 0, 0); } while (0)
; #define PG8_LDA(dst, b, h) do { _Pragma("unroll") for (int m = 0; m < 4; ++m) _Pragma("unroll") for (int k = 0; k < 2; ++k) dst[m][k] = *(const LAS bf16x8*)(lds + PG8_SA(b, h) + aoff + m * 2048 + k * 1024); } while (0)
; #define PG8_LDB(dst, b, h) do { _Pragma("unroll") for (int n = 0; n < 2; ++n) _Pragma("unroll") for (int k = 0; k < 2; ++k) dst[n][k] = *(const LAS bf16x8*)(lds + PG8_SB(b, h) + boff + n * 2048 + k * 1024); } while (0)
; #define PG8_WAIT_V(n) asm volatile("s_waitcnt vmcnt(" #n ")" ::: "memory")
; #define PG8_WAIT_L(n) asm volatile("s_waitcnt lgkmcnt(" #n ")" ::: "memory")
; #define PG8_BAR __builtin_amdgcn_s_barrier()
; #define PG8_SCHED __builtin_amdgcn_sched_barrier(0)
; template <class Epi>
; __device__ __forceinline__ void gemm_phase(LAS unsigned char* lds, const bf16_t* A, int lda, const bf16_t* Bt, int ldb, int M, int N, int K, int asel, const Epi& E, const int fixed_round = -1) {
;     ...
;             PG8_STAGE(PG8_SB(0, 1), b2 + hstepB, voffB);
;             PG8_WAIT_V(6); PG8_BAR; PG8_MMA(1, 1, At, B1); PG8_BAR;
;             PG8_LDB(B0, 1, 0); PG8_SCHED; PG8_LDA(At, 1, 0); PG8_STAGE(PG8_SA(0, 1), a2 + hstepA, voffA);
;             PG8_WAIT_L(8); PG8_BAR; PG8_WAIT_L(0); PG8_MMA(0, 0, At, B0); PG8_BAR; PG8_SCHED;
;             PG8_LDB(B1, 1, 1); PG8_STAGE(PG8_SB(1, 0), b3, voffB);
;             PG8_BAR; PG8_WAIT_L(0); PG8_MMA(0, 1, At, B1); PG8_BAR;
;             PG8_LDA(At, 1, 1); PG8_STAGE(PG8_SA(1, 0), a3, voffA);
;             PG8_BAR; PG8_WAIT_L(0); PG8_MMA(1, 0, At, B0); PG8_BAR; PG8_SCHED;
	s_setprio 0
	s_add_u32 s28, s66, 0x10100
	s_addc_u32 s29, s67, 0
	s_add_i32 vcc_lo, s82, s70
	v_lshl_add_u64 v[8:9], s[28:29], 0, v[142:143]
	s_mov_b32 m0, vcc_lo
	s_add_i32 s95, vcc_lo, 0x2000
	global_load_lds_dwordx4 v[8:9], off
	v_lshl_add_u64 v[8:9], s[28:29], 0, v[146:147]
	s_mov_b32 m0, s95
	s_setprio 1
	global_load_lds_dwordx4 v[8:9], off
	s_waitcnt vmcnt(6)
	s_barrier
	v_mfma_f32_16x16x32_bf16 v[8:11], v[80:83], v[44:47], 0
	v_mfma_f32_16x16x32_bf16 v[12:15], v[88:91], v[44:47], 0
	v_mfma_f32_16x16x32_bf16 v[8:11], v[84:87], v[100:103], v[8:11]
	v_mfma_f32_16x16x32_bf16 v[12:15], v[92:95], v[100:103], v[12:15]
	v_mfma_f32_16x16x32_bf16 v[44:47], v[80:83], v[104:107], 0
	v_mfma_f32_16x16x32_bf16 v[100:103], v[88:91], v[104:107], 0
	v_mfma_f32_16x16x32_bf16 v[104:107], v[80:83], v[112:115], 0
	v_mfma_f32_16x16x32_bf16 v[80:83], v[80:83], v[120:123], 0
	v_mfma_f32_16x16x32_bf16 v[44:47], v[84:87], v[108:111], v[44:47]
	v_mfma_f32_16x16x32_bf16 v[100:103], v[92:95], v[108:111], v[100:103]
	v_mfma_f32_16x16x32_bf16 v[104:107], v[84:87], v[116:119], v[104:107]
	v_mfma_f32_16x16x32_bf16 v[108:111], v[88:91], v[112:115], 0
	v_mfma_f32_16x16x32_bf16 v[80:83], v[84:87], v[124:127], v[80:83]
	v_mfma_f32_16x16x32_bf16 v[84:87], v[88:91], v[120:123], 0
	v_mfma_f32_16x16x32_bf16 v[108:111], v[92:95], v[116:119], v[108:111]
	v_mfma_f32_16x16x32_bf16 v[84:87], v[92:95], v[124:127], v[84:87]
	s_barrier
	s_setprio 0
	v_add_u32_e32 v153, s83, v213
	ds_read_b128 v[88:91], v153
	ds_read_b128 v[92:95], v153 offset:1024
	ds_read_b128 v[112:115], v153 offset:2048
	ds_read_b128 v[116:119], v153 offset:3072
	s_add_u32 s28, s64, 0x80100
	s_addc_u32 s29, s65, 0
	s_mov_b32 m0, s72
	v_lshl_add_u64 v[190:191], s[28:29], 0, v[140:141]
	ds_read_b128 v[120:123], v216 offset:32768
	ds_read_b128 v[124:127], v216 offset:33792
	ds_read_b128 v[166:169], v216 offset:34816
	ds_read_b128 v[170:173], v216 offset:35840
	ds_read_b128 v[174:177], v216 offset:36864
	ds_read_b128 v[178:181], v216 offset:37888
	ds_read_b128 v[182:185], v216 offset:38912
	ds_read_b128 v[186:189], v216 offset:39936
	global_load_lds_dwordx4 v[190:191], off
	v_lshl_add_u64 v[190:191], s[28:29], 0, v[144:145]
	s_mov_b32 m0, s73
	s_setprio 1
	global_load_lds_dwordx4 v[190:191], off
	s_waitcnt lgkmcnt(8)
	s_barrier
	s_waitcnt lgkmcnt(0)
	v_mfma_f32_16x16x32_bf16 v[48:51], v[88:91], v[120:123], v[48:51]
	v_mfma_f32_16x16x32_bf16 v[52:55], v[112:115], v[120:123], v[52:55]
	v_mfma_f32_16x16x32_bf16 v[56:59], v[88:91], v[166:169], v[56:59]
	v_mfma_f32_16x16x32_bf16 v[60:63], v[112:115], v[166:169], v[60:63]
	v_mfma_f32_16x16x32_bf16 v[64:67], v[88:91], v[174:177], v[64:67]
	v_mfma_f32_16x16x32_bf16 v[68:71], v[112:115], v[174:177], v[68:71]
	v_mfma_f32_16x16x32_bf16 v[72:75], v[88:91], v[182:185], v[72:75]
	v_mfma_f32_16x16x32_bf16 v[76:79], v[112:115], v[182:185], v[76:79]
	v_mfma_f32_16x16x32_bf16 v[48:51], v[92:95], v[124:127], v[48:51]
	v_mfma_f32_16x16x32_bf16 v[52:55], v[116:119], v[124:127], v[52:55]
	v_mfma_f32_16x16x32_bf16 v[56:59], v[92:95], v[170:173], v[56:59]
	v_mfma_f32_16x16x32_bf16 v[60:63], v[116:119], v[170:173], v[60:63]
	v_mfma_f32_16x16x32_bf16 v[64:67], v[92:95], v[178:181], v[64:67]
	v_mfma_f32_16x16x32_bf16 v[68:71], v[116:119], v[178:181], v[68:71]
	v_mfma_f32_16x16x32_bf16 v[72:75], v[92:95], v[186:189], v[72:75]
	v_mfma_f32_16x16x32_bf16 v[76:79], v[116:119], v[186:189], v[76:79]
	s_barrier
	s_setprio 0
	s_add_i32 s97, s83, s70
	v_add_u32_e32 v223, s84, v213
	v_lshl_add_u64 v[198:199], v[198:199], 0, s[48:49]
	s_mov_b32 m0, s97
	s_add_i32 s28, s97, 0x2000
	ds_read_b128 v[190:193], v223
	ds_read_b128 v[194:197], v223 offset:1024
	ds_read_b128 v[202:205], v223 offset:2048
	ds_read_b128 v[206:209], v223 offset:3072
	global_load_lds_dwordx4 v[198:199], off
	v_lshl_add_u64 v[198:199], v[210:211], 0, s[48:49]
	s_mov_b32 m0, s28
	s_setprio 1
	global_load_lds_dwordx4 v[198:199], off
	s_barrier
	s_waitcnt lgkmcnt(0)
	v_mfma_f32_16x16x32_bf16 v[96:99], v[190:193], v[120:123], v[96:99]
	v_mfma_f32_16x16x32_bf16 v[16:19], v[202:205], v[120:123], v[16:19]
	v_mfma_f32_16x16x32_bf16 v[20:23], v[190:193], v[166:169], v[20:23]
	v_mfma_f32_16x16x32_bf16 v[24:27], v[202:205], v[166:169], v[24:27]
	v_mfma_f32_16x16x32_bf16 v[28:31], v[190:193], v[174:177], v[28:31]
	v_mfma_f32_16x16x32_bf16 v[32:35], v[202:205], v[174:177], v[32:35]
	v_mfma_f32_16x16x32_bf16 v[36:39], v[190:193], v[182:185], v[36:39]
	v_mfma_f32_16x16x32_bf16 v[40:43], v[202:205], v[182:185], v[40:43]
	v_mfma_f32_16x16x32_bf16 v[96:99], v[194:197], v[124:127], v[96:99]
	v_mfma_f32_16x16x32_bf16 v[16:19], v[206:209], v[124:127], v[16:19]
	v_mfma_f32_16x16x32_bf16 v[20:23], v[194:197], v[170:173], v[20:23]
	v_mfma_f32_16x16x32_bf16 v[24:27], v[206:209], v[170:173], v[24:27]
	v_mfma_f32_16x16x32_bf16 v[28:31], v[194:197], v[178:181], v[28:31]
	v_mfma_f32_16x16x32_bf16 v[32:35], v[206:209], v[178:181], v[32:35]
	v_mfma_f32_16x16x32_bf16 v[36:39], v[194:197], v[186:189], v[36:39]
	v_mfma_f32_16x16x32_bf16 v[40:43], v[206:209], v[186:189], v[40:43]
	s_setprio 0
	s_mov_b32 m0, s74
	v_lshl_add_u64 v[198:199], v[224:225], 0, s[48:49]
	s_barrier
	ds_read_b128 v[120:123], v216 offset:49152
	ds_read_b128 v[124:127], v216 offset:50176
	ds_read_b128 v[166:169], v216 offset:51200
	ds_read_b128 v[170:173], v216 offset:52224
	ds_read_b128 v[174:177], v216 offset:53248
	ds_read_b128 v[178:181], v216 offset:54272
	ds_read_b128 v[182:185], v216 offset:55296
	ds_read_b128 v[186:189], v216 offset:56320
	global_load_lds_dwordx4 v[198:199], off
	v_lshl_add_u64 v[198:199], v[226:227], 0, s[48:49]
	s_mov_b32 m0, s75
	s_setprio 1
	global_load_lds_dwordx4 v[198:199], off
	s_barrier
; #define PG8_STAGE(bufoff, gbase, voff) do { _Pragma("unroll") for (int _i = 0; _i < 2; ++_i) \
;         __builtin_amdgcn_global_load_lds((const unsigned*)((const char*)(gbase) + (voff)[_i]), (LAS unsigned*)(lds + (bufoff) + ldsw + _i * 8192), 16, 0, 0); } while (0)
; #define PG8_LDA(dst, b, h) do { _Pragma("unroll") for (int m = 0; m < 4; ++m) _Pragma("unroll") for (int k = 0; k < 2; ++k) dst[m][k] = *(const LAS bf16x8*)(lds + PG8_SA(b, h) + aoff + m * 2048 + k * 1024); } while (0)
; #define PG8_LDB(dst, b, h) do { _Pragma("unroll") for (int n = 0; n < 2; ++n) _Pragma("unroll") for (int k = 0; k < 2; ++k) dst[n][k] = *(const LAS bf16x8*)(lds + PG8_SB(b, h) + boff + n * 2048 + k * 1024); } while (0)
; #define PG8_WAIT_V(n) asm volatile("s_waitcnt vmcnt(" #n ")" ::: "memory")
; #define PG8_WAIT_L(n) asm volatile("s_waitcnt lgkmcnt(" #n ")" ::: "memory")
; #define PG8_BAR __builtin_amdgcn_s_barrier()
; #define PG8_SCHED __builtin_amdgcn_sched_barrier(0)
; template <class Epi>
; __device__ __forceinline__ void gemm_phase(LAS unsigned char* lds, const bf16_t* A, int lda, const bf16_t* Bt, int ldb, int M, int N, int K, int asel, const Epi& E, const int fixed_round = -1) {
;     ...
;             PG8_LDB(B0, 0, 0); PG8_SCHED; PG8_LDA(At, 0, 0); PG8_STAGE(PG8_SA(1, 1), a1 + hstepA, voffA);
;             PG8_WAIT_L(8); PG8_BAR; PG8_WAIT_L(0); PG8_MMA(0, 0, At, B0); PG8_BAR; PG8_SCHED;
;     ...
;             PG8_LDB(B0, 1, 0); PG8_SCHED; PG8_LDA(At, 1, 0); PG8_STAGE(PG8_SA(0, 1), a2 + hstepA, voffA);
;             PG8_WAIT_L(8); PG8_BAR; PG8_WAIT_L(0); PG8_MMA(0, 0, At, B0); PG8_BAR; PG8_SCHED;
;             PG8_LDB(B1, 1, 1); PG8_STAGE(PG8_SB(1, 0), b3, voffB);
;             PG8_BAR; PG8_WAIT_L(0); PG8_MMA(0, 1, At, B1); PG8_BAR;
;             PG8_LDA(At, 1, 1); PG8_STAGE(PG8_SA(1, 0), a3, voffA);
;             PG8_BAR; PG8_WAIT_L(0); PG8_MMA(1, 0, At, B0); PG8_BAR; PG8_SCHED;
;             PG8_STAGE(PG8_SB(1, 1), b3 + hstepB, voffB);
;             PG8_WAIT_V(6); PG8_BAR; PG8_MMA(1, 1, At, B1); PG8_BAR;
	s_waitcnt lgkmcnt(0)
	v_mfma_f32_16x16x32_bf16 v[128:131], v[88:91], v[120:123], v[128:131]
	v_mfma_f32_16x16x32_bf16 v[132:135], v[112:115], v[120:123], v[132:135]
	v_mfma_f32_16x16x32_bf16 v[136:139], v[88:91], v[166:169], v[136:139]
	v_mfma_f32_16x16x32_bf16 v[154:157], v[112:115], v[166:169], v[154:157]
	v_mfma_f32_16x16x32_bf16 v[158:161], v[88:91], v[174:177], v[158:161]
	v_mfma_f32_16x16x32_bf16 v[162:165], v[112:115], v[174:177], v[162:165]
	v_mfma_f32_16x16x32_bf16 v[0:3], v[88:91], v[182:185], v[0:3]
	v_mfma_f32_16x16x32_bf16 v[4:7], v[112:115], v[182:185], v[4:7]
	v_mfma_f32_16x16x32_bf16 v[128:131], v[92:95], v[124:127], v[128:131]
	v_mfma_f32_16x16x32_bf16 v[132:135], v[116:119], v[124:127], v[132:135]
	v_mfma_f32_16x16x32_bf16 v[136:139], v[92:95], v[170:173], v[136:139]
	v_mfma_f32_16x16x32_bf16 v[154:157], v[116:119], v[170:173], v[154:157]
	v_mfma_f32_16x16x32_bf16 v[158:161], v[92:95], v[178:181], v[158:161]
	v_mfma_f32_16x16x32_bf16 v[162:165], v[116:119], v[178:181], v[162:165]
	v_mfma_f32_16x16x32_bf16 v[0:3], v[92:95], v[186:189], v[0:3]
	v_mfma_f32_16x16x32_bf16 v[4:7], v[116:119], v[186:189], v[4:7]
	s_barrier
	s_setprio 0
	s_add_u32 s66, s66, 0x10180
	s_addc_u32 s67, s67, 0
	s_add_i32 s29, s84, s70
	v_lshl_add_u64 v[88:89], s[66:67], 0, v[142:143]
	s_mov_b32 m0, s29
	s_nop 0
	global_load_lds_dwordx4 v[88:89], off
	v_lshl_add_u64 v[88:89], s[66:67], 0, v[146:147]
	s_add_i32 s66, s29, 0x2000
	s_mov_b32 m0, s66
	s_setprio 1
	global_load_lds_dwordx4 v[88:89], off
	s_waitcnt vmcnt(6)
	s_barrier
	v_mfma_f32_16x16x32_bf16 v[8:11], v[190:193], v[120:123], v[8:11]
	v_mfma_f32_16x16x32_bf16 v[12:15], v[202:205], v[120:123], v[12:15]
	v_mfma_f32_16x16x32_bf16 v[44:47], v[190:193], v[166:169], v[44:47]
	v_mfma_f32_16x16x32_bf16 v[88:91], v[202:205], v[166:169], v[100:103]
	v_mfma_f32_16x16x32_bf16 v[92:95], v[190:193], v[174:177], v[104:107]
	v_mfma_f32_16x16x32_bf16 v[100:103], v[202:205], v[174:177], v[108:111]
	v_mfma_f32_16x16x32_bf16 v[80:83], v[190:193], v[182:185], v[80:83]
	v_mfma_f32_16x16x32_bf16 v[84:87], v[202:205], v[182:185], v[84:87]
	v_mfma_f32_16x16x32_bf16 v[8:11], v[194:197], v[124:127], v[8:11]
	v_mfma_f32_16x16x32_bf16 v[12:15], v[206:209], v[124:127], v[12:15]
	v_mfma_f32_16x16x32_bf16 v[44:47], v[194:197], v[170:173], v[44:47]
	v_mfma_f32_16x16x32_bf16 v[88:91], v[206:209], v[170:173], v[88:91]
	v_mfma_f32_16x16x32_bf16 v[92:95], v[194:197], v[178:181], v[92:95]
	v_mfma_f32_16x16x32_bf16 v[100:103], v[206:209], v[178:181], v[100:103]
	v_mfma_f32_16x16x32_bf16 v[80:83], v[194:197], v[186:189], v[80:83]
	v_mfma_f32_16x16x32_bf16 v[84:87], v[206:209], v[186:189], v[84:87]
	s_barrier
	s_setprio 0
	ds_read_b128 v[104:107], v215
	ds_read_b128 v[108:111], v215 offset:1024
	ds_read_b128 v[112:115], v215 offset:2048
	ds_read_b128 v[116:119], v215 offset:3072
	s_add_u32 s64, s64, 0x80180
	s_addc_u32 s65, s65, 0
	s_mov_b32 m0, vcc_hi
	v_lshl_add_u64 v[190:191], s[64:65], 0, v[140:141]
	ds_read_b128 v[120:123], v216
	ds_read_b128 v[124:127], v216 offset:1024
	ds_read_b128 v[166:169], v216 offset:2048
	ds_read_b128 v[170:173], v216 offset:3072
	ds_read_b128 v[174:177], v216 offset:4096
	ds_read_b128 v[178:181], v216 offset:5120
	ds_read_b128 v[182:185], v216 offset:6144
	ds_read_b128 v[186:189], v216 offset:7168
	global_load_lds_dwordx4 v[190:191], off
	v_lshl_add_u64 v[190:191], s[64:65], 0, v[144:145]
	s_mov_b32 m0, s55
	s_setprio 1
	global_load_lds_dwordx4 v[190:191], off
	s_waitcnt lgkmcnt(8)
	s_barrier
	s_waitcnt lgkmcnt(0)
	v_mfma_f32_16x16x32_bf16 v[56:59], v[104:107], v[166:169], v[56:59]
	v_mfma_f32_16x16x32_bf16 v[190:193], v[108:111], v[170:173], v[56:59]
	v_mfma_f32_16x16x32_bf16 v[56:59], v[112:115], v[166:169], v[60:63]
	v_mfma_f32_16x16x32_bf16 v[60:63], v[116:119], v[170:173], v[56:59]
	v_mfma_f32_16x16x32_bf16 v[56:59], v[104:107], v[174:177], v[64:67]
	v_mfma_f32_16x16x32_bf16 v[64:67], v[108:111], v[178:181], v[56:59]
	v_mfma_f32_16x16x32_bf16 v[56:59], v[112:115], v[174:177], v[68:71]
	v_mfma_f32_16x16x32_bf16 v[68:71], v[116:119], v[178:181], v[56:59]
	v_mfma_f32_16x16x32_bf16 v[56:59], v[104:107], v[182:185], v[72:75]
	v_mfma_f32_16x16x32_bf16 v[48:51], v[104:107], v[120:123], v[48:51]
	v_mfma_f32_16x16x32_bf16 v[52:55], v[112:115], v[120:123], v[52:55]
	v_mfma_f32_16x16x32_bf16 v[72:75], v[108:111], v[186:189], v[56:59]
	v_mfma_f32_16x16x32_bf16 v[56:59], v[112:115], v[182:185], v[76:79]
	v_mfma_f32_16x16x32_bf16 v[48:51], v[108:111], v[124:127], v[48:51]
	v_mfma_f32_16x16x32_bf16 v[52:55], v[116:119], v[124:127], v[52:55]
	v_mfma_f32_16x16x32_bf16 v[76:79], v[116:119], v[186:189], v[56:59]
	s_barrier
	s_setprio 0
	s_mov_b32 m0, s96
	v_lshl_add_u64 v[198:199], s[0:1], 0, v[142:143]
	s_nop 0
	ds_read_b128 v[56:59], v217
	ds_read_b128 v[194:197], v217 offset:1024
	ds_read_b128 v[202:205], v217 offset:2048
	ds_read_b128 v[206:209], v217 offset:3072
	global_load_lds_dwordx4 v[198:199], off
	v_lshl_add_u64 v[210:211], s[0:1], 0, v[146:147]
	s_mov_b32 m0, s57
	s_setprio 1
	global_load_lds_dwordx4 v[210:211], off
	s_barrier
; #define PG8_STAGE(bufoff, gbase, voff) do { _Pragma("unroll") for (int _i = 0; _i < 2; ++_i) \
;         __builtin_amdgcn_global_load_lds((const unsigned*)((const char*)(gbase) + (voff)[_i]), (LAS unsigned*)(lds + (bufoff) + ldsw + _i * 8192), 16, 0, 0); } while (0)
; #define PG8_LDA(dst, b, h) do { _Pragma("unroll") for (int m = 0; m < 4; ++m) _Pragma("unroll") for (int k = 0; k < 2; ++k) dst[m][k] = *(const LAS bf16x8*)(lds + PG8_SA(b, h) + aoff + m * 2048 + k * 1024); } while (0)
; #define PG8_LDB(dst, b, h) do { _Pragma("unroll") for (int n = 0; n < 2; ++n) _Pragma("unroll") for (int k = 0; k < 2; ++k) dst[n][k] = *(const LAS bf16x8*)(lds + PG8_SB(b, h) + boff + n * 2048 + k * 1024); } while (0)
; #define PG8_WAIT_V(n) asm volatile("s_waitcnt vmcnt(" #n ")" ::: "memory")
; #define PG8_WAIT_L(n) asm volatile("s_waitcnt lgkmcnt(" #n ")" ::: "memory")
; #define PG8_BAR __builtin_amdgcn_s_barrier()
; #define PG8_SCHED __builtin_amdgcn_sched_barrier(0)
; template <class Epi>
; __device__ __forceinline__ void gemm_phase(LAS unsigned char* lds, const bf16_t* A, int lda, const bf16_t* Bt, int ldb, int M, int N, int K, int asel, const Epi& E, const int fixed_round = -1) {
;     ...
;             PG8_LDB(B1, 0, 1); PG8_STAGE(PG8_SB(0, 0), b2, voffB);
;             PG8_BAR; PG8_WAIT_L(0); PG8_MMA(0, 1, At, B1); PG8_BAR;
;             PG8_LDA(At, 0, 1); PG8_STAGE(PG8_SA(0, 0), a2, voffA);
;             PG8_BAR; PG8_WAIT_L(0); PG8_MMA(1, 0, At, B0); PG8_BAR; PG8_SCHED;
;             PG8_STAGE(PG8_SB(0, 1), b2 + hstepB, voffB);
;             PG8_WAIT_V(6); PG8_BAR; PG8_MMA(1, 1, At, B1); PG8_BAR;
;             PG8_LDB(B0, 1, 0); PG8_SCHED; PG8_LDA(At, 1, 0); PG8_STAGE(PG8_SA(0, 1), a2 + hstepA, voffA);
;             PG8_WAIT_L(8); PG8_BAR; PG8_WAIT_L(0); PG8_MMA(0, 0, At, B0); PG8_BAR; PG8_SCHED;
;             PG8_LDB(B1, 1, 1); PG8_STAGE(PG8_SB(1, 0), b3, voffB);
;             PG8_BAR; PG8_WAIT_L(0); PG8_MMA(0, 1, At, B1); PG8_BAR;
	s_waitcnt lgkmcnt(0)
	v_mfma_f32_16x16x32_bf16 v[32:35], v[202:205], v[174:177], v[32:35]
	v_mfma_f32_16x16x32_bf16 v[20:23], v[56:59], v[166:169], v[20:23]
	v_mfma_f32_16x16x32_bf16 v[24:27], v[202:205], v[166:169], v[24:27]
	v_mfma_f32_16x16x32_bf16 v[166:169], v[206:209], v[178:181], v[32:35]
	v_mfma_f32_16x16x32_bf16 v[32:35], v[56:59], v[182:185], v[36:39]
	v_mfma_f32_16x16x32_bf16 v[96:99], v[56:59], v[120:123], v[96:99]
	v_mfma_f32_16x16x32_bf16 v[16:19], v[202:205], v[120:123], v[16:19]
	v_mfma_f32_16x16x32_bf16 v[28:31], v[56:59], v[174:177], v[28:31]
	v_mfma_f32_16x16x32_bf16 v[36:39], v[194:197], v[186:189], v[32:35]
	v_mfma_f32_16x16x32_bf16 v[32:35], v[202:205], v[182:185], v[40:43]
	v_mfma_f32_16x16x32_bf16 v[96:99], v[194:197], v[124:127], v[96:99]
	v_mfma_f32_16x16x32_bf16 v[16:19], v[206:209], v[124:127], v[16:19]
	v_mfma_f32_16x16x32_bf16 v[20:23], v[194:197], v[170:173], v[20:23]
	v_mfma_f32_16x16x32_bf16 v[24:27], v[206:209], v[170:173], v[24:27]
	v_mfma_f32_16x16x32_bf16 v[28:31], v[194:197], v[178:181], v[28:31]
	v_mfma_f32_16x16x32_bf16 v[170:173], v[206:209], v[186:189], v[32:35]
	s_setprio 0
	s_mov_b32 m0, s63
	v_lshl_add_u64 v[252:253], s[2:3], 0, v[140:141]
	s_barrier
	ds_read_b128 v[32:35], v216 offset:16384
	ds_read_b128 v[40:43], v216 offset:17408
	ds_read_b128 v[120:123], v216 offset:18432
	ds_read_b128 v[124:127], v216 offset:19456
	ds_read_b128 v[174:177], v216 offset:20480
	ds_read_b128 v[178:181], v216 offset:21504
	ds_read_b128 v[182:185], v216 offset:22528
	ds_read_b128 v[186:189], v216 offset:23552
	global_load_lds_dwordx4 v[252:253], off
	v_lshl_add_u64 v[148:149], s[2:3], 0, v[144:145]
	s_mov_b32 m0, s71
	s_setprio 1
	global_load_lds_dwordx4 v[148:149], off
	s_barrier
	s_waitcnt lgkmcnt(0)
	v_mfma_f32_16x16x32_bf16 v[128:131], v[104:107], v[32:35], v[128:131]
	v_mfma_f32_16x16x32_bf16 v[224:227], v[108:111], v[40:43], v[128:131]
	v_mfma_f32_16x16x32_bf16 v[128:131], v[112:115], v[32:35], v[132:135]
	v_mfma_f32_16x16x32_bf16 v[228:231], v[116:119], v[40:43], v[128:131]
	v_mfma_f32_16x16x32_bf16 v[128:131], v[104:107], v[120:123], v[136:139]
	v_mfma_f32_16x16x32_bf16 v[136:139], v[108:111], v[124:127], v[128:131]
	v_mfma_f32_16x16x32_bf16 v[128:131], v[112:115], v[120:123], v[154:157]
	v_mfma_f32_16x16x32_bf16 v[154:157], v[116:119], v[124:127], v[128:131]
	v_mfma_f32_16x16x32_bf16 v[128:131], v[104:107], v[174:177], v[158:161]
	v_mfma_f32_16x16x32_bf16 v[158:161], v[108:111], v[178:181], v[128:131]
	v_mfma_f32_16x16x32_bf16 v[128:131], v[112:115], v[174:177], v[162:165]
	v_mfma_f32_16x16x32_bf16 v[0:3], v[104:107], v[182:185], v[0:3]
	v_mfma_f32_16x16x32_bf16 v[4:7], v[112:115], v[182:185], v[4:7]
	v_mfma_f32_16x16x32_bf16 v[162:165], v[116:119], v[178:181], v[128:131]
	v_mfma_f32_16x16x32_bf16 v[0:3], v[108:111], v[186:189], v[0:3]
	v_mfma_f32_16x16x32_bf16 v[4:7], v[116:119], v[186:189], v[4:7]
	s_barrier
	s_setprio 0
	s_add_u32 s64, s0, 0x10000
	s_addc_u32 s65, s1, 0
	s_mov_b32 m0, vcc_lo
	v_lshl_add_u64 v[104:105], s[64:65], 0, v[142:143]
	global_load_lds_dwordx4 v[104:105], off
	v_lshl_add_u64 v[104:105], s[64:65], 0, v[146:147]
	s_mov_b32 m0, s95
	s_setprio 1
	global_load_lds_dwordx4 v[104:105], off
	s_waitcnt vmcnt(6)
	s_barrier
	v_mfma_f32_16x16x32_bf16 v[8:11], v[56:59], v[32:35], v[8:11]
	v_mfma_f32_16x16x32_bf16 v[232:235], v[194:197], v[40:43], v[8:11]
	v_mfma_f32_16x16x32_bf16 v[8:11], v[202:205], v[32:35], v[12:15]
	v_mfma_f32_16x16x32_bf16 v[12:15], v[206:209], v[40:43], v[8:11]
	v_mfma_f32_16x16x32_bf16 v[8:11], v[56:59], v[120:123], v[44:47]
	v_mfma_f32_16x16x32_bf16 v[236:239], v[194:197], v[124:127], v[8:11]
	v_mfma_f32_16x16x32_bf16 v[8:11], v[202:205], v[120:123], v[88:91]
	v_mfma_f32_16x16x32_bf16 v[240:243], v[206:209], v[124:127], v[8:11]
	v_mfma_f32_16x16x32_bf16 v[8:11], v[56:59], v[174:177], v[92:95]
	v_mfma_f32_16x16x32_bf16 v[244:247], v[194:197], v[178:181], v[8:11]
	v_mfma_f32_16x16x32_bf16 v[8:11], v[202:205], v[174:177], v[100:103]
	v_mfma_f32_16x16x32_bf16 v[174:177], v[206:209], v[178:181], v[8:11]
	v_mfma_f32_16x16x32_bf16 v[8:11], v[56:59], v[182:185], v[80:83]
	v_mfma_f32_16x16x32_bf16 v[178:181], v[194:197], v[186:189], v[8:11]
	v_mfma_f32_16x16x32_bf16 v[8:11], v[202:205], v[182:185], v[84:87]
	v_mfma_f32_16x16x32_bf16 v[182:185], v[206:209], v[186:189], v[8:11]
	s_barrier
	s_setprio 0
	ds_read_b128 v[84:87], v153
	ds_read_b128 v[92:95], v153 offset:1024
	ds_read_b128 v[100:103], v153 offset:2048
	ds_read_b128 v[186:189], v153 offset:3072
	s_add_u32 s2, s2, 0x80000
	s_addc_u32 s3, s3, 0
	s_mov_b32 m0, s72
	v_lshl_add_u64 v[32:33], s[2:3], 0, v[140:141]
	ds_read_b128 v[8:11], v216 offset:32768
	ds_read_b128 v[44:47], v216 offset:33792
	ds_read_b128 v[80:83], v216 offset:34816
	ds_read_b128 v[88:91], v216 offset:35840
	ds_read_b128 v[108:111], v216 offset:36864
	ds_read_b128 v[194:197], v216 offset:37888
	ds_read_b128 v[202:205], v216 offset:38912
	ds_read_b128 v[206:209], v216 offset:39936
	global_load_lds_dwordx4 v[32:33], off
	v_lshl_add_u64 v[32:33], s[2:3], 0, v[144:145]
	s_mov_b32 m0, s73
	s_setprio 1
	global_load_lds_dwordx4 v[32:33], off
	s_waitcnt lgkmcnt(8)
	s_barrier
; #define PG8_STAGE(bufoff, gbase, voff) do { _Pragma("unroll") for (int _i = 0; _i < 2; ++_i) \
;         __builtin_amdgcn_global_load_lds((const unsigned*)((const char*)(gbase) + (voff)[_i]), (LAS unsigned*)(lds + (bufoff) + ldsw + _i * 8192), 16, 0, 0); } while (0)
; #define PG8_LDA(dst, b, h) do { _Pragma("unroll") for (int m = 0; m < 4; ++m) _Pragma("unroll") for (int k = 0; k < 2; ++k) dst[m][k] = *(const LAS bf16x8*)(lds + PG8_SA(b, h) + aoff + m * 2048 + k * 1024); } while (0)
; #define PG8_WAIT_V(n) asm volatile("s_waitcnt vmcnt(" #n ")" ::: "memory")
; #define PG8_WAIT_L(n) asm volatile("s_waitcnt lgkmcnt(" #n ")" ::: "memory")
; #define PG8_BAR __builtin_amdgcn_s_barrier()
; #define PG8_SCHED __builtin_amdgcn_sched_barrier(0)
; template <class Epi>
; __device__ __forceinline__ void gemm_phase(LAS unsigned char* lds, const bf16_t* A, int lda, const bf16_t* Bt, int ldb, int M, int N, int K, int asel, const Epi& E, const int fixed_round = -1) {
;     ...
;             PG8_BAR; PG8_WAIT_L(0); PG8_MMA(0, 1, At, B1); PG8_BAR;
;             PG8_LDA(At, 1, 1); PG8_STAGE(PG8_SA(1, 0), a3, voffA);
;             PG8_BAR; PG8_WAIT_L(0); PG8_MMA(1, 0, At, B0); PG8_BAR; PG8_SCHED;
;             PG8_STAGE(PG8_SB(1, 1), b3 + hstepB, voffB);
;             PG8_WAIT_V(6); PG8_BAR; PG8_MMA(1, 1, At, B1); PG8_BAR;
	s_waitcnt lgkmcnt(0)
	v_mfma_f32_16x16x32_bf16 v[32:35], v[84:87], v[8:11], v[48:51]
	v_mfma_f32_16x16x32_bf16 v[128:131], v[92:95], v[44:47], v[32:35]
	v_mfma_f32_16x16x32_bf16 v[32:35], v[100:103], v[8:11], v[52:55]
	v_mfma_f32_16x16x32_bf16 v[56:59], v[186:189], v[44:47], v[32:35]
	v_mfma_f32_16x16x32_bf16 v[32:35], v[84:87], v[80:83], v[190:193]
	v_mfma_f32_16x16x32_bf16 v[120:123], v[92:95], v[88:91], v[32:35]
	v_mfma_f32_16x16x32_bf16 v[32:35], v[100:103], v[80:83], v[60:63]
	v_mfma_f32_16x16x32_bf16 v[48:51], v[186:189], v[88:91], v[32:35]
	v_mfma_f32_16x16x32_bf16 v[32:35], v[84:87], v[108:111], v[64:67]
	v_mfma_f32_16x16x32_bf16 v[112:115], v[92:95], v[194:197], v[32:35]
	v_mfma_f32_16x16x32_bf16 v[32:35], v[100:103], v[108:111], v[68:71]
	v_mfma_f32_16x16x32_bf16 v[40:43], v[186:189], v[194:197], v[32:35]
	v_mfma_f32_16x16x32_bf16 v[32:35], v[84:87], v[202:205], v[72:75]
	v_mfma_f32_16x16x32_bf16 v[104:107], v[92:95], v[206:209], v[32:35]
	v_mfma_f32_16x16x32_bf16 v[32:35], v[100:103], v[202:205], v[76:79]
	v_mfma_f32_16x16x32_bf16 v[32:35], v[186:189], v[206:209], v[32:35]
	s_barrier
	s_setprio 0
	s_mov_b32 m0, s97
	v_lshl_add_u64 v[52:53], v[198:199], 0, s[44:45]
	ds_read_b128 v[68:71], v223
	ds_read_b128 v[72:75], v223 offset:1024
	ds_read_b128 v[76:79], v223 offset:2048
	ds_read_b128 v[190:193], v223 offset:3072
	global_load_lds_dwordx4 v[52:53], off
	v_lshl_add_u64 v[52:53], v[210:211], 0, s[44:45]
	s_mov_b32 m0, s28
	s_setprio 1
	global_load_lds_dwordx4 v[52:53], off
	s_barrier
	s_waitcnt lgkmcnt(0)
	v_mfma_f32_16x16x32_bf16 v[52:55], v[68:71], v[8:11], v[96:99]
	v_mfma_f32_16x16x32_bf16 v[8:11], v[76:79], v[8:11], v[16:19]
	v_mfma_f32_16x16x32_bf16 v[60:63], v[190:193], v[44:47], v[8:11]
	v_mfma_f32_16x16x32_bf16 v[8:11], v[68:71], v[80:83], v[20:23]
	v_mfma_f32_16x16x32_bf16 v[124:127], v[72:75], v[88:91], v[8:11]
	v_mfma_f32_16x16x32_bf16 v[8:11], v[76:79], v[80:83], v[24:27]
	v_mfma_f32_16x16x32_bf16 v[132:135], v[72:75], v[44:47], v[52:55]
	v_mfma_f32_16x16x32_bf16 v[52:55], v[190:193], v[88:91], v[8:11]
	v_mfma_f32_16x16x32_bf16 v[8:11], v[68:71], v[108:111], v[28:31]
	v_mfma_f32_16x16x32_bf16 v[116:119], v[72:75], v[194:197], v[8:11]
	v_mfma_f32_16x16x32_bf16 v[8:11], v[76:79], v[108:111], v[166:169]
	v_mfma_f32_16x16x32_bf16 v[44:47], v[190:193], v[194:197], v[8:11]
	v_mfma_f32_16x16x32_bf16 v[8:11], v[68:71], v[202:205], v[36:39]
	v_mfma_f32_16x16x32_bf16 v[108:111], v[72:75], v[206:209], v[8:11]
	v_mfma_f32_16x16x32_bf16 v[8:11], v[76:79], v[202:205], v[170:173]
	v_mfma_f32_16x16x32_bf16 v[36:39], v[190:193], v[206:209], v[8:11]
	s_setprio 0
	s_mov_b32 m0, s74
	s_nop 4
	v_lshl_add_u64 v[8:9], v[252:253], 0, s[44:45]
	s_barrier
	ds_read_b128 v[20:23], v216 offset:49152
	ds_read_b128 v[28:31], v216 offset:50176
	ds_read_b128 v[166:169], v216 offset:51200
	ds_read_b128 v[170:173], v216 offset:52224
	ds_read_b128 v[194:197], v216 offset:53248
	ds_read_b128 v[202:205], v216 offset:54272
	ds_read_b128 v[206:209], v216 offset:55296
	ds_read_b128 v[248:251], v216 offset:56320
	global_load_lds_dwordx4 v[8:9], off
	v_lshl_add_u64 v[8:9], v[148:149], 0, s[44:45]
	s_mov_b32 m0, s75
	s_setprio 1
	global_load_lds_dwordx4 v[8:9], off
	s_barrier
	s_waitcnt lgkmcnt(0)
	v_mfma_f32_16x16x32_bf16 v[8:11], v[84:87], v[20:23], v[224:227]
	v_mfma_f32_16x16x32_bf16 v[96:99], v[92:95], v[28:31], v[8:11]
	v_mfma_f32_16x16x32_bf16 v[8:11], v[100:103], v[20:23], v[228:231]
	v_mfma_f32_16x16x32_bf16 v[24:27], v[186:189], v[28:31], v[8:11]
	v_mfma_f32_16x16x32_bf16 v[8:11], v[84:87], v[166:169], v[136:139]
	v_mfma_f32_16x16x32_bf16 v[88:91], v[92:95], v[170:173], v[8:11]
	v_mfma_f32_16x16x32_bf16 v[8:11], v[100:103], v[166:169], v[154:157]
	v_mfma_f32_16x16x32_bf16 v[16:19], v[186:189], v[170:173], v[8:11]
	v_mfma_f32_16x16x32_bf16 v[8:11], v[84:87], v[194:197], v[158:161]
	v_mfma_f32_16x16x32_bf16 v[0:3], v[84:87], v[206:209], v[0:3]
	v_mfma_f32_16x16x32_bf16 v[80:83], v[92:95], v[202:205], v[8:11]
	v_mfma_f32_16x16x32_bf16 v[8:11], v[100:103], v[194:197], v[162:165]
	v_mfma_f32_16x16x32_bf16 v[64:67], v[92:95], v[248:251], v[0:3]
	v_mfma_f32_16x16x32_bf16 v[0:3], v[100:103], v[206:209], v[4:7]
	v_mfma_f32_16x16x32_bf16 v[8:11], v[186:189], v[202:205], v[8:11]
	v_mfma_f32_16x16x32_bf16 v[0:3], v[186:189], v[248:251], v[0:3]
	s_barrier
	s_setprio 0
	s_add_u32 s0, s0, 0x10080
	s_addc_u32 s1, s1, 0
	s_mov_b32 m0, s29
	v_lshl_add_u64 v[4:5], s[0:1], 0, v[142:143]
	global_load_lds_dwordx4 v[4:5], off
	v_lshl_add_u64 v[4:5], s[0:1], 0, v[146:147]
	s_mov_b32 m0, s66
	s_setprio 1
	global_load_lds_dwordx4 v[4:5], off
	s_waitcnt vmcnt(6)
	s_barrier
; #define LAS __attribute__((address_space(3)))
; #define PG8_WAIT_V(n) asm volatile("s_waitcnt vmcnt(" #n ")" ::: "memory")
; #define PG8_BAR __builtin_amdgcn_s_barrier()
; template <class Epi>
; __device__ __forceinline__ void gemm_phase(LAS unsigned char* lds, const bf16_t* A, int lda, const bf16_t* Bt, int ldb, int M, int N, int K, int asel, const Epi& E, const int fixed_round = -1) {
;     ...
;             PG8_WAIT_V(6); PG8_BAR; PG8_MMA(1, 1, At, B1); PG8_BAR;
;             if constexpr (Epi::HEADSCALE) {
;                 if (t & 2) {
;                     const LAS float* rt = (const LAS float*)(lds + L_RT) + (t >> 2);
; #pragma unroll
;                     for (int ai = 0; ai < 2; ++ai)
; #pragma unroll
;                         for (int m = 0; m < 4; ++m) { const float f = rt[(ai * HALF + wr * 64 + m * 16 + fr) * 8];
; #pragma unroll
;                             for (int bj = 0; bj < 2; ++bj)
; #pragma unroll
;                                 for (int n = 0; n < 2; ++n) acc[ai][bj][m][n] *= f; }
;                 }
;             }
;         }
;         if constexpr (!Epi::AFTER_DRAIN) E(acc, cur, wr, wc, fr, fq);
;         if (!has_next) break;
; #pragma unroll
;         for (int a = 0; a < 2; ++a)
; #pragma unroll
;             for (int b = 0; b < 2; ++b)
; #pragma unroll
;                 for (int m = 0; m < 4; ++m)
; #pragma unroll
;                     for (int n = 0; n < 2; ++n) acc[a][b][m][n] = (f32x4){0.f, 0.f, 0.f, 0.f};
;         cur = nxt; cA = nA; cB = nB; ++ui;
;     __device__ __forceinline__ void operator()(const AccT& acc, const Unit& u, int wr, int wc, int fr, int fq) const {
;         const int row0 = u.pm * BM + wr * 64 + fr, ch0 = u.pn * HALF + wc * 32 + 4 * fq;
; #pragma unroll
;         for (int n = 0; n < 2; ++n) {
;             u32x2 xw[2][4];
; #pragma unroll
;             for (int ai = 0; ai < 2; ++ai)
; #pragma unroll
;                 for (int m = 0; m < 4; ++m) xw[ai][m] = *(const u32x2*)(XC + (size_t)(row0 + ai * HALF + m * 16) * DM + ch0 + 16 * n);
;             const f32x4 bra = *(const f32x4*)(b_ra + ch0 + 16 * n), bri = *(const f32x4*)(b_ri + ch0 + 16 * n), l = *(const f32x4*)(lam + ch0 + 16 * n);
;             f32x4 sp;
; #pragma unroll
;             for (int j = 0; j < 4; ++j) sp[j] = -8.0f * log1pf(__expf(-l[j]));
	v_mfma_f32_16x16x32_bf16 v[4:7], v[68:71], v[20:23], v[232:235]
	v_mfma_f32_16x16x32_bf16 v[100:103], v[72:75], v[28:31], v[4:7]
	v_mfma_f32_16x16x32_bf16 v[4:7], v[76:79], v[20:23], v[12:15]
	v_mfma_f32_16x16x32_bf16 v[28:31], v[190:193], v[28:31], v[4:7]
	v_mfma_f32_16x16x32_bf16 v[4:7], v[68:71], v[166:169], v[236:239]
	v_mfma_f32_16x16x32_bf16 v[92:95], v[72:75], v[170:173], v[4:7]
	v_mfma_f32_16x16x32_bf16 v[4:7], v[76:79], v[166:169], v[240:243]
	v_mfma_f32_16x16x32_bf16 v[20:23], v[190:193], v[170:173], v[4:7]
	v_mfma_f32_16x16x32_bf16 v[4:7], v[68:71], v[194:197], v[244:247]
	v_mfma_f32_16x16x32_bf16 v[84:87], v[72:75], v[202:205], v[4:7]
	v_mfma_f32_16x16x32_bf16 v[4:7], v[76:79], v[194:197], v[174:177]
	v_mfma_f32_16x16x32_bf16 v[12:15], v[190:193], v[202:205], v[4:7]
	v_mfma_f32_16x16x32_bf16 v[4:7], v[68:71], v[206:209], v[178:181]
	v_mfma_f32_16x16x32_bf16 v[68:71], v[72:75], v[248:251], v[4:7]
	v_mfma_f32_16x16x32_bf16 v[4:7], v[76:79], v[206:209], v[182:185]
	v_mfma_f32_16x16x32_bf16 v[4:7], v[190:193], v[248:251], v[4:7]
	s_setprio 0
	v_readlane_b32 s8, v254, 8
	v_lshl_or_b32 v72, s94, 7, v214
	v_readlane_b32 s12, v254, 12
	v_readlane_b32 s13, v254, 13
	v_readlane_b32 s14, v254, 14
	v_readlane_b32 s15, v254, 15
	v_readlane_b32 s20, v254, 20
	v_readlane_b32 s21, v254, 21
	v_ashrrev_i32_e32 v73, 31, v72
	v_readlane_b32 s22, v254, 22
	v_readlane_b32 s23, v254, 23
	s_mov_b64 s[12:13], s[20:21]
	v_lshlrev_b64 v[174:175], 2, v[72:73]
	s_mov_b64 s[14:15], s[22:23]
	v_lshl_add_u64 v[172:173], s[14:15], 0, v[174:175]
	global_load_dwordx4 v[136:139], v[172:173], off
	v_lshl_add_u32 v206, s62, 8, v212
	v_ashrrev_i32_e32 v207, 31, v206
	v_or_b32_e32 v202, 16, v206
	v_lshl_add_u64 v[74:75], v[72:73], 1, s[6:7]
	v_lshlrev_b64 v[76:77], 12, v[206:207]
	v_ashrrev_i32_e32 v203, 31, v202
	v_or_b32_e32 v196, 32, v206
	v_lshl_add_u64 v[154:155], v[74:75], 0, v[76:77]
	v_lshlrev_b64 v[76:77], 12, v[202:203]
	v_ashrrev_i32_e32 v197, 31, v196
	v_or_b32_e32 v192, 48, v206
	v_lshl_add_u64 v[156:157], v[74:75], 0, v[76:77]
	v_lshlrev_b64 v[76:77], 12, v[196:197]
	v_ashrrev_i32_e32 v193, 31, v192
	v_add_u32_e32 v188, 0x80, v206
	v_lshl_add_u64 v[158:159], v[74:75], 0, v[76:77]
	v_lshlrev_b64 v[76:77], 12, v[192:193]
	v_ashrrev_i32_e32 v189, 31, v188
	v_add_u32_e32 v184, 0x90, v206
	v_lshl_add_u64 v[160:161], v[74:75], 0, v[76:77]
	v_lshlrev_b64 v[76:77], 12, v[188:189]
	v_ashrrev_i32_e32 v185, 31, v184
	v_add_u32_e32 v180, 0xa0, v206
	v_lshl_add_u64 v[162:163], v[74:75], 0, v[76:77]
	v_lshlrev_b64 v[76:77], 12, v[184:185]
	v_ashrrev_i32_e32 v181, 31, v180
	v_add_u32_e32 v170, 0xb0, v206
	v_readlane_b32 s9, v254, 9
	v_readlane_b32 s16, v254, 16
	v_readlane_b32 s17, v254, 17
	v_lshl_add_u64 v[164:165], v[74:75], 0, v[76:77]
	v_lshlrev_b64 v[76:77], 12, v[180:181]
	v_ashrrev_i32_e32 v171, 31, v170
	s_mov_b64 s[8:9], s[16:17]
	v_lshl_add_u64 v[166:167], v[74:75], 0, v[76:77]
	v_lshlrev_b64 v[76:77], 12, v[170:171]
	v_lshl_add_u64 v[176:177], s[8:9], 0, v[174:175]
	v_lshl_add_u64 v[168:169], v[74:75], 0, v[76:77]
	global_load_dwordx4 v[76:79], v[176:177], off
	v_lshl_add_u64 v[178:179], s[12:13], 0, v[174:175]
	global_load_dwordx4 v[72:75], v[178:179], off
	global_load_dwordx2 v[210:211], v[154:155], off
	global_load_dwordx2 v[208:209], v[156:157], off
	global_load_dwordx2 v[204:205], v[158:159], off
	global_load_dwordx2 v[198:199], v[160:161], off
	global_load_dwordx2 v[194:195], v[162:163], off
	global_load_dwordx2 v[190:191], v[164:165], off
	global_load_dwordx2 v[186:187], v[166:167], off
	global_load_dwordx2 v[182:183], v[168:169], off
	v_readlane_b32 s96, v254, 58
	s_mov_b64 s[2:3], s[52:53]
	s_mov_b32 s94, s54
	s_mov_b32 s62, s56
	s_mov_b64 s[66:67], s[60:61]
	s_mov_b64 s[64:65], s[58:59]
	v_readlane_b32 s97, v254, 59
	v_readlane_b32 s10, v254, 10
	v_readlane_b32 s11, v254, 11
	v_readlane_b32 s18, v254, 18
	v_readlane_b32 s19, v254, 19
	s_barrier
	s_waitcnt vmcnt(0)
	v_mul_f32_e32 v136, 0xbfb8aa3b, v136
	v_exp_f32_e32 v136, v136
	v_mul_f32_e32 v137, 0xbfb8aa3b, v137
	v_exp_f32_e32 v137, v137
	v_mul_f32_e32 v138, 0xbfb8aa3b, v138
	v_add_f32_e32 v153, 1.0, v136
	v_add_f32_e32 v148, -1.0, v153
	v_sub_f32_e32 v149, v148, v153
	v_add_f32_e32 v149, 1.0, v149
	v_sub_f32_e32 v148, v136, v148
	v_add_f32_e32 v223, v148, v149
	v_frexp_mant_f32_e32 v148, v153
	v_cmp_gt_f32_e32 vcc, s76, v148
	v_cvt_f64_f32_e32 v[148:149], v153
	v_frexp_exp_i32_f64_e32 v148, v[148:149]
	v_subbrev_co_u32_e32 v230, vcc, 0, v148, vcc
	v_sub_u32_e32 v148, 0, v230
	v_ldexp_f32 v149, v153, v148
	v_add_f32_e32 v153, -1.0, v149
	v_add_f32_e32 v224, 1.0, v149
	v_ldexp_f32 v148, v223, v148
	v_add_f32_e32 v223, 1.0, v153
	v_add_f32_e32 v225, -1.0, v224
	v_sub_f32_e32 v223, v149, v223
	v_sub_f32_e32 v149, v149, v225
	v_add_f32_e32 v223, v148, v223
	v_add_f32_e32 v148, v148, v149
	v_add_f32_e32 v231, v224, v148
	v_rcp_f32_e32 v233, v231
	v_sub_f32_e32 v149, v231, v224
	v_sub_f32_e32 v232, v148, v149
	v_add_f32_e32 v149, v153, v223
	v_sub_f32_e32 v148, v149, v153
	v_sub_f32_e32 v153, v223, v148
	v_mul_f32_e32 v223, v149, v233
	v_mul_f32_e32 v224, v231, v223
	v_fma_f32 v226, v223, v231, -v224
	v_fmac_f32_e32 v226, v223, v232
	v_add_f32_e32 v148, v224, v226
	v_sub_f32_e32 v225, v149, v148
	v_pk_add_f32 v[228:229], v[148:149], v[224:225] neg_lo:[0,1] neg_hi:[0,1]
	v_mov_b32_e32 v227, v148
	v_pk_add_f32 v[148:149], v[228:229], v[226:227] neg_lo:[0,1] neg_hi:[0,1]
	v_cmp_neq_f32_e32 vcc, s78, v136
	v_add_f32_e32 v149, v153, v149
	v_add_f32_e32 v148, v148, v149
	v_add_f32_e32 v149, v225, v148
	v_mul_f32_e32 v153, v233, v149
	v_mul_f32_e32 v224, v231, v153
	v_fma_f32 v226, v153, v231, -v224
; __device__ __forceinline__ float bf_lo(unsigned w) { return __uint_as_float(w << 16); }
; __device__ __forceinline__ float bf_hi(unsigned w) { return __uint_as_float(w & 0xffff0000u); }
;     __device__ __forceinline__ void operator()(const AccT& acc, const Unit& u, int wr, int wc, int fr, int fq) const {
;     ...
;             const f32x4 bra = *(const f32x4*)(b_ra + ch0 + 16 * n), bri = *(const f32x4*)(b_ri + ch0 + 16 * n), l = *(const f32x4*)(lam + ch0 + 16 * n);
;             f32x4 sp;
; #pragma unroll
;             for (int j = 0; j < 4; ++j) sp[j] = -8.0f * log1pf(__expf(-l[j]));
; #pragma unroll
;             for (int ai = 0; ai < 2; ++ai)
; #pragma unroll
;                 for (int m = 0; m < 4; ++m) { const size_t off = (size_t)(row0 + ai * HALF + m * 16) * DM + ch0 + 16 * n;
;                     const f32x4 rp = acc[ai][0][m][n] + bra, ip = acc[ai][1][m][n] + bri;
;                     const u32x2 w = xw[ai][m]; const float xv[4] = {bf_lo(w.x), bf_hi(w.x), bf_lo(w.y), bf_hi(w.y)};
;                     u32x4 o;
; #pragma unroll
;                     for (int j = 0; j < 4; ++j) { const float r = __builtin_amdgcn_rcpf(1.0f + __expf(-rp[j])), ig = __builtin_amdgcn_rcpf(1.0f + __expf(-ip[j])); const float la = sp[j] * r; const float d = 1.0f - __expf(la);
	v_fmac_f32_e32 v226, v153, v232
	v_sub_f32_e32 v225, v225, v149
	v_add_f32_e32 v231, v148, v225
	v_add_f32_e32 v148, v224, v226
	v_sub_f32_e32 v225, v149, v148
	v_pk_add_f32 v[228:229], v[148:149], v[224:225] neg_lo:[0,1] neg_hi:[0,1]
	v_mov_b32_e32 v227, v148
	v_pk_add_f32 v[148:149], v[228:229], v[226:227] neg_lo:[0,1] neg_hi:[0,1]
	v_exp_f32_e32 v138, v138
	v_add_f32_e32 v149, v231, v149
	v_add_f32_e32 v148, v148, v149
	v_add_f32_e32 v149, v223, v153
	v_add_f32_e32 v148, v225, v148
	v_sub_f32_e32 v223, v149, v223
	v_mul_f32_e32 v148, v233, v148
	v_sub_f32_e32 v153, v153, v223
	v_add_f32_e32 v223, v153, v148
	v_add_f32_e32 v224, v149, v223
	v_mul_f32_e32 v226, v224, v224
	v_fmamk_f32 v148, v226, 0x3e9b6dac, v218
	v_fmaak_f32 v153, v226, v148, 0x3f2aaada
	v_cvt_f32_i32_e32 v148, v230
	v_sub_f32_e32 v149, v224, v149
	v_sub_f32_e32 v149, v223, v149
	v_ldexp_f32 v223, v149, 1
	v_mul_f32_e32 v149, v224, v226
	v_pk_mul_f32 v[226:227], v[148:149], v[152:153]
	v_ldexp_f32 v225, v224, 1
	v_fma_f32 v224, v148, s77, -v226
	v_fmac_f32_e32 v224, 0xb102e308, v148
	v_pk_add_f32 v[148:149], v[226:227], v[224:225]
	v_mov_b32_e32 v228, v226
	v_sub_f32_e32 v153, v149, v225
	v_sub_f32_e32 v153, v227, v153
	v_add_f32_e32 v229, v223, v153
	v_pk_add_f32 v[226:227], v[148:149], v[226:227] neg_lo:[0,1] neg_hi:[0,1]
	v_pk_add_f32 v[230:231], v[148:149], v[228:229]
	v_mov_b32_e32 v225, v148
	v_mov_b32_e32 v227, v231
	v_pk_add_f32 v[232:233], v[224:225], v[226:227] neg_lo:[0,1] neg_hi:[0,1]
	v_pk_add_f32 v[224:225], v[224:225], v[226:227]
	v_mov_b32_e32 v228, v229
	v_pk_add_f32 v[226:227], v[224:225], v[148:149] op_sel:[1,0] op_sel_hi:[0,1] neg_lo:[0,1] neg_hi:[0,1]
	v_pk_add_f32 v[234:235], v[230:231], v[226:227] op_sel_hi:[1,0] neg_lo:[0,1] neg_hi:[0,1]
	v_mov_b32_e32 v230, v231
	v_mov_b32_e32 v231, v225
	v_pk_mov_b32 v[226:227], v[148:149], v[226:227] op_sel:[1,0]
	v_mov_b32_e32 v229, v148
	v_pk_add_f32 v[226:227], v[230:231], v[226:227] neg_lo:[0,1] neg_hi:[0,1]
	v_mov_b32_e32 v234, v232
	v_pk_add_f32 v[148:149], v[228:229], v[226:227] neg_lo:[0,1] neg_hi:[0,1]
	v_mov_b32_e32 v233, v225
	v_pk_add_f32 v[226:227], v[234:235], v[148:149]
	v_mul_f32_e32 v139, 0xbfb8aa3b, v139
	v_pk_add_f32 v[228:229], v[226:227], v[226:227] op_sel:[0,1] op_sel_hi:[1,0]
	v_exp_f32_e32 v139, v139
	v_pk_add_f32 v[224:225], v[224:225], v[228:229] op_sel:[1,0] op_sel_hi:[0,1]
	v_mov_b32_e32 v227, v224
	v_pk_add_f32 v[230:231], v[226:227], v[232:233] neg_lo:[0,1] neg_hi:[0,1]
	v_mov_b32_e32 v149, v228
	v_sub_f32_e32 v153, v226, v230
	v_pk_add_f32 v[148:149], v[148:149], v[230:231] neg_lo:[0,1] neg_hi:[0,1]
	v_sub_f32_e32 v153, v232, v153
	v_add_f32_e32 v148, v148, v153
	v_add_f32_e32 v148, v148, v149
	v_add_f32_e32 v148, v224, v148
	v_cndmask_b32_e32 v148, v219, v148, vcc
	v_cmp_ngt_f32_e32 vcc, -1.0, v136
	v_add_f32_e32 v153, 1.0, v137
	v_add_f32_e32 v128, v128, v76
	v_cndmask_b32_e32 v148, v220, v148, vcc
	v_cmp_neq_f32_e32 vcc, -1.0, v136
	v_mul_f32_e32 v128, 0xbfb8aa3b, v128
	v_exp_f32_e32 v128, v128
	v_cndmask_b32_e32 v148, v221, v148, vcc
	v_cmp_lt_f32_e64 vcc, |v136|, s79
	v_add_f32_e32 v132, v132, v72
	v_add_f32_e32 v128, 1.0, v128
	v_cndmask_b32_e32 v136, v148, v136, vcc
	v_add_f32_e32 v148, -1.0, v153
	v_sub_f32_e32 v149, v148, v153
	v_add_f32_e32 v149, 1.0, v149
	v_sub_f32_e32 v148, v137, v148
	v_add_f32_e32 v223, v148, v149
	v_frexp_mant_f32_e32 v148, v153
	v_cmp_gt_f32_e32 vcc, s76, v148
	v_cvt_f64_f32_e32 v[148:149], v153
	v_frexp_exp_i32_f64_e32 v148, v[148:149]
	v_subbrev_co_u32_e32 v230, vcc, 0, v148, vcc
	v_sub_u32_e32 v148, 0, v230
	v_ldexp_f32 v149, v153, v148
	v_add_f32_e32 v153, -1.0, v149
	v_add_f32_e32 v224, 1.0, v149
	v_ldexp_f32 v148, v223, v148
	v_add_f32_e32 v223, 1.0, v153
	v_add_f32_e32 v225, -1.0, v224
	v_sub_f32_e32 v223, v149, v223
	v_sub_f32_e32 v149, v149, v225
	v_add_f32_e32 v223, v148, v223
	v_add_f32_e32 v148, v148, v149
	v_add_f32_e32 v231, v224, v148
	v_rcp_f32_e32 v233, v231
	v_sub_f32_e32 v149, v231, v224
	v_sub_f32_e32 v232, v148, v149
	v_add_f32_e32 v149, v153, v223
	v_sub_f32_e32 v148, v149, v153
	v_sub_f32_e32 v153, v223, v148
	v_mul_f32_e32 v223, v149, v233
	v_mul_f32_e32 v224, v231, v223
	v_fma_f32 v226, v223, v231, -v224
	v_fmac_f32_e32 v226, v223, v232
	v_add_f32_e32 v148, v224, v226
	v_sub_f32_e32 v225, v149, v148
	v_pk_add_f32 v[228:229], v[148:149], v[224:225] neg_lo:[0,1] neg_hi:[0,1]
	v_mov_b32_e32 v227, v148
	v_pk_add_f32 v[148:149], v[228:229], v[226:227] neg_lo:[0,1] neg_hi:[0,1]
	v_cmp_neq_f32_e32 vcc, s78, v137
	v_add_f32_e32 v149, v153, v149
	v_add_f32_e32 v148, v148, v149
	v_add_f32_e32 v149, v225, v148
	v_mul_f32_e32 v153, v233, v149
	v_mul_f32_e32 v224, v231, v153
	v_fma_f32 v226, v153, v231, -v224
	v_fmac_f32_e32 v226, v153, v232
	v_sub_f32_e32 v225, v225, v149
	v_add_f32_e32 v231, v148, v225
	v_add_f32_e32 v148, v224, v226
	v_sub_f32_e32 v225, v149, v148
	v_pk_add_f32 v[228:229], v[148:149], v[224:225] neg_lo:[0,1] neg_hi:[0,1]
	v_mov_b32_e32 v227, v148
	v_pk_add_f32 v[148:149], v[228:229], v[226:227] neg_lo:[0,1] neg_hi:[0,1]
	v_rcp_f32_e32 v128, v128
	v_add_f32_e32 v149, v231, v149
	v_add_f32_e32 v148, v148, v149
	v_add_f32_e32 v149, v223, v153
	v_add_f32_e32 v148, v225, v148
	v_sub_f32_e32 v223, v149, v223
	v_mul_f32_e32 v148, v233, v148
	v_sub_f32_e32 v153, v153, v223
	v_add_f32_e32 v223, v153, v148
	v_add_f32_e32 v224, v149, v223
	v_mul_f32_e32 v226, v224, v224
	v_fmamk_f32 v148, v226, 0x3e9b6dac, v218
	v_fmaak_f32 v153, v226, v148, 0x3f2aaada
	v_cvt_f32_i32_e32 v148, v230
	v_sub_f32_e32 v149, v224, v149
	v_sub_f32_e32 v149, v223, v149
	v_ldexp_f32 v223, v149, 1
	v_mul_f32_e32 v149, v224, v226
; __device__ __forceinline__ float bf_lo(unsigned w) { return __uint_as_float(w << 16); }
; __device__ __forceinline__ float bf_hi(unsigned w) { return __uint_as_float(w & 0xffff0000u); }
;     __device__ __forceinline__ void operator()(const AccT& acc, const Unit& u, int wr, int wc, int fr, int fq) const {
;     ...
;             for (int j = 0; j < 4; ++j) sp[j] = -8.0f * log1pf(__expf(-l[j]));
; #pragma unroll
;             for (int ai = 0; ai < 2; ++ai)
; #pragma unroll
;                 for (int m = 0; m < 4; ++m) { const size_t off = (size_t)(row0 + ai * HALF + m * 16) * DM + ch0 + 16 * n;
;                     const f32x4 rp = acc[ai][0][m][n] + bra, ip = acc[ai][1][m][n] + bri;
;                     const u32x2 w = xw[ai][m]; const float xv[4] = {bf_lo(w.x), bf_hi(w.x), bf_lo(w.y), bf_hi(w.y)};
;                     u32x4 o;
; #pragma unroll
;                     for (int j = 0; j < 4; ++j) { const float r = __builtin_amdgcn_rcpf(1.0f + __expf(-rp[j])), ig = __builtin_amdgcn_rcpf(1.0f + __expf(-ip[j])); const float la = sp[j] * r; const float d = 1.0f - __expf(la);
	v_pk_mul_f32 v[226:227], v[148:149], v[152:153]
	v_ldexp_f32 v225, v224, 1
	v_fma_f32 v224, v148, s77, -v226
	v_fmac_f32_e32 v224, 0xb102e308, v148
	v_pk_add_f32 v[148:149], v[226:227], v[224:225]
	v_mov_b32_e32 v228, v226
	v_sub_f32_e32 v153, v149, v225
	v_sub_f32_e32 v153, v227, v153
	v_add_f32_e32 v229, v223, v153
	v_pk_add_f32 v[226:227], v[148:149], v[226:227] neg_lo:[0,1] neg_hi:[0,1]
	v_pk_add_f32 v[230:231], v[148:149], v[228:229]
	v_mov_b32_e32 v225, v148
	v_mov_b32_e32 v227, v231
	v_pk_add_f32 v[232:233], v[224:225], v[226:227] neg_lo:[0,1] neg_hi:[0,1]
	v_pk_add_f32 v[224:225], v[224:225], v[226:227]
	v_mov_b32_e32 v228, v229
	v_pk_add_f32 v[226:227], v[224:225], v[148:149] op_sel:[1,0] op_sel_hi:[0,1] neg_lo:[0,1] neg_hi:[0,1]
	v_pk_add_f32 v[234:235], v[230:231], v[226:227] op_sel_hi:[1,0] neg_lo:[0,1] neg_hi:[0,1]
	v_mov_b32_e32 v230, v231
	v_mov_b32_e32 v231, v225
	v_pk_mov_b32 v[226:227], v[148:149], v[226:227] op_sel:[1,0]
	v_mov_b32_e32 v229, v148
	v_pk_add_f32 v[226:227], v[230:231], v[226:227] neg_lo:[0,1] neg_hi:[0,1]
	v_mov_b32_e32 v234, v232
	v_pk_add_f32 v[148:149], v[228:229], v[226:227] neg_lo:[0,1] neg_hi:[0,1]
	v_mov_b32_e32 v233, v225
	v_pk_add_f32 v[226:227], v[234:235], v[148:149]
	v_mul_f32_e32 v136, 0xc1000000, v136
	v_pk_add_f32 v[228:229], v[226:227], v[226:227] op_sel:[0,1] op_sel_hi:[1,0]
	v_mul_f32_e32 v128, v128, v136
	v_pk_add_f32 v[224:225], v[224:225], v[228:229] op_sel:[1,0] op_sel_hi:[0,1]
	v_mov_b32_e32 v227, v224
	v_pk_add_f32 v[230:231], v[226:227], v[232:233] neg_lo:[0,1] neg_hi:[0,1]
	v_mov_b32_e32 v149, v228
	v_sub_f32_e32 v153, v226, v230
	v_pk_add_f32 v[148:149], v[148:149], v[230:231] neg_lo:[0,1] neg_hi:[0,1]
	v_sub_f32_e32 v153, v232, v153
	v_add_f32_e32 v148, v148, v153
	v_add_f32_e32 v148, v148, v149
	v_add_f32_e32 v148, v224, v148
	v_cndmask_b32_e32 v148, v219, v148, vcc
	v_cmp_ngt_f32_e32 vcc, -1.0, v137
	v_add_f32_e32 v153, 1.0, v138
	v_mul_f32_e32 v128, 0x3fb8aa3b, v128
	v_cndmask_b32_e32 v148, v220, v148, vcc
	v_cmp_neq_f32_e32 vcc, -1.0, v137
	v_exp_f32_e32 v128, v128
	v_mul_f32_e32 v132, 0xbfb8aa3b, v132
	v_cndmask_b32_e32 v148, v221, v148, vcc
	v_cmp_lt_f32_e64 vcc, |v137|, s79
	v_exp_f32_e32 v132, v132
	v_sub_f32_e32 v128, 1.0, v128
	v_cndmask_b32_e32 v137, v148, v137, vcc
	v_add_f32_e32 v148, -1.0, v153
	v_sub_f32_e32 v149, v148, v153
	v_add_f32_e32 v149, 1.0, v149
	v_sub_f32_e32 v148, v138, v148
	v_add_f32_e32 v223, v148, v149
	v_frexp_mant_f32_e32 v148, v153
	v_cmp_gt_f32_e32 vcc, s76, v148
	v_cvt_f64_f32_e32 v[148:149], v153
	v_frexp_exp_i32_f64_e32 v148, v[148:149]
	v_subbrev_co_u32_e32 v230, vcc, 0, v148, vcc
	v_sub_u32_e32 v148, 0, v230
	v_ldexp_f32 v149, v153, v148
	v_add_f32_e32 v153, -1.0, v149
	v_add_f32_e32 v224, 1.0, v149
	v_ldexp_f32 v148, v223, v148
	v_add_f32_e32 v223, 1.0, v153
	v_add_f32_e32 v225, -1.0, v224
	v_sub_f32_e32 v223, v149, v223
	v_sub_f32_e32 v149, v149, v225
	v_add_f32_e32 v223, v148, v223
	v_add_f32_e32 v148, v148, v149
	v_add_f32_e32 v231, v224, v148
	v_rcp_f32_e32 v233, v231
	v_sub_f32_e32 v149, v231, v224
	v_sub_f32_e32 v232, v148, v149
	v_add_f32_e32 v149, v153, v223
	v_sub_f32_e32 v148, v149, v153
	v_sub_f32_e32 v153, v223, v148
	v_mul_f32_e32 v223, v149, v233
	v_mul_f32_e32 v224, v231, v223
	v_fma_f32 v226, v223, v231, -v224
	v_fmac_f32_e32 v226, v223, v232
	v_add_f32_e32 v148, v224, v226
	v_sub_f32_e32 v225, v149, v148
	v_pk_add_f32 v[228:229], v[148:149], v[224:225] neg_lo:[0,1] neg_hi:[0,1]
	v_mov_b32_e32 v227, v148
	v_pk_add_f32 v[148:149], v[228:229], v[226:227] neg_lo:[0,1] neg_hi:[0,1]
	v_cmp_neq_f32_e32 vcc, s78, v138
	v_add_f32_e32 v149, v153, v149
	v_add_f32_e32 v148, v148, v149
	v_add_f32_e32 v149, v225, v148
	v_mul_f32_e32 v153, v233, v149
	v_mul_f32_e32 v224, v231, v153
	v_fma_f32 v226, v153, v231, -v224
	v_fmac_f32_e32 v226, v153, v232
	v_sub_f32_e32 v225, v225, v149
	v_add_f32_e32 v231, v148, v225
	v_add_f32_e32 v148, v224, v226
	v_sub_f32_e32 v225, v149, v148
	v_pk_add_f32 v[228:229], v[148:149], v[224:225] neg_lo:[0,1] neg_hi:[0,1]
	v_mov_b32_e32 v227, v148
	v_pk_add_f32 v[148:149], v[228:229], v[226:227] neg_lo:[0,1] neg_hi:[0,1]
	v_add_f32_e32 v132, 1.0, v132
	v_add_f32_e32 v149, v231, v149
	v_add_f32_e32 v148, v148, v149
	v_add_f32_e32 v149, v223, v153
	v_add_f32_e32 v148, v225, v148
	v_sub_f32_e32 v223, v149, v223
	v_mul_f32_e32 v148, v233, v148
	v_sub_f32_e32 v153, v153, v223
	v_add_f32_e32 v223, v153, v148
	v_add_f32_e32 v224, v149, v223
	v_mul_f32_e32 v226, v224, v224
	v_fmamk_f32 v148, v226, 0x3e9b6dac, v218
	v_fmaak_f32 v153, v226, v148, 0x3f2aaada
	v_cvt_f32_i32_e32 v148, v230
	v_sub_f32_e32 v149, v224, v149
	v_sub_f32_e32 v149, v223, v149
	v_ldexp_f32 v223, v149, 1
	v_mul_f32_e32 v149, v224, v226
	v_pk_mul_f32 v[226:227], v[148:149], v[152:153]
	v_ldexp_f32 v225, v224, 1
	v_fma_f32 v224, v148, s77, -v226
	v_fmac_f32_e32 v224, 0xb102e308, v148
	v_pk_add_f32 v[148:149], v[226:227], v[224:225]
	v_mov_b32_e32 v228, v226
	v_sub_f32_e32 v153, v149, v225
	v_sub_f32_e32 v153, v227, v153
	v_add_f32_e32 v229, v223, v153
	v_pk_add_f32 v[226:227], v[148:149], v[226:227] neg_lo:[0,1] neg_hi:[0,1]
	v_pk_add_f32 v[230:231], v[148:149], v[228:229]
	v_mov_b32_e32 v225, v148
	v_mov_b32_e32 v227, v231
	v_pk_add_f32 v[232:233], v[224:225], v[226:227] neg_lo:[0,1] neg_hi:[0,1]
	v_pk_add_f32 v[224:225], v[224:225], v[226:227]
	v_mov_b32_e32 v228, v229
	v_pk_add_f32 v[226:227], v[224:225], v[148:149] op_sel:[1,0] op_sel_hi:[0,1] neg_lo:[0,1] neg_hi:[0,1]
	v_pk_add_f32 v[234:235], v[230:231], v[226:227] op_sel_hi:[1,0] neg_lo:[0,1] neg_hi:[0,1]
	v_mov_b32_e32 v230, v231
	v_mov_b32_e32 v231, v225
	v_pk_mov_b32 v[226:227], v[148:149], v[226:227] op_sel:[1,0]
; __device__ __forceinline__ float bf_lo(unsigned w) { return __uint_as_float(w << 16); }
; __device__ __forceinline__ float bf_hi(unsigned w) { return __uint_as_float(w & 0xffff0000u); }
;     __device__ __forceinline__ void operator()(const AccT& acc, const Unit& u, int wr, int wc, int fr, int fq) const {
;     ...
;             for (int j = 0; j < 4; ++j) sp[j] = -8.0f * log1pf(__expf(-l[j]));
; #pragma unroll
;             for (int ai = 0; ai < 2; ++ai)
; #pragma unroll
;                 for (int m = 0; m < 4; ++m) { const size_t off = (size_t)(row0 + ai * HALF + m * 16) * DM + ch0 + 16 * n;
;                     const f32x4 rp = acc[ai][0][m][n] + bra, ip = acc[ai][1][m][n] + bri;
;                     const u32x2 w = xw[ai][m]; const float xv[4] = {bf_lo(w.x), bf_hi(w.x), bf_lo(w.y), bf_hi(w.y)};
;                     u32x4 o;
; #pragma unroll
;                     for (int j = 0; j < 4; ++j) { const float r = __builtin_amdgcn_rcpf(1.0f + __expf(-rp[j])), ig = __builtin_amdgcn_rcpf(1.0f + __expf(-ip[j])); const float la = sp[j] * r; const float d = 1.0f - __expf(la);
	v_mov_b32_e32 v229, v148
	v_pk_add_f32 v[226:227], v[230:231], v[226:227] neg_lo:[0,1] neg_hi:[0,1]
	v_mov_b32_e32 v234, v232
	v_pk_add_f32 v[148:149], v[228:229], v[226:227] neg_lo:[0,1] neg_hi:[0,1]
	v_mov_b32_e32 v233, v225
	v_pk_add_f32 v[226:227], v[234:235], v[148:149]
	v_rcp_f32_e32 v132, v132
	v_pk_add_f32 v[228:229], v[226:227], v[226:227] op_sel:[0,1] op_sel_hi:[1,0]
	v_mul_f32_e32 v137, 0xc1000000, v137
	v_pk_add_f32 v[224:225], v[224:225], v[228:229] op_sel:[1,0] op_sel_hi:[0,1]
	v_mov_b32_e32 v227, v224
	v_pk_add_f32 v[230:231], v[226:227], v[232:233] neg_lo:[0,1] neg_hi:[0,1]
	v_mov_b32_e32 v149, v228
	v_sub_f32_e32 v153, v226, v230
	v_pk_add_f32 v[148:149], v[148:149], v[230:231] neg_lo:[0,1] neg_hi:[0,1]
	v_sub_f32_e32 v153, v232, v153
	v_add_f32_e32 v148, v148, v153
	v_add_f32_e32 v148, v148, v149
	v_add_f32_e32 v148, v224, v148
	v_cndmask_b32_e32 v148, v219, v148, vcc
	v_cmp_ngt_f32_e32 vcc, -1.0, v138
	v_add_f32_e32 v153, 1.0, v139
	v_add_f32_e32 v120, v120, v76
	v_cndmask_b32_e32 v148, v220, v148, vcc
	v_cmp_neq_f32_e32 vcc, -1.0, v138
	v_mul_f32_e32 v120, 0xbfb8aa3b, v120
	v_exp_f32_e32 v120, v120
	v_cndmask_b32_e32 v148, v221, v148, vcc
	v_cmp_lt_f32_e64 vcc, |v138|, s79
	v_add_f32_e32 v124, v124, v72
	v_add_f32_e32 v120, 1.0, v120
	v_cndmask_b32_e32 v138, v148, v138, vcc
	v_add_f32_e32 v148, -1.0, v153
	v_sub_f32_e32 v149, v148, v153
	v_add_f32_e32 v149, 1.0, v149
	v_sub_f32_e32 v148, v139, v148
	v_add_f32_e32 v223, v148, v149
	v_frexp_mant_f32_e32 v148, v153
	v_cmp_gt_f32_e32 vcc, s76, v148
	v_cvt_f64_f32_e32 v[148:149], v153
	v_frexp_exp_i32_f64_e32 v148, v[148:149]
	v_subbrev_co_u32_e32 v230, vcc, 0, v148, vcc
	v_sub_u32_e32 v148, 0, v230
	v_ldexp_f32 v149, v153, v148
	v_add_f32_e32 v153, -1.0, v149
	v_add_f32_e32 v224, 1.0, v149
	v_ldexp_f32 v148, v223, v148
	v_add_f32_e32 v223, 1.0, v153
	v_add_f32_e32 v225, -1.0, v224
	v_sub_f32_e32 v223, v149, v223
	v_sub_f32_e32 v149, v149, v225
	v_add_f32_e32 v223, v148, v223
	v_add_f32_e32 v148, v148, v149
	v_add_f32_e32 v231, v224, v148
	v_rcp_f32_e32 v233, v231
	v_sub_f32_e32 v149, v231, v224
	v_sub_f32_e32 v232, v148, v149
	v_add_f32_e32 v149, v153, v223
	v_sub_f32_e32 v148, v149, v153
	v_sub_f32_e32 v153, v223, v148
	v_mul_f32_e32 v223, v149, v233
	v_mul_f32_e32 v224, v231, v223
	v_fma_f32 v226, v223, v231, -v224
	v_fmac_f32_e32 v226, v223, v232
	v_add_f32_e32 v148, v224, v226
	v_sub_f32_e32 v225, v149, v148
	v_pk_add_f32 v[228:229], v[148:149], v[224:225] neg_lo:[0,1] neg_hi:[0,1]
	v_mov_b32_e32 v227, v148
	v_pk_add_f32 v[148:149], v[228:229], v[226:227] neg_lo:[0,1] neg_hi:[0,1]
	v_cmp_neq_f32_e32 vcc, s78, v139
	v_add_f32_e32 v149, v153, v149
	v_add_f32_e32 v148, v148, v149
	v_add_f32_e32 v149, v225, v148
	v_mul_f32_e32 v153, v233, v149
	v_mul_f32_e32 v224, v231, v153
	v_fma_f32 v226, v153, v231, -v224
	v_fmac_f32_e32 v226, v153, v232
	v_sub_f32_e32 v225, v225, v149
	v_add_f32_e32 v231, v148, v225
	v_add_f32_e32 v148, v224, v226
	v_sub_f32_e32 v225, v149, v148
	v_pk_add_f32 v[228:229], v[148:149], v[224:225] neg_lo:[0,1] neg_hi:[0,1]
	v_mov_b32_e32 v227, v148
	v_pk_add_f32 v[148:149], v[228:229], v[226:227] neg_lo:[0,1] neg_hi:[0,1]
	v_mul_f32_e32 v138, 0xc1000000, v138
	v_add_f32_e32 v149, v231, v149
	v_add_f32_e32 v148, v148, v149
	v_add_f32_e32 v149, v223, v153
	v_add_f32_e32 v148, v225, v148
	v_sub_f32_e32 v223, v149, v223
	v_mul_f32_e32 v148, v233, v148
	v_sub_f32_e32 v153, v153, v223
	v_add_f32_e32 v223, v153, v148
	v_add_f32_e32 v224, v149, v223
	v_mul_f32_e32 v226, v224, v224
	v_fmamk_f32 v148, v226, 0x3e9b6dac, v218
	v_fmaak_f32 v153, v226, v148, 0x3f2aaada
	v_cvt_f32_i32_e32 v148, v230
	v_sub_f32_e32 v149, v224, v149
	v_sub_f32_e32 v149, v223, v149
	v_ldexp_f32 v223, v149, 1
	v_mul_f32_e32 v149, v224, v226
	v_pk_mul_f32 v[226:227], v[148:149], v[152:153]
	v_ldexp_f32 v225, v224, 1
	v_fma_f32 v224, v148, s77, -v226
	v_fmac_f32_e32 v224, 0xb102e308, v148
	v_pk_add_f32 v[148:149], v[226:227], v[224:225]
	v_mov_b32_e32 v228, v226
	v_sub_f32_e32 v153, v149, v225
	v_sub_f32_e32 v153, v227, v153
	v_add_f32_e32 v229, v223, v153
	v_pk_add_f32 v[226:227], v[148:149], v[226:227] neg_lo:[0,1] neg_hi:[0,1]
	v_pk_add_f32 v[230:231], v[148:149], v[228:229]
	v_mov_b32_e32 v225, v148
	v_mov_b32_e32 v227, v231
	v_pk_add_f32 v[232:233], v[224:225], v[226:227] neg_lo:[0,1] neg_hi:[0,1]
	v_pk_add_f32 v[224:225], v[224:225], v[226:227]
	v_mov_b32_e32 v228, v229
	v_pk_add_f32 v[226:227], v[224:225], v[148:149] op_sel:[1,0] op_sel_hi:[0,1] neg_lo:[0,1] neg_hi:[0,1]
	v_pk_add_f32 v[234:235], v[230:231], v[226:227] op_sel_hi:[1,0] neg_lo:[0,1] neg_hi:[0,1]
	v_mov_b32_e32 v230, v231
	v_mov_b32_e32 v231, v225
	v_pk_mov_b32 v[226:227], v[148:149], v[226:227] op_sel:[1,0]
	v_mov_b32_e32 v229, v148
	v_pk_add_f32 v[226:227], v[230:231], v[226:227] neg_lo:[0,1] neg_hi:[0,1]
	v_mov_b32_e32 v234, v232
	v_pk_add_f32 v[148:149], v[228:229], v[226:227] neg_lo:[0,1] neg_hi:[0,1]
	v_mov_b32_e32 v233, v225
	v_pk_add_f32 v[226:227], v[234:235], v[148:149]
	v_rcp_f32_e32 v120, v120
	v_pk_add_f32 v[228:229], v[226:227], v[226:227] op_sel:[0,1] op_sel_hi:[1,0]
	v_mul_f32_e32 v124, 0xbfb8aa3b, v124
	v_pk_add_f32 v[224:225], v[224:225], v[228:229] op_sel:[1,0] op_sel_hi:[0,1]
	v_mov_b32_e32 v227, v224
	v_pk_add_f32 v[230:231], v[226:227], v[232:233] neg_lo:[0,1] neg_hi:[0,1]
	v_mov_b32_e32 v149, v228
	v_sub_f32_e32 v153, v226, v230
	v_pk_add_f32 v[148:149], v[148:149], v[230:231] neg_lo:[0,1] neg_hi:[0,1]
	v_sub_f32_e32 v153, v232, v153
	v_add_f32_e32 v148, v148, v153
	v_add_f32_e32 v148, v148, v149
	v_add_f32_e32 v148, v224, v148
	v_cndmask_b32_e32 v148, v219, v148, vcc
	v_cmp_ngt_f32_e32 vcc, -1.0, v139
; __device__ __forceinline__ unsigned cvt_pk_bf16(float lo, float hi) { const bf16x2_t r = __builtin_convertvector((f32x2){lo, hi}, bf16x2_t); return __builtin_bit_cast(unsigned, r); }
; __device__ __forceinline__ float bf_lo(unsigned w) { return __uint_as_float(w << 16); }
; __device__ __forceinline__ float bf_hi(unsigned w) { return __uint_as_float(w & 0xffff0000u); }
;     __device__ __forceinline__ void operator()(const AccT& acc, const Unit& u, int wr, int wc, int fr, int fq) const {
;     ...
; #pragma unroll
;             for (int ai = 0; ai < 2; ++ai)
; #pragma unroll
;                 for (int m = 0; m < 4; ++m) { const size_t off = (size_t)(row0 + ai * HALF + m * 16) * DM + ch0 + 16 * n;
;                     const f32x4 rp = acc[ai][0][m][n] + bra, ip = acc[ai][1][m][n] + bri;
;                     const u32x2 w = xw[ai][m]; const float xv[4] = {bf_lo(w.x), bf_hi(w.x), bf_lo(w.y), bf_hi(w.y)};
;                     u32x4 o;
; #pragma unroll
;                     for (int j = 0; j < 4; ++j) { const float r = __builtin_amdgcn_rcpf(1.0f + __expf(-rp[j])), ig = __builtin_amdgcn_rcpf(1.0f + __expf(-ip[j])); const float la = sp[j] * r; const float d = 1.0f - __expf(la);
;                         o[j] = cvt_pk_bf16(d, __builtin_amdgcn_sqrtf(fmaxf(d * (2.0f - d), 0.f)) * (ig * xv[j])); }
;                     *(u32x4*)(AU + off) = o; }
	v_and_b32_e32 v149, 0xffff0000, v210
	v_lshlrev_b32_e32 v153, 16, v211
	v_cndmask_b32_e32 v148, v220, v148, vcc
	v_cmp_neq_f32_e32 vcc, -1.0, v139
	v_mul_f32_e32 v120, v120, v136
	v_mul_f32_e32 v120, 0x3fb8aa3b, v120
	v_cndmask_b32_e32 v148, v221, v148, vcc
	v_cmp_lt_f32_e64 vcc, |v139|, s79
	v_exp_f32_e32 v120, v120
	v_exp_f32_e32 v124, v124
	v_cndmask_b32_e32 v139, v148, v139, vcc
	v_lshlrev_b32_e32 v148, 16, v210
	v_and_b32_e32 v210, 0xffff0000, v211
	v_sub_f32_e32 v211, 2.0, v128
	v_mul_f32_e32 v211, v128, v211
	v_max_f32_e32 v211, 0, v211
	v_sqrt_f32_e32 v211, v211
	v_mul_f32_e32 v132, v132, v148
	v_mul_f32_e32 v139, 0xc1000000, v139
	v_sub_f32_e32 v120, 1.0, v120
	v_mul_f32_e32 v132, v132, v211
	v_cvt_pk_bf16_f32 v132, v128, v132
	v_add_f32_e32 v128, v129, v77
	v_mul_f32_e32 v128, 0xbfb8aa3b, v128
	v_exp_f32_e32 v128, v128
	v_add_f32_e32 v129, v133, v73
	v_mul_f32_e32 v129, 0xbfb8aa3b, v129
	v_exp_f32_e32 v129, v129
	v_add_f32_e32 v128, 1.0, v128
	v_rcp_f32_e32 v128, v128
	v_add_f32_e32 v124, 1.0, v124
	v_add_f32_e32 v129, 1.0, v129
	v_rcp_f32_e32 v129, v129
	v_mul_f32_e32 v128, v128, v137
	v_mul_f32_e32 v128, 0x3fb8aa3b, v128
	v_exp_f32_e32 v128, v128
	v_mul_f32_e32 v129, v129, v149
	v_rcp_f32_e32 v124, v124
	v_add_f32_e32 v112, v112, v76
	v_sub_f32_e32 v128, 1.0, v128
	v_sub_f32_e32 v133, 2.0, v128
	v_mul_f32_e32 v133, v128, v133
	v_max_f32_e32 v133, 0, v133
	v_sqrt_f32_e32 v133, v133
	v_mul_f32_e32 v112, 0xbfb8aa3b, v112
	v_exp_f32_e32 v112, v112
	v_add_f32_e32 v116, v116, v72
	v_mul_f32_e32 v129, v129, v133
	v_cvt_pk_bf16_f32 v133, v128, v129
	v_add_f32_e32 v128, v130, v78
	v_mul_f32_e32 v128, 0xbfb8aa3b, v128
	v_exp_f32_e32 v128, v128
	v_add_f32_e32 v129, v134, v74
	v_mul_f32_e32 v129, 0xbfb8aa3b, v129
	v_exp_f32_e32 v129, v129
	v_add_f32_e32 v128, 1.0, v128
	v_rcp_f32_e32 v128, v128
	v_add_f32_e32 v112, 1.0, v112
	v_add_f32_e32 v129, 1.0, v129
	v_rcp_f32_e32 v129, v129
	v_mul_f32_e32 v128, v128, v138
	v_mul_f32_e32 v128, 0x3fb8aa3b, v128
	v_exp_f32_e32 v128, v128
	v_mul_f32_e32 v129, v129, v153
	v_rcp_f32_e32 v112, v112
	v_mul_f32_e32 v116, 0xbfb8aa3b, v116
	v_sub_f32_e32 v128, 1.0, v128
	v_sub_f32_e32 v130, 2.0, v128
	v_mul_f32_e32 v130, v128, v130
	v_max_f32_e32 v130, 0, v130
	v_sqrt_f32_e32 v130, v130
	v_mul_f32_e32 v112, v112, v136
	v_mul_f32_e32 v112, 0x3fb8aa3b, v112
	v_exp_f32_e32 v112, v112
	v_mul_f32_e32 v129, v129, v130
	v_cvt_pk_bf16_f32 v134, v128, v129
	v_add_f32_e32 v128, v131, v79
	v_mul_f32_e32 v128, 0xbfb8aa3b, v128
	v_exp_f32_e32 v128, v128
	v_add_f32_e32 v129, v135, v75
	v_mul_f32_e32 v129, 0xbfb8aa3b, v129
	v_exp_f32_e32 v129, v129
	v_add_f32_e32 v128, 1.0, v128
	v_rcp_f32_e32 v128, v128
	v_and_b32_e32 v131, 0xffff0000, v208
	v_add_f32_e32 v129, 1.0, v129
	v_rcp_f32_e32 v129, v129
	v_mul_f32_e32 v128, v128, v139
	v_mul_f32_e32 v128, 0x3fb8aa3b, v128
	v_exp_f32_e32 v128, v128
	v_mul_f32_e32 v129, v129, v210
	v_exp_f32_e32 v116, v116
	v_sub_f32_e32 v112, 1.0, v112
	v_sub_f32_e32 v128, 1.0, v128
	v_sub_f32_e32 v130, 2.0, v128
	v_mul_f32_e32 v130, v128, v130
	v_max_f32_e32 v130, 0, v130
	v_sqrt_f32_e32 v130, v130
	v_add_f32_e32 v116, 1.0, v116
	v_rcp_f32_e32 v116, v116
	v_add_f32_e32 v104, v104, v76
	v_mul_f32_e32 v129, v129, v130
	v_cvt_pk_bf16_f32 v135, v128, v129
	v_lshlrev_b64 v[128:129], 13, v[206:207]
	v_lshl_add_u64 v[128:129], s[42:43], 0, v[128:129]
	v_lshl_add_u64 v[128:129], v[128:129], 0, v[174:175]
	global_store_dwordx4 v[128:129], v[132:135], off
	v_lshlrev_b32_e32 v130, 16, v208
	v_mul_f32_e32 v124, v124, v130
	v_sub_f32_e32 v134, 2.0, v120
	v_mul_f32_e32 v134, v120, v134
	v_max_f32_e32 v134, 0, v134
	v_sqrt_f32_e32 v134, v134
	v_lshlrev_b32_e32 v132, 16, v209
	v_and_b32_e32 v133, 0xffff0000, v209
	v_mul_f32_e32 v104, 0xbfb8aa3b, v104
	v_mul_f32_e32 v124, v124, v134
	v_cvt_pk_bf16_f32 v124, v120, v124
	v_add_f32_e32 v120, v121, v77
	v_mul_f32_e32 v120, 0xbfb8aa3b, v120
	v_exp_f32_e32 v120, v120
	v_add_f32_e32 v121, v125, v73
	v_mul_f32_e32 v121, 0xbfb8aa3b, v121
	v_exp_f32_e32 v121, v121
	v_add_f32_e32 v120, 1.0, v120
	v_rcp_f32_e32 v120, v120
	v_exp_f32_e32 v104, v104
	v_add_f32_e32 v121, 1.0, v121
	v_rcp_f32_e32 v121, v121
	v_mul_f32_e32 v120, v120, v137
	v_mul_f32_e32 v120, 0x3fb8aa3b, v120
	v_exp_f32_e32 v120, v120
	v_mul_f32_e32 v121, v121, v131
	v_add_f32_e32 v104, 1.0, v104
	v_rcp_f32_e32 v104, v104
	v_sub_f32_e32 v120, 1.0, v120
	v_sub_f32_e32 v125, 2.0, v120
	v_mul_f32_e32 v125, v120, v125
	v_max_f32_e32 v125, 0, v125
	v_sqrt_f32_e32 v125, v125
	v_mul_f32_e32 v104, v104, v136
	v_mul_f32_e32 v104, 0x3fb8aa3b, v104
	v_add_f32_e32 v108, v108, v72
	v_mul_f32_e32 v121, v121, v125
	v_cvt_pk_bf16_f32 v125, v120, v121
	v_add_f32_e32 v120, v122, v78
	v_mul_f32_e32 v120, 0xbfb8aa3b, v120
	v_exp_f32_e32 v120, v120
	v_add_f32_e32 v121, v126, v74
	v_mul_f32_e32 v121, 0xbfb8aa3b, v121
	v_exp_f32_e32 v121, v121
	v_add_f32_e32 v120, 1.0, v120
	v_rcp_f32_e32 v120, v120
	v_exp_f32_e32 v104, v104
	v_add_f32_e32 v121, 1.0, v121
	v_rcp_f32_e32 v121, v121
	v_mul_f32_e32 v120, v120, v138
	v_mul_f32_e32 v120, 0x3fb8aa3b, v120
	v_exp_f32_e32 v120, v120
	v_mul_f32_e32 v121, v121, v132
	v_mul_f32_e32 v108, 0xbfb8aa3b, v108
	v_exp_f32_e32 v108, v108
	v_sub_f32_e32 v120, 1.0, v120
	v_sub_f32_e32 v122, 2.0, v120
	v_mul_f32_e32 v122, v120, v122
	v_max_f32_e32 v122, 0, v122
	v_sqrt_f32_e32 v122, v122
	v_sub_f32_e32 v104, 1.0, v104
	v_add_f32_e32 v108, 1.0, v108
	v_rcp_f32_e32 v108, v108
	v_mul_f32_e32 v121, v121, v122
	v_cvt_pk_bf16_f32 v126, v120, v121
	v_add_f32_e32 v120, v123, v79
	v_mul_f32_e32 v120, 0xbfb8aa3b, v120
	v_exp_f32_e32 v120, v120
	v_add_f32_e32 v121, v127, v75
	v_mul_f32_e32 v121, 0xbfb8aa3b, v121
; __device__ __forceinline__ unsigned cvt_pk_bf16(float lo, float hi) { const bf16x2_t r = __builtin_convertvector((f32x2){lo, hi}, bf16x2_t); return __builtin_bit_cast(unsigned, r); }
; __device__ __forceinline__ float bf_lo(unsigned w) { return __uint_as_float(w << 16); }
; __device__ __forceinline__ float bf_hi(unsigned w) { return __uint_as_float(w & 0xffff0000u); }
;     __device__ __forceinline__ void operator()(const AccT& acc, const Unit& u, int wr, int wc, int fr, int fq) const {
;     ...
; #pragma unroll
;             for (int ai = 0; ai < 2; ++ai)
; #pragma unroll
;                 for (int m = 0; m < 4; ++m) { const size_t off = (size_t)(row0 + ai * HALF + m * 16) * DM + ch0 + 16 * n;
;                     const f32x4 rp = acc[ai][0][m][n] + bra, ip = acc[ai][1][m][n] + bri;
;                     const u32x2 w = xw[ai][m]; const float xv[4] = {bf_lo(w.x), bf_hi(w.x), bf_lo(w.y), bf_hi(w.y)};
;                     u32x4 o;
; #pragma unroll
;                     for (int j = 0; j < 4; ++j) { const float r = __builtin_amdgcn_rcpf(1.0f + __expf(-rp[j])), ig = __builtin_amdgcn_rcpf(1.0f + __expf(-ip[j])); const float la = sp[j] * r; const float d = 1.0f - __expf(la);
;                         o[j] = cvt_pk_bf16(d, __builtin_amdgcn_sqrtf(fmaxf(d * (2.0f - d), 0.f)) * (ig * xv[j])); }
;                     *(u32x4*)(AU + off) = o; }
	v_exp_f32_e32 v121, v121
	v_add_f32_e32 v120, 1.0, v120
	v_rcp_f32_e32 v120, v120
	v_and_b32_e32 v123, 0xffff0000, v204
	v_add_f32_e32 v121, 1.0, v121
	v_rcp_f32_e32 v121, v121
	v_mul_f32_e32 v120, v120, v139
	v_mul_f32_e32 v120, 0x3fb8aa3b, v120
	v_exp_f32_e32 v120, v120
	v_mul_f32_e32 v121, v121, v133
	v_add_f32_e32 v96, v96, v76
	v_mul_f32_e32 v96, 0xbfb8aa3b, v96
	v_sub_f32_e32 v120, 1.0, v120
	v_sub_f32_e32 v122, 2.0, v120
	v_mul_f32_e32 v122, v120, v122
	v_max_f32_e32 v122, 0, v122
	v_sqrt_f32_e32 v122, v122
	v_exp_f32_e32 v96, v96
	v_add_f32_e32 v100, v100, v72
	v_mul_f32_e32 v100, 0xbfb8aa3b, v100
	v_mul_f32_e32 v121, v121, v122
	v_cvt_pk_bf16_f32 v127, v120, v121
	v_lshlrev_b64 v[120:121], 13, v[202:203]
	v_lshl_add_u64 v[120:121], s[42:43], 0, v[120:121]
	v_lshl_add_u64 v[120:121], v[120:121], 0, v[174:175]
	global_store_dwordx4 v[120:121], v[124:127], off
	v_lshlrev_b32_e32 v122, 16, v204
	v_mul_f32_e32 v116, v116, v122
	v_sub_f32_e32 v126, 2.0, v112
	v_mul_f32_e32 v126, v112, v126
	v_max_f32_e32 v126, 0, v126
	v_sqrt_f32_e32 v126, v126
	v_lshlrev_b32_e32 v124, 16, v205
	v_and_b32_e32 v125, 0xffff0000, v205
	v_add_f32_e32 v96, 1.0, v96
	v_mul_f32_e32 v116, v116, v126
	v_cvt_pk_bf16_f32 v116, v112, v116
	v_add_f32_e32 v112, v113, v77
	v_mul_f32_e32 v112, 0xbfb8aa3b, v112
	v_exp_f32_e32 v112, v112
	v_add_f32_e32 v113, v117, v73
	v_mul_f32_e32 v113, 0xbfb8aa3b, v113
	v_exp_f32_e32 v113, v113
	v_add_f32_e32 v112, 1.0, v112
	v_rcp_f32_e32 v112, v112
	v_rcp_f32_e32 v96, v96
	v_add_f32_e32 v113, 1.0, v113
	v_rcp_f32_e32 v113, v113
	v_mul_f32_e32 v112, v112, v137
	v_mul_f32_e32 v112, 0x3fb8aa3b, v112
	v_exp_f32_e32 v112, v112
	v_mul_f32_e32 v113, v113, v123
	v_mul_f32_e32 v96, v96, v136
	v_mul_f32_e32 v96, 0x3fb8aa3b, v96
	v_sub_f32_e32 v112, 1.0, v112
	v_sub_f32_e32 v117, 2.0, v112
	v_mul_f32_e32 v117, v112, v117
	v_max_f32_e32 v117, 0, v117
	v_sqrt_f32_e32 v117, v117
	v_exp_f32_e32 v96, v96
	v_exp_f32_e32 v100, v100
	v_add_f32_e32 v88, v88, v76
	v_mul_f32_e32 v113, v113, v117
	v_cvt_pk_bf16_f32 v117, v112, v113
	v_add_f32_e32 v112, v114, v78
	v_mul_f32_e32 v112, 0xbfb8aa3b, v112
	v_exp_f32_e32 v112, v112
	v_add_f32_e32 v113, v118, v74
	v_mul_f32_e32 v113, 0xbfb8aa3b, v113
	v_exp_f32_e32 v113, v113
	v_add_f32_e32 v112, 1.0, v112
	v_rcp_f32_e32 v112, v112
	v_sub_f32_e32 v96, 1.0, v96
	v_add_f32_e32 v113, 1.0, v113
	v_rcp_f32_e32 v113, v113
	v_mul_f32_e32 v112, v112, v138
	v_mul_f32_e32 v112, 0x3fb8aa3b, v112
	v_exp_f32_e32 v112, v112
	v_mul_f32_e32 v113, v113, v124
	v_add_f32_e32 v100, 1.0, v100
	v_rcp_f32_e32 v100, v100
	v_sub_f32_e32 v112, 1.0, v112
	v_sub_f32_e32 v114, 2.0, v112
	v_mul_f32_e32 v114, v112, v114
	v_max_f32_e32 v114, 0, v114
	v_sqrt_f32_e32 v114, v114
	v_mul_f32_e32 v88, 0xbfb8aa3b, v88
	v_exp_f32_e32 v88, v88
	v_add_f32_e32 v92, v92, v72
	v_mul_f32_e32 v113, v113, v114
	v_cvt_pk_bf16_f32 v118, v112, v113
	v_add_f32_e32 v112, v115, v79
	v_mul_f32_e32 v112, 0xbfb8aa3b, v112
	v_exp_f32_e32 v112, v112
	v_add_f32_e32 v113, v119, v75
	v_mul_f32_e32 v113, 0xbfb8aa3b, v113
	v_exp_f32_e32 v113, v113
	v_add_f32_e32 v112, 1.0, v112
	v_rcp_f32_e32 v112, v112
	v_and_b32_e32 v115, 0xffff0000, v198
	v_add_f32_e32 v113, 1.0, v113
	v_rcp_f32_e32 v113, v113
	v_mul_f32_e32 v112, v112, v139
	v_mul_f32_e32 v112, 0x3fb8aa3b, v112
	v_exp_f32_e32 v112, v112
	v_mul_f32_e32 v113, v113, v125
	v_add_f32_e32 v88, 1.0, v88
	v_rcp_f32_e32 v88, v88
	v_sub_f32_e32 v112, 1.0, v112
	v_sub_f32_e32 v114, 2.0, v112
	v_mul_f32_e32 v114, v112, v114
	v_max_f32_e32 v114, 0, v114
	v_sqrt_f32_e32 v114, v114
	v_mul_f32_e32 v88, v88, v136
	v_mul_f32_e32 v88, 0x3fb8aa3b, v88
	v_exp_f32_e32 v88, v88
	v_mul_f32_e32 v113, v113, v114
	v_cvt_pk_bf16_f32 v119, v112, v113
	v_lshlrev_b64 v[112:113], 13, v[196:197]
	v_lshl_add_u64 v[112:113], s[42:43], 0, v[112:113]
	v_lshl_add_u64 v[112:113], v[112:113], 0, v[174:175]
	global_store_dwordx4 v[112:113], v[116:119], off
	v_lshlrev_b32_e32 v114, 16, v198
	v_mul_f32_e32 v108, v108, v114
	v_sub_f32_e32 v118, 2.0, v104
	v_mul_f32_e32 v118, v104, v118
	v_max_f32_e32 v118, 0, v118
	v_sqrt_f32_e32 v118, v118
	v_lshlrev_b32_e32 v116, 16, v199
	v_and_b32_e32 v117, 0xffff0000, v199
	v_mul_f32_e32 v92, 0xbfb8aa3b, v92
	v_mul_f32_e32 v108, v108, v118
	v_cvt_pk_bf16_f32 v108, v104, v108
	v_add_f32_e32 v104, v105, v77
	v_mul_f32_e32 v104, 0xbfb8aa3b, v104
	v_exp_f32_e32 v104, v104
	v_add_f32_e32 v105, v109, v73
	v_mul_f32_e32 v105, 0xbfb8aa3b, v105
	v_exp_f32_e32 v105, v105
	v_add_f32_e32 v104, 1.0, v104
	v_rcp_f32_e32 v104, v104
	v_exp_f32_e32 v92, v92
	v_add_f32_e32 v105, 1.0, v105
	v_rcp_f32_e32 v105, v105
	v_mul_f32_e32 v104, v104, v137
	v_mul_f32_e32 v104, 0x3fb8aa3b, v104
	v_exp_f32_e32 v104, v104
	v_mul_f32_e32 v105, v105, v115
	v_sub_f32_e32 v88, 1.0, v88
	v_add_f32_e32 v92, 1.0, v92
	v_sub_f32_e32 v104, 1.0, v104
	v_sub_f32_e32 v109, 2.0, v104
	v_mul_f32_e32 v109, v104, v109
	v_max_f32_e32 v109, 0, v109
	v_sqrt_f32_e32 v109, v109
	v_rcp_f32_e32 v92, v92
	v_add_f32_e32 v80, v80, v76
	v_mul_f32_e32 v80, 0xbfb8aa3b, v80
	v_mul_f32_e32 v105, v105, v109
	v_cvt_pk_bf16_f32 v109, v104, v105
	v_add_f32_e32 v104, v106, v78
	v_mul_f32_e32 v104, 0xbfb8aa3b, v104
	v_exp_f32_e32 v104, v104
	v_add_f32_e32 v105, v110, v74
	v_mul_f32_e32 v105, 0xbfb8aa3b, v105
	v_exp_f32_e32 v105, v105
	v_add_f32_e32 v104, 1.0, v104
	v_rcp_f32_e32 v104, v104
	v_exp_f32_e32 v80, v80
	v_add_f32_e32 v105, 1.0, v105
	v_rcp_f32_e32 v105, v105
	v_mul_f32_e32 v104, v104, v138
	v_mul_f32_e32 v104, 0x3fb8aa3b, v104
	v_exp_f32_e32 v104, v104
	v_mul_f32_e32 v105, v105, v116
	v_add_f32_e32 v80, 1.0, v80
	v_rcp_f32_e32 v80, v80
	v_sub_f32_e32 v104, 1.0, v104
; __device__ __forceinline__ unsigned cvt_pk_bf16(float lo, float hi) { const bf16x2_t r = __builtin_convertvector((f32x2){lo, hi}, bf16x2_t); return __builtin_bit_cast(unsigned, r); }
; __device__ __forceinline__ float bf_lo(unsigned w) { return __uint_as_float(w << 16); }
; __device__ __forceinline__ float bf_hi(unsigned w) { return __uint_as_float(w & 0xffff0000u); }
;     __device__ __forceinline__ void operator()(const AccT& acc, const Unit& u, int wr, int wc, int fr, int fq) const {
;     ...
;                 for (int m = 0; m < 4; ++m) xw[ai][m] = *(const u32x2*)(XC + (size_t)(row0 + ai * HALF + m * 16) * DM + ch0 + 16 * n);
;             const f32x4 bra = *(const f32x4*)(b_ra + ch0 + 16 * n), bri = *(const f32x4*)(b_ri + ch0 + 16 * n), l = *(const f32x4*)(lam + ch0 + 16 * n);
;             f32x4 sp;
; #pragma unroll
;             for (int j = 0; j < 4; ++j) sp[j] = -8.0f * log1pf(__expf(-l[j]));
; #pragma unroll
;             for (int ai = 0; ai < 2; ++ai)
; #pragma unroll
;                 for (int m = 0; m < 4; ++m) { const size_t off = (size_t)(row0 + ai * HALF + m * 16) * DM + ch0 + 16 * n;
;                     const f32x4 rp = acc[ai][0][m][n] + bra, ip = acc[ai][1][m][n] + bri;
;                     const u32x2 w = xw[ai][m]; const float xv[4] = {bf_lo(w.x), bf_hi(w.x), bf_lo(w.y), bf_hi(w.y)};
;                     u32x4 o;
; #pragma unroll
;                     for (int j = 0; j < 4; ++j) { const float r = __builtin_amdgcn_rcpf(1.0f + __expf(-rp[j])), ig = __builtin_amdgcn_rcpf(1.0f + __expf(-ip[j])); const float la = sp[j] * r; const float d = 1.0f - __expf(la);
;                         o[j] = cvt_pk_bf16(d, __builtin_amdgcn_sqrtf(fmaxf(d * (2.0f - d), 0.f)) * (ig * xv[j])); }
;                     *(u32x4*)(AU + off) = o; }
	v_sub_f32_e32 v106, 2.0, v104
	v_mul_f32_e32 v106, v104, v106
	v_max_f32_e32 v106, 0, v106
	v_sqrt_f32_e32 v106, v106
	v_mul_f32_e32 v80, v80, v136
	v_mul_f32_e32 v80, 0x3fb8aa3b, v80
	v_add_f32_e32 v84, v84, v72
	v_mul_f32_e32 v105, v105, v106
	v_cvt_pk_bf16_f32 v110, v104, v105
	v_add_f32_e32 v104, v107, v79
	v_mul_f32_e32 v104, 0xbfb8aa3b, v104
	v_exp_f32_e32 v104, v104
	v_add_f32_e32 v105, v111, v75
	v_mul_f32_e32 v105, 0xbfb8aa3b, v105
	v_exp_f32_e32 v105, v105
	v_add_f32_e32 v104, 1.0, v104
	v_rcp_f32_e32 v104, v104
	v_and_b32_e32 v107, 0xffff0000, v194
	v_add_f32_e32 v105, 1.0, v105
	v_rcp_f32_e32 v105, v105
	v_mul_f32_e32 v104, v104, v139
	v_mul_f32_e32 v104, 0x3fb8aa3b, v104
	v_exp_f32_e32 v104, v104
	v_mul_f32_e32 v105, v105, v117
	v_exp_f32_e32 v80, v80
	v_mul_f32_e32 v84, 0xbfb8aa3b, v84
	v_sub_f32_e32 v104, 1.0, v104
	v_sub_f32_e32 v106, 2.0, v104
	v_mul_f32_e32 v106, v104, v106
	v_max_f32_e32 v106, 0, v106
	v_sqrt_f32_e32 v106, v106
	v_exp_f32_e32 v84, v84
	v_sub_f32_e32 v80, 1.0, v80
	v_add_f32_e32 v64, v64, v76
	v_mul_f32_e32 v105, v105, v106
	v_cvt_pk_bf16_f32 v111, v104, v105
	v_lshlrev_b64 v[104:105], 13, v[192:193]
	v_lshl_add_u64 v[104:105], s[42:43], 0, v[104:105]
	v_lshl_add_u64 v[104:105], v[104:105], 0, v[174:175]
	global_store_dwordx4 v[104:105], v[108:111], off
	global_load_dwordx2 v[114:115], v[154:155], off offset:32
	global_load_dwordx2 v[122:123], v[156:157], off offset:32
	global_load_dwordx2 v[148:149], v[158:159], off offset:32
	global_load_dwordx2 v[192:193], v[160:161], off offset:32
	global_load_dwordx2 v[202:203], v[162:163], off offset:32
	global_load_dwordx2 v[208:209], v[164:165], off offset:32
	global_load_dwordx2 v[210:211], v[166:167], off offset:32
	global_load_dwordx2 v[224:225], v[168:169], off offset:32
	global_load_dwordx4 v[116:119], v[176:177], off offset:64
	global_load_dwordx4 v[196:199], v[178:179], off offset:64
	global_load_dwordx4 v[204:207], v[172:173], off offset:64
	v_lshlrev_b32_e32 v106, 16, v194
	v_mul_f32_e32 v100, v100, v106
	v_sub_f32_e32 v110, 2.0, v96
	v_mul_f32_e32 v110, v96, v110
	v_max_f32_e32 v110, 0, v110
	v_sqrt_f32_e32 v110, v110
	v_lshlrev_b32_e32 v108, 16, v195
	v_and_b32_e32 v109, 0xffff0000, v195
	v_add_f32_e32 v84, 1.0, v84
	v_mul_f32_e32 v100, v100, v110
	v_cvt_pk_bf16_f32 v100, v96, v100
	v_add_f32_e32 v96, v97, v77
	v_mul_f32_e32 v96, 0xbfb8aa3b, v96
	v_exp_f32_e32 v96, v96
	v_add_f32_e32 v97, v101, v73
	v_mul_f32_e32 v97, 0xbfb8aa3b, v97
	v_exp_f32_e32 v97, v97
	v_add_f32_e32 v96, 1.0, v96
	v_rcp_f32_e32 v96, v96
	v_rcp_f32_e32 v84, v84
	v_add_f32_e32 v97, 1.0, v97
	v_rcp_f32_e32 v97, v97
	v_mul_f32_e32 v96, v96, v137
	v_mul_f32_e32 v96, 0x3fb8aa3b, v96
	v_exp_f32_e32 v96, v96
	v_mul_f32_e32 v97, v97, v107
	v_mul_f32_e32 v64, 0xbfb8aa3b, v64
	v_exp_f32_e32 v64, v64
	v_sub_f32_e32 v96, 1.0, v96
	v_sub_f32_e32 v101, 2.0, v96
	v_mul_f32_e32 v101, v96, v101
	v_max_f32_e32 v101, 0, v101
	v_sqrt_f32_e32 v101, v101
	v_add_f32_e32 v64, 1.0, v64
	v_rcp_f32_e32 v64, v64
	v_add_f32_e32 v68, v68, v72
	v_mul_f32_e32 v97, v97, v101
	v_cvt_pk_bf16_f32 v101, v96, v97
	v_add_f32_e32 v96, v98, v78
	v_mul_f32_e32 v96, 0xbfb8aa3b, v96
	v_exp_f32_e32 v96, v96
	v_add_f32_e32 v97, v102, v74
	v_mul_f32_e32 v97, 0xbfb8aa3b, v97
	v_exp_f32_e32 v97, v97
	v_add_f32_e32 v96, 1.0, v96
	v_rcp_f32_e32 v96, v96
	v_mul_f32_e32 v64, v64, v136
	v_add_f32_e32 v97, 1.0, v97
	v_rcp_f32_e32 v97, v97
	v_mul_f32_e32 v96, v96, v138
	v_mul_f32_e32 v96, 0x3fb8aa3b, v96
	v_exp_f32_e32 v96, v96
	v_mul_f32_e32 v97, v97, v108
	v_mul_f32_e32 v64, 0x3fb8aa3b, v64
	v_exp_f32_e32 v64, v64
	v_sub_f32_e32 v96, 1.0, v96
	v_sub_f32_e32 v98, 2.0, v96
	v_mul_f32_e32 v98, v96, v98
	v_max_f32_e32 v98, 0, v98
	v_sqrt_f32_e32 v98, v98
	v_add_f32_e32 v65, v65, v77
	v_mul_f32_e32 v68, 0xbfb8aa3b, v68
	v_mul_f32_e32 v65, 0xbfb8aa3b, v65
	v_mul_f32_e32 v97, v97, v98
	v_cvt_pk_bf16_f32 v102, v96, v97
	v_add_f32_e32 v96, v99, v79
	v_mul_f32_e32 v96, 0xbfb8aa3b, v96
	v_exp_f32_e32 v96, v96
	v_add_f32_e32 v97, v103, v75
	v_mul_f32_e32 v97, 0xbfb8aa3b, v97
	v_exp_f32_e32 v97, v97
	v_add_f32_e32 v96, 1.0, v96
	v_rcp_f32_e32 v96, v96
	v_and_b32_e32 v99, 0xffff0000, v190
	v_add_f32_e32 v97, 1.0, v97
	v_rcp_f32_e32 v97, v97
	v_mul_f32_e32 v96, v96, v139
	v_mul_f32_e32 v96, 0x3fb8aa3b, v96
	v_exp_f32_e32 v96, v96
	v_mul_f32_e32 v97, v97, v109
	v_exp_f32_e32 v68, v68
	v_exp_f32_e32 v65, v65
	v_sub_f32_e32 v96, 1.0, v96
	v_sub_f32_e32 v98, 2.0, v96
	v_mul_f32_e32 v98, v96, v98
	v_max_f32_e32 v98, 0, v98
	v_sqrt_f32_e32 v98, v98
	v_sub_f32_e32 v64, 1.0, v64
	v_sub_f32_e32 v72, 2.0, v64
	v_add_f32_e32 v68, 1.0, v68
	v_mul_f32_e32 v97, v97, v98
	v_cvt_pk_bf16_f32 v103, v96, v97
	v_lshlrev_b64 v[96:97], 13, v[188:189]
	v_lshl_add_u64 v[96:97], s[42:43], 0, v[96:97]
	v_lshl_add_u64 v[96:97], v[96:97], 0, v[174:175]
	global_store_dwordx4 v[96:97], v[100:103], off
	v_lshlrev_b32_e32 v98, 16, v190
	v_mul_f32_e32 v92, v92, v98
	v_sub_f32_e32 v102, 2.0, v88
	v_mul_f32_e32 v102, v88, v102
	v_max_f32_e32 v102, 0, v102
	v_sqrt_f32_e32 v102, v102
	v_lshlrev_b32_e32 v100, 16, v191
	v_and_b32_e32 v101, 0xffff0000, v191
	v_mul_f32_e32 v72, v64, v72
	v_mul_f32_e32 v92, v92, v102
	v_cvt_pk_bf16_f32 v92, v88, v92
	v_add_f32_e32 v88, v89, v77
	v_mul_f32_e32 v88, 0xbfb8aa3b, v88
	v_exp_f32_e32 v88, v88
	v_add_f32_e32 v89, v93, v73
	v_mul_f32_e32 v89, 0xbfb8aa3b, v89
	v_exp_f32_e32 v89, v89
	v_add_f32_e32 v88, 1.0, v88
	v_rcp_f32_e32 v88, v88
	v_add_f32_e32 v65, 1.0, v65
	v_add_f32_e32 v89, 1.0, v89
	v_rcp_f32_e32 v89, v89
	v_mul_f32_e32 v88, v88, v137
	v_mul_f32_e32 v88, 0x3fb8aa3b, v88
	v_exp_f32_e32 v88, v88
	v_mul_f32_e32 v89, v89, v99
; __device__ __forceinline__ unsigned cvt_pk_bf16(float lo, float hi) { const bf16x2_t r = __builtin_convertvector((f32x2){lo, hi}, bf16x2_t); return __builtin_bit_cast(unsigned, r); }
; __device__ __forceinline__ float bf_lo(unsigned w) { return __uint_as_float(w << 16); }
; __device__ __forceinline__ float bf_hi(unsigned w) { return __uint_as_float(w & 0xffff0000u); }
;     __device__ __forceinline__ void operator()(const AccT& acc, const Unit& u, int wr, int wc, int fr, int fq) const {
;     ...
; #pragma unroll
;             for (int ai = 0; ai < 2; ++ai)
; #pragma unroll
;                 for (int m = 0; m < 4; ++m) { const size_t off = (size_t)(row0 + ai * HALF + m * 16) * DM + ch0 + 16 * n;
;                     const f32x4 rp = acc[ai][0][m][n] + bra, ip = acc[ai][1][m][n] + bri;
;                     const u32x2 w = xw[ai][m]; const float xv[4] = {bf_lo(w.x), bf_hi(w.x), bf_lo(w.y), bf_hi(w.y)};
;                     u32x4 o;
; #pragma unroll
;                     for (int j = 0; j < 4; ++j) { const float r = __builtin_amdgcn_rcpf(1.0f + __expf(-rp[j])), ig = __builtin_amdgcn_rcpf(1.0f + __expf(-ip[j])); const float la = sp[j] * r; const float d = 1.0f - __expf(la);
;                         o[j] = cvt_pk_bf16(d, __builtin_amdgcn_sqrtf(fmaxf(d * (2.0f - d), 0.f)) * (ig * xv[j])); }
;                     *(u32x4*)(AU + off) = o; }
	v_rcp_f32_e32 v68, v68
	v_max_f32_e32 v72, 0, v72
	v_sub_f32_e32 v88, 1.0, v88
	v_sub_f32_e32 v93, 2.0, v88
	v_mul_f32_e32 v93, v88, v93
	v_max_f32_e32 v93, 0, v93
	v_sqrt_f32_e32 v93, v93
	v_rcp_f32_e32 v65, v65
	v_sqrt_f32_e32 v72, v72
	v_add_f32_e32 v66, v66, v78
	v_mul_f32_e32 v89, v89, v93
	v_cvt_pk_bf16_f32 v93, v88, v89
	v_add_f32_e32 v88, v90, v78
	v_mul_f32_e32 v88, 0xbfb8aa3b, v88
	v_exp_f32_e32 v88, v88
	v_add_f32_e32 v89, v94, v74
	v_mul_f32_e32 v89, 0xbfb8aa3b, v89
	v_exp_f32_e32 v89, v89
	v_add_f32_e32 v88, 1.0, v88
	v_rcp_f32_e32 v88, v88
	v_mul_f32_e32 v65, v65, v137
	v_add_f32_e32 v89, 1.0, v89
	v_rcp_f32_e32 v89, v89
	v_mul_f32_e32 v88, v88, v138
	v_mul_f32_e32 v88, 0x3fb8aa3b, v88
	v_exp_f32_e32 v88, v88
	v_mul_f32_e32 v89, v89, v100
	v_mul_f32_e32 v65, 0x3fb8aa3b, v65
	v_exp_f32_e32 v65, v65
	v_sub_f32_e32 v88, 1.0, v88
	v_sub_f32_e32 v90, 2.0, v88
	v_mul_f32_e32 v90, v88, v90
	v_max_f32_e32 v90, 0, v90
	v_sqrt_f32_e32 v90, v90
	v_mul_f32_e32 v66, 0xbfb8aa3b, v66
	v_exp_f32_e32 v66, v66
	v_sub_f32_e32 v65, 1.0, v65
	v_mul_f32_e32 v89, v89, v90
	v_cvt_pk_bf16_f32 v94, v88, v89
	v_add_f32_e32 v88, v91, v79
	v_mul_f32_e32 v88, 0xbfb8aa3b, v88
	v_exp_f32_e32 v88, v88
	v_add_f32_e32 v89, v95, v75
	v_mul_f32_e32 v89, 0xbfb8aa3b, v89
	v_exp_f32_e32 v89, v89
	v_add_f32_e32 v88, 1.0, v88
	v_rcp_f32_e32 v88, v88
	v_and_b32_e32 v91, 0xffff0000, v186
	v_add_f32_e32 v89, 1.0, v89
	v_rcp_f32_e32 v89, v89
	v_mul_f32_e32 v88, v88, v139
	v_mul_f32_e32 v88, 0x3fb8aa3b, v88
	v_exp_f32_e32 v88, v88
	v_mul_f32_e32 v89, v89, v101
	v_add_f32_e32 v66, 1.0, v66
	v_rcp_f32_e32 v66, v66
	v_sub_f32_e32 v88, 1.0, v88
	v_sub_f32_e32 v90, 2.0, v88
	v_mul_f32_e32 v90, v88, v90
	v_max_f32_e32 v90, 0, v90
	v_sqrt_f32_e32 v90, v90
	v_mul_f32_e32 v66, v66, v138
	v_mul_f32_e32 v66, 0x3fb8aa3b, v66
	v_exp_f32_e32 v66, v66
	v_mul_f32_e32 v89, v89, v90
	v_cvt_pk_bf16_f32 v95, v88, v89
	v_lshlrev_b64 v[88:89], 13, v[184:185]
	v_lshl_add_u64 v[88:89], s[42:43], 0, v[88:89]
	v_lshl_add_u64 v[88:89], v[88:89], 0, v[174:175]
	global_store_dwordx4 v[88:89], v[92:95], off
	v_lshlrev_b32_e32 v90, 16, v186
	v_mul_f32_e32 v84, v84, v90
	v_sub_f32_e32 v94, 2.0, v80
	v_mul_f32_e32 v94, v80, v94
	v_max_f32_e32 v94, 0, v94
	v_sqrt_f32_e32 v94, v94
	v_lshlrev_b32_e32 v92, 16, v187
	v_and_b32_e32 v93, 0xffff0000, v187
	v_add_f32_e32 v67, v67, v79
	v_mul_f32_e32 v84, v84, v94
	v_cvt_pk_bf16_f32 v84, v80, v84
	v_add_f32_e32 v80, v81, v77
	v_mul_f32_e32 v80, 0xbfb8aa3b, v80
	v_exp_f32_e32 v80, v80
	v_add_f32_e32 v81, v85, v73
	v_mul_f32_e32 v81, 0xbfb8aa3b, v81
	v_exp_f32_e32 v81, v81
	v_add_f32_e32 v80, 1.0, v80
	v_rcp_f32_e32 v80, v80
	v_mul_f32_e32 v67, 0xbfb8aa3b, v67
	v_add_f32_e32 v81, 1.0, v81
	v_rcp_f32_e32 v81, v81
	v_mul_f32_e32 v80, v80, v137
	v_mul_f32_e32 v80, 0x3fb8aa3b, v80
	v_exp_f32_e32 v80, v80
	v_mul_f32_e32 v81, v81, v91
	v_exp_f32_e32 v67, v67
	v_sub_f32_e32 v66, 1.0, v66
	v_sub_f32_e32 v80, 1.0, v80
	v_sub_f32_e32 v85, 2.0, v80
	v_mul_f32_e32 v85, v80, v85
	v_max_f32_e32 v85, 0, v85
	v_sqrt_f32_e32 v85, v85
	v_add_f32_e32 v67, 1.0, v67
	v_rcp_f32_e32 v67, v67
	v_mul_f32_e32 v81, v81, v85
	v_cvt_pk_bf16_f32 v85, v80, v81
	v_add_f32_e32 v80, v82, v78
	v_mul_f32_e32 v80, 0xbfb8aa3b, v80
	v_exp_f32_e32 v80, v80
	v_add_f32_e32 v81, v86, v74
	v_mul_f32_e32 v81, 0xbfb8aa3b, v81
	v_exp_f32_e32 v81, v81
	v_add_f32_e32 v80, 1.0, v80
	v_rcp_f32_e32 v80, v80
	v_mul_f32_e32 v67, v67, v139
	v_add_f32_e32 v81, 1.0, v81
	v_rcp_f32_e32 v81, v81
	v_mul_f32_e32 v80, v80, v138
	v_mul_f32_e32 v80, 0x3fb8aa3b, v80
	v_exp_f32_e32 v80, v80
	v_mul_f32_e32 v81, v81, v92
	v_mul_f32_e32 v67, 0x3fb8aa3b, v67
	v_exp_f32_e32 v67, v67
	v_sub_f32_e32 v80, 1.0, v80
	v_sub_f32_e32 v82, 2.0, v80
	v_mul_f32_e32 v82, v80, v82
	v_max_f32_e32 v82, 0, v82
	v_sqrt_f32_e32 v82, v82
	v_sub_f32_e32 v67, 1.0, v67
	v_mul_f32_e32 v81, v81, v82
	v_cvt_pk_bf16_f32 v86, v80, v81
	v_add_f32_e32 v80, v83, v79
	v_mul_f32_e32 v80, 0xbfb8aa3b, v80
	v_exp_f32_e32 v80, v80
	v_add_f32_e32 v81, v87, v75
	v_mul_f32_e32 v81, 0xbfb8aa3b, v81
	v_exp_f32_e32 v81, v81
	v_add_f32_e32 v80, 1.0, v80
	v_rcp_f32_e32 v80, v80
	v_and_b32_e32 v83, 0xffff0000, v182
	v_add_f32_e32 v81, 1.0, v81
	v_rcp_f32_e32 v81, v81
	v_mul_f32_e32 v80, v80, v139
	v_mul_f32_e32 v80, 0x3fb8aa3b, v80
	v_exp_f32_e32 v80, v80
	v_mul_f32_e32 v81, v81, v93
	v_sub_f32_e32 v80, 1.0, v80
	v_sub_f32_e32 v82, 2.0, v80
	v_mul_f32_e32 v82, v80, v82
	v_max_f32_e32 v82, 0, v82
	v_sqrt_f32_e32 v82, v82
	s_nop 0
	v_mul_f32_e32 v81, v81, v82
	v_lshlrev_b32_e32 v82, 16, v182
	v_mul_f32_e32 v68, v68, v82
	v_mul_f32_e32 v68, v68, v72
	v_cvt_pk_bf16_f32 v64, v64, v68
	v_add_f32_e32 v68, v69, v73
	v_mul_f32_e32 v68, 0xbfb8aa3b, v68
	v_exp_f32_e32 v68, v68
	v_sub_f32_e32 v69, 2.0, v65
	v_mul_f32_e32 v69, v65, v69
	v_max_f32_e32 v69, 0, v69
	v_add_f32_e32 v68, 1.0, v68
	v_rcp_f32_e32 v68, v68
	v_sqrt_f32_e32 v69, v69
	v_cvt_pk_bf16_f32 v87, v80, v81
	v_lshlrev_b64 v[80:81], 13, v[180:181]
	v_mul_f32_e32 v68, v68, v83
	v_mul_f32_e32 v68, v68, v69
	v_cvt_pk_bf16_f32 v65, v65, v68
	v_add_f32_e32 v68, v70, v74
	v_mul_f32_e32 v68, 0xbfb8aa3b, v68
	v_exp_f32_e32 v68, v68
	v_sub_f32_e32 v69, 2.0, v66
	v_mul_f32_e32 v69, v66, v69
	v_max_f32_e32 v69, 0, v69
	v_add_f32_e32 v68, 1.0, v68
	v_rcp_f32_e32 v68, v68
	v_lshl_add_u64 v[80:81], s[42:43], 0, v[80:81]
	v_sqrt_f32_e32 v69, v69
	v_lshl_add_u64 v[80:81], v[80:81], 0, v[174:175]
	global_store_dwordx4 v[80:81], v[84:87], off
	s_nop 1
	v_lshlrev_b32_e32 v84, 16, v183
	v_mul_f32_e32 v68, v68, v84
	v_mul_f32_e32 v68, v68, v69
	v_cvt_pk_bf16_f32 v66, v66, v68
	v_add_f32_e32 v68, v71, v75
	v_mul_f32_e32 v68, 0xbfb8aa3b, v68
	v_exp_f32_e32 v68, v68
	v_sub_f32_e32 v69, 2.0, v67
	v_mul_f32_e32 v69, v67, v69
	v_max_f32_e32 v69, 0, v69
	v_add_f32_e32 v68, 1.0, v68
	v_rcp_f32_e32 v68, v68
	v_sqrt_f32_e32 v69, v69
	v_and_b32_e32 v85, 0xffff0000, v183
	v_mul_f32_e32 v68, v68, v85
	v_mul_f32_e32 v68, v68, v69
	v_cvt_pk_bf16_f32 v67, v67, v68
	v_lshlrev_b64 v[68:69], 13, v[170:171]
	v_lshl_add_u64 v[68:69], s[42:43], 0, v[68:69]
	v_lshl_add_u64 v[76:77], v[68:69], 0, v[174:175]
	global_store_dwordx4 v[76:77], v[64:67], off
	s_waitcnt vmcnt(4)
;     __device__ __forceinline__ void operator()(const AccT& acc, const Unit& u, int wr, int wc, int fr, int fq) const {
;     ...
;             const f32x4 bra = *(const f32x4*)(b_ra + ch0 + 16 * n), bri = *(const f32x4*)(b_ri + ch0 + 16 * n), l = *(const f32x4*)(lam + ch0 + 16 * n);
;             f32x4 sp;
; #pragma unroll
;             for (int j = 0; j < 4; ++j) sp[j] = -8.0f * log1pf(__expf(-l[j]));
; #pragma unroll
;             for (int ai = 0; ai < 2; ++ai)
; #pragma unroll
;                 for (int m = 0; m < 4; ++m) { const size_t off = (size_t)(row0 + ai * HALF + m * 16) * DM + ch0 + 16 * n;
;                     const f32x4 rp = acc[ai][0][m][n] + bra, ip = acc[ai][1][m][n] + bri;
	v_mov_b64_e32 v[98:99], v[114:115]
	v_mov_b64_e32 v[94:95], v[122:123]
	v_mov_b64_e32 v[92:93], v[148:149]
	v_mov_b64_e32 v[90:91], v[192:193]
	v_mov_b64_e32 v[86:87], v[202:203]
	v_mov_b64_e32 v[84:85], v[208:209]
	v_mov_b64_e32 v[82:83], v[210:211]
	v_mov_b64_e32 v[78:79], v[224:225]
	v_mov_b64_e32 v[68:69], v[116:117]
	v_mov_b64_e32 v[70:71], v[118:119]
	v_mov_b64_e32 v[64:65], v[196:197]
	v_mov_b64_e32 v[66:67], v[198:199]
	v_mov_b64_e32 v[72:73], v[204:205]
	v_mov_b64_e32 v[74:75], v[206:207]
	v_add_f32_e32 v56, v56, v68
	v_mul_f32_e32 v56, 0xbfb8aa3b, v56
	v_mul_f32_e32 v72, 0xbfb8aa3b, v72
	v_exp_f32_e32 v72, v72
	v_mul_f32_e32 v73, 0xbfb8aa3b, v73
	v_exp_f32_e32 v73, v73
	v_mul_f32_e32 v74, 0xbfb8aa3b, v74
	v_add_f32_e32 v102, 1.0, v72
	v_add_f32_e32 v100, -1.0, v102
	v_sub_f32_e32 v101, v100, v102
	v_add_f32_e32 v101, 1.0, v101
	v_sub_f32_e32 v100, v72, v100
	v_add_f32_e32 v103, v100, v101
	v_frexp_mant_f32_e32 v100, v102
	v_cmp_gt_f32_e32 vcc, s76, v100
	v_cvt_f64_f32_e32 v[100:101], v102
	v_frexp_exp_i32_f64_e32 v100, v[100:101]
	v_subbrev_co_u32_e32 v110, vcc, 0, v100, vcc
	v_sub_u32_e32 v100, 0, v110
	v_ldexp_f32 v101, v102, v100
	v_add_f32_e32 v102, -1.0, v101
	v_add_f32_e32 v106, 1.0, v101
	v_ldexp_f32 v100, v103, v100
	v_add_f32_e32 v103, 1.0, v102
	v_add_f32_e32 v107, -1.0, v106
	v_sub_f32_e32 v103, v101, v103
	v_sub_f32_e32 v101, v101, v107
	v_add_f32_e32 v103, v100, v103
	v_add_f32_e32 v100, v100, v101
	v_add_f32_e32 v111, v106, v100
	v_rcp_f32_e32 v115, v111
	v_sub_f32_e32 v101, v111, v106
	v_sub_f32_e32 v114, v100, v101
	v_add_f32_e32 v101, v102, v103
	v_mul_f32_e32 v117, v101, v115
	v_sub_f32_e32 v100, v101, v102
	v_mul_f32_e32 v102, v111, v117
	v_fma_f32 v106, v117, v111, -v102
	v_fmac_f32_e32 v106, v117, v114
	v_sub_f32_e32 v116, v103, v100
	v_add_f32_e32 v100, v102, v106
	v_sub_f32_e32 v103, v101, v100
	v_pk_add_f32 v[108:109], v[100:101], v[102:103] neg_lo:[0,1] neg_hi:[0,1]
	v_mov_b32_e32 v107, v100
	v_pk_add_f32 v[100:101], v[108:109], v[106:107] neg_lo:[0,1] neg_hi:[0,1]
	v_cmp_neq_f32_e32 vcc, s78, v72
	v_add_f32_e32 v101, v116, v101
	v_add_f32_e32 v100, v100, v101
	v_add_f32_e32 v101, v103, v100
	v_mul_f32_e32 v116, v115, v101
	v_mul_f32_e32 v102, v111, v116
	v_fma_f32 v106, v116, v111, -v102
	v_fmac_f32_e32 v106, v116, v114
	v_sub_f32_e32 v103, v103, v101
	v_add_f32_e32 v111, v100, v103
	v_add_f32_e32 v100, v102, v106
	v_sub_f32_e32 v103, v101, v100
	v_pk_add_f32 v[108:109], v[100:101], v[102:103] neg_lo:[0,1] neg_hi:[0,1]
	v_mov_b32_e32 v107, v100
	v_pk_add_f32 v[100:101], v[108:109], v[106:107] neg_lo:[0,1] neg_hi:[0,1]
	v_exp_f32_e32 v74, v74
	v_add_f32_e32 v101, v111, v101
	v_add_f32_e32 v100, v100, v101
	v_add_f32_e32 v101, v117, v116
	v_add_f32_e32 v100, v103, v100
	v_sub_f32_e32 v102, v101, v117
	v_mul_f32_e32 v100, v115, v100
	v_sub_f32_e32 v102, v116, v102
	v_add_f32_e32 v102, v102, v100
	v_add_f32_e32 v106, v101, v102
	v_mul_f32_e32 v107, v106, v106
	v_fmamk_f32 v100, v107, 0x3e9b6dac, v218
	v_fmaak_f32 v153, v107, v100, 0x3f2aaada
	v_cvt_f32_i32_e32 v100, v110
	v_sub_f32_e32 v101, v106, v101
	v_sub_f32_e32 v101, v102, v101
	v_ldexp_f32 v108, v101, 1
	v_mul_f32_e32 v101, v106, v107
	v_ldexp_f32 v103, v106, 1
	v_pk_mul_f32 v[106:107], v[100:101], v[152:153]
	v_mul_f32_e32 v75, 0xbfb8aa3b, v75
	v_fma_f32 v102, v100, s77, -v106
	v_fmac_f32_e32 v102, 0xb102e308, v100
	v_pk_add_f32 v[100:101], v[106:107], v[102:103]
	v_exp_f32_e32 v75, v75
	v_sub_f32_e32 v103, v101, v103
	v_sub_f32_e32 v103, v107, v103
	v_add_f32_e32 v109, v108, v103
	v_mov_b32_e32 v108, v106
	v_pk_add_f32 v[106:107], v[100:101], v[106:107] neg_lo:[0,1] neg_hi:[0,1]
	v_pk_add_f32 v[110:111], v[100:101], v[108:109]
	v_mov_b32_e32 v103, v100
	v_mov_b32_e32 v107, v111
	v_pk_add_f32 v[114:115], v[102:103], v[106:107] neg_lo:[0,1] neg_hi:[0,1]
	v_pk_add_f32 v[102:103], v[102:103], v[106:107]
	v_mov_b32_e32 v108, v109
	v_pk_add_f32 v[106:107], v[102:103], v[100:101] op_sel:[1,0] op_sel_hi:[0,1] neg_lo:[0,1] neg_hi:[0,1]
	v_pk_add_f32 v[116:117], v[110:111], v[106:107] op_sel_hi:[1,0] neg_lo:[0,1] neg_hi:[0,1]
	v_mov_b32_e32 v110, v111
	v_mov_b32_e32 v111, v103
	v_pk_mov_b32 v[106:107], v[100:101], v[106:107] op_sel:[1,0]
	v_mov_b32_e32 v109, v100
	v_pk_add_f32 v[106:107], v[110:111], v[106:107] neg_lo:[0,1] neg_hi:[0,1]
	v_mov_b32_e32 v116, v114
	v_pk_add_f32 v[100:101], v[108:109], v[106:107] neg_lo:[0,1] neg_hi:[0,1]
	v_mov_b32_e32 v115, v103
	v_pk_add_f32 v[106:107], v[116:117], v[100:101]
	v_exp_f32_e32 v56, v56
	v_pk_add_f32 v[108:109], v[106:107], v[106:107] op_sel:[0,1] op_sel_hi:[1,0]
	v_add_f32_e32 v60, v60, v64
	v_pk_add_f32 v[102:103], v[102:103], v[108:109] op_sel:[1,0] op_sel_hi:[0,1]
	v_mov_b32_e32 v107, v102
	v_pk_add_f32 v[110:111], v[106:107], v[114:115] neg_lo:[0,1] neg_hi:[0,1]
	v_mov_b32_e32 v101, v108
	v_sub_f32_e32 v103, v106, v110
	v_pk_add_f32 v[100:101], v[100:101], v[110:111] neg_lo:[0,1] neg_hi:[0,1]
	v_sub_f32_e32 v103, v114, v103
	v_add_f32_e32 v100, v100, v103
	v_add_f32_e32 v100, v100, v101
	v_add_f32_e32 v100, v102, v100
	v_cndmask_b32_e32 v100, v219, v100, vcc
	v_cmp_ngt_f32_e32 vcc, -1.0, v72
	v_add_f32_e32 v102, 1.0, v73
	v_add_f32_e32 v56, 1.0, v56
	v_cndmask_b32_e32 v100, v220, v100, vcc
	v_cmp_neq_f32_e32 vcc, -1.0, v72
	v_rcp_f32_e32 v56, v56
	v_add_f32_e32 v57, v57, v69
	v_cndmask_b32_e32 v100, v221, v100, vcc
	v_cmp_lt_f32_e64 vcc, |v72|, s79
	v_mul_f32_e32 v60, 0xbfb8aa3b, v60
	v_mul_f32_e32 v57, 0xbfb8aa3b, v57
	v_cndmask_b32_e32 v72, v100, v72, vcc
	v_add_f32_e32 v100, -1.0, v102
	v_sub_f32_e32 v101, v100, v102
	v_add_f32_e32 v101, 1.0, v101
	v_sub_f32_e32 v100, v73, v100
	v_add_f32_e32 v103, v100, v101
;     __device__ __forceinline__ void operator()(const AccT& acc, const Unit& u, int wr, int wc, int fr, int fq) const {
;     ...
;             for (int j = 0; j < 4; ++j) sp[j] = -8.0f * log1pf(__expf(-l[j]));
;     ...
;                     for (int j = 0; j < 4; ++j) { const float r = __builtin_amdgcn_rcpf(1.0f + __expf(-rp[j])), ig = __builtin_amdgcn_rcpf(1.0f + __expf(-ip[j])); const float la = sp[j] * r; const float d = 1.0f - __expf(la);
	v_frexp_mant_f32_e32 v100, v102
	v_cmp_gt_f32_e32 vcc, s76, v100
	v_cvt_f64_f32_e32 v[100:101], v102
	v_frexp_exp_i32_f64_e32 v100, v[100:101]
	v_subbrev_co_u32_e32 v110, vcc, 0, v100, vcc
	v_sub_u32_e32 v100, 0, v110
	v_ldexp_f32 v101, v102, v100
	v_add_f32_e32 v102, -1.0, v101
	v_add_f32_e32 v106, 1.0, v101
	v_ldexp_f32 v100, v103, v100
	v_add_f32_e32 v103, 1.0, v102
	v_add_f32_e32 v107, -1.0, v106
	v_sub_f32_e32 v103, v101, v103
	v_sub_f32_e32 v101, v101, v107
	v_add_f32_e32 v103, v100, v103
	v_add_f32_e32 v100, v100, v101
	v_add_f32_e32 v111, v106, v100
	v_rcp_f32_e32 v115, v111
	v_sub_f32_e32 v101, v111, v106
	v_sub_f32_e32 v114, v100, v101
	v_add_f32_e32 v101, v102, v103
	v_mul_f32_e32 v117, v101, v115
	v_sub_f32_e32 v100, v101, v102
	v_mul_f32_e32 v102, v111, v117
	v_fma_f32 v106, v117, v111, -v102
	v_fmac_f32_e32 v106, v117, v114
	v_sub_f32_e32 v116, v103, v100
	v_add_f32_e32 v100, v102, v106
	v_sub_f32_e32 v103, v101, v100
	v_pk_add_f32 v[108:109], v[100:101], v[102:103] neg_lo:[0,1] neg_hi:[0,1]
	v_mov_b32_e32 v107, v100
	v_pk_add_f32 v[100:101], v[108:109], v[106:107] neg_lo:[0,1] neg_hi:[0,1]
	v_cmp_neq_f32_e32 vcc, s78, v73
	v_add_f32_e32 v101, v116, v101
	v_add_f32_e32 v100, v100, v101
	v_add_f32_e32 v101, v103, v100
	v_mul_f32_e32 v116, v115, v101
	v_mul_f32_e32 v102, v111, v116
	v_fma_f32 v106, v116, v111, -v102
	v_fmac_f32_e32 v106, v116, v114
	v_sub_f32_e32 v103, v103, v101
	v_add_f32_e32 v111, v100, v103
	v_add_f32_e32 v100, v102, v106
	v_sub_f32_e32 v103, v101, v100
	v_pk_add_f32 v[108:109], v[100:101], v[102:103] neg_lo:[0,1] neg_hi:[0,1]
	v_mov_b32_e32 v107, v100
	v_pk_add_f32 v[100:101], v[108:109], v[106:107] neg_lo:[0,1] neg_hi:[0,1]
	v_mul_f32_e32 v72, 0xc1000000, v72
	v_add_f32_e32 v101, v111, v101
	v_add_f32_e32 v100, v100, v101
	v_add_f32_e32 v101, v117, v116
	v_add_f32_e32 v100, v103, v100
	v_sub_f32_e32 v102, v101, v117
	v_mul_f32_e32 v100, v115, v100
	v_sub_f32_e32 v102, v116, v102
	v_add_f32_e32 v102, v102, v100
	v_add_f32_e32 v106, v101, v102
	v_mul_f32_e32 v107, v106, v106
	v_fmamk_f32 v100, v107, 0x3e9b6dac, v218
	v_fmaak_f32 v153, v107, v100, 0x3f2aaada
	v_cvt_f32_i32_e32 v100, v110
	v_sub_f32_e32 v101, v106, v101
	v_sub_f32_e32 v101, v102, v101
	v_ldexp_f32 v108, v101, 1
	v_mul_f32_e32 v101, v106, v107
	v_ldexp_f32 v103, v106, 1
	v_pk_mul_f32 v[106:107], v[100:101], v[152:153]
	v_mul_f32_e32 v56, v56, v72
	v_fma_f32 v102, v100, s77, -v106
	v_fmac_f32_e32 v102, 0xb102e308, v100
	v_pk_add_f32 v[100:101], v[106:107], v[102:103]
	v_mul_f32_e32 v56, 0x3fb8aa3b, v56
	v_sub_f32_e32 v103, v101, v103
	v_sub_f32_e32 v103, v107, v103
	v_add_f32_e32 v109, v108, v103
	v_mov_b32_e32 v108, v106
	v_pk_add_f32 v[106:107], v[100:101], v[106:107] neg_lo:[0,1] neg_hi:[0,1]
	v_pk_add_f32 v[110:111], v[100:101], v[108:109]
	v_mov_b32_e32 v103, v100
	v_mov_b32_e32 v107, v111
	v_pk_add_f32 v[114:115], v[102:103], v[106:107] neg_lo:[0,1] neg_hi:[0,1]
	v_pk_add_f32 v[102:103], v[102:103], v[106:107]
	v_mov_b32_e32 v108, v109
	v_pk_add_f32 v[106:107], v[102:103], v[100:101] op_sel:[1,0] op_sel_hi:[0,1] neg_lo:[0,1] neg_hi:[0,1]
	v_pk_add_f32 v[116:117], v[110:111], v[106:107] op_sel_hi:[1,0] neg_lo:[0,1] neg_hi:[0,1]
	v_mov_b32_e32 v110, v111
	v_mov_b32_e32 v111, v103
	v_pk_mov_b32 v[106:107], v[100:101], v[106:107] op_sel:[1,0]
	v_mov_b32_e32 v109, v100
	v_pk_add_f32 v[106:107], v[110:111], v[106:107] neg_lo:[0,1] neg_hi:[0,1]
	v_mov_b32_e32 v116, v114
	v_pk_add_f32 v[100:101], v[108:109], v[106:107] neg_lo:[0,1] neg_hi:[0,1]
	v_mov_b32_e32 v115, v103
	v_pk_add_f32 v[106:107], v[116:117], v[100:101]
	v_exp_f32_e32 v56, v56
	v_pk_add_f32 v[108:109], v[106:107], v[106:107] op_sel:[0,1] op_sel_hi:[1,0]
	v_exp_f32_e32 v60, v60
	v_pk_add_f32 v[102:103], v[102:103], v[108:109] op_sel:[1,0] op_sel_hi:[0,1]
	v_mov_b32_e32 v107, v102
	v_pk_add_f32 v[110:111], v[106:107], v[114:115] neg_lo:[0,1] neg_hi:[0,1]
	v_mov_b32_e32 v101, v108
	v_sub_f32_e32 v103, v106, v110
	v_pk_add_f32 v[100:101], v[100:101], v[110:111] neg_lo:[0,1] neg_hi:[0,1]
	v_sub_f32_e32 v103, v114, v103
	v_add_f32_e32 v100, v100, v103
	v_add_f32_e32 v100, v100, v101
	v_add_f32_e32 v100, v102, v100
	v_cndmask_b32_e32 v100, v219, v100, vcc
	v_cmp_ngt_f32_e32 vcc, -1.0, v73
	v_add_f32_e32 v102, 1.0, v74
	v_exp_f32_e32 v57, v57
	v_cndmask_b32_e32 v100, v220, v100, vcc
	v_cmp_neq_f32_e32 vcc, -1.0, v73
	v_sub_f32_e32 v56, 1.0, v56
	v_add_f32_e32 v60, 1.0, v60
	v_cndmask_b32_e32 v100, v221, v100, vcc
	v_cmp_lt_f32_e64 vcc, |v73|, s79
	v_add_f32_e32 v57, 1.0, v57
	v_rcp_f32_e32 v60, v60
	v_cndmask_b32_e32 v73, v100, v73, vcc
	v_add_f32_e32 v100, -1.0, v102
	v_sub_f32_e32 v101, v100, v102
	v_add_f32_e32 v101, 1.0, v101
	v_sub_f32_e32 v100, v74, v100
	v_add_f32_e32 v103, v100, v101
	v_frexp_mant_f32_e32 v100, v102
	v_cmp_gt_f32_e32 vcc, s76, v100
	v_cvt_f64_f32_e32 v[100:101], v102
	v_frexp_exp_i32_f64_e32 v100, v[100:101]
	v_subbrev_co_u32_e32 v110, vcc, 0, v100, vcc
	v_sub_u32_e32 v100, 0, v110
	v_ldexp_f32 v101, v102, v100
	v_add_f32_e32 v102, -1.0, v101
	v_add_f32_e32 v106, 1.0, v101
	v_ldexp_f32 v100, v103, v100
	v_add_f32_e32 v103, 1.0, v102
	v_add_f32_e32 v107, -1.0, v106
	v_sub_f32_e32 v103, v101, v103
	v_sub_f32_e32 v101, v101, v107
	v_add_f32_e32 v103, v100, v103
	v_add_f32_e32 v100, v100, v101
	v_add_f32_e32 v111, v106, v100
	v_rcp_f32_e32 v115, v111
	v_sub_f32_e32 v101, v111, v106
	v_sub_f32_e32 v114, v100, v101
	v_add_f32_e32 v101, v102, v103
	v_mul_f32_e32 v117, v101, v115
	v_sub_f32_e32 v100, v101, v102
	v_mul_f32_e32 v102, v111, v117
	v_fma_f32 v106, v117, v111, -v102
	v_fmac_f32_e32 v106, v117, v114
	v_sub_f32_e32 v116, v103, v100
	v_add_f32_e32 v100, v102, v106
;     __device__ __forceinline__ void operator()(const AccT& acc, const Unit& u, int wr, int wc, int fr, int fq) const {
;     ...
;             for (int j = 0; j < 4; ++j) sp[j] = -8.0f * log1pf(__expf(-l[j]));
;     ...
;                     for (int j = 0; j < 4; ++j) { const float r = __builtin_amdgcn_rcpf(1.0f + __expf(-rp[j])), ig = __builtin_amdgcn_rcpf(1.0f + __expf(-ip[j])); const float la = sp[j] * r; const float d = 1.0f - __expf(la);
	v_sub_f32_e32 v103, v101, v100
	v_pk_add_f32 v[108:109], v[100:101], v[102:103] neg_lo:[0,1] neg_hi:[0,1]
	v_mov_b32_e32 v107, v100
	v_pk_add_f32 v[100:101], v[108:109], v[106:107] neg_lo:[0,1] neg_hi:[0,1]
	v_cmp_neq_f32_e32 vcc, s78, v74
	v_add_f32_e32 v101, v116, v101
	v_add_f32_e32 v100, v100, v101
	v_add_f32_e32 v101, v103, v100
	v_mul_f32_e32 v116, v115, v101
	v_mul_f32_e32 v102, v111, v116
	v_fma_f32 v106, v116, v111, -v102
	v_fmac_f32_e32 v106, v116, v114
	v_sub_f32_e32 v103, v103, v101
	v_add_f32_e32 v111, v100, v103
	v_add_f32_e32 v100, v102, v106
	v_sub_f32_e32 v103, v101, v100
	v_pk_add_f32 v[108:109], v[100:101], v[102:103] neg_lo:[0,1] neg_hi:[0,1]
	v_mov_b32_e32 v107, v100
	v_pk_add_f32 v[100:101], v[108:109], v[106:107] neg_lo:[0,1] neg_hi:[0,1]
	v_rcp_f32_e32 v57, v57
	v_add_f32_e32 v101, v111, v101
	v_add_f32_e32 v100, v100, v101
	v_add_f32_e32 v101, v117, v116
	v_add_f32_e32 v100, v103, v100
	v_sub_f32_e32 v102, v101, v117
	v_mul_f32_e32 v100, v115, v100
	v_sub_f32_e32 v102, v116, v102
	v_add_f32_e32 v102, v102, v100
	v_add_f32_e32 v106, v101, v102
	v_mul_f32_e32 v107, v106, v106
	v_fmamk_f32 v100, v107, 0x3e9b6dac, v218
	v_fmaak_f32 v153, v107, v100, 0x3f2aaada
	v_cvt_f32_i32_e32 v100, v110
	v_sub_f32_e32 v101, v106, v101
	v_sub_f32_e32 v101, v102, v101
	v_ldexp_f32 v108, v101, 1
	v_mul_f32_e32 v101, v106, v107
	v_ldexp_f32 v103, v106, 1
	v_pk_mul_f32 v[106:107], v[100:101], v[152:153]
	v_mul_f32_e32 v73, 0xc1000000, v73
	v_fma_f32 v102, v100, s77, -v106
	v_fmac_f32_e32 v102, 0xb102e308, v100
	v_pk_add_f32 v[100:101], v[106:107], v[102:103]
	v_mul_f32_e32 v57, v57, v73
	v_sub_f32_e32 v103, v101, v103
	v_sub_f32_e32 v103, v107, v103
	v_add_f32_e32 v109, v108, v103
	v_mov_b32_e32 v108, v106
	v_pk_add_f32 v[106:107], v[100:101], v[106:107] neg_lo:[0,1] neg_hi:[0,1]
	v_pk_add_f32 v[110:111], v[100:101], v[108:109]
	v_mov_b32_e32 v103, v100
	v_mov_b32_e32 v107, v111
	v_pk_add_f32 v[114:115], v[102:103], v[106:107] neg_lo:[0,1] neg_hi:[0,1]
	v_pk_add_f32 v[102:103], v[102:103], v[106:107]
	v_mov_b32_e32 v108, v109
	v_pk_add_f32 v[106:107], v[102:103], v[100:101] op_sel:[1,0] op_sel_hi:[0,1] neg_lo:[0,1] neg_hi:[0,1]
	v_pk_add_f32 v[116:117], v[110:111], v[106:107] op_sel_hi:[1,0] neg_lo:[0,1] neg_hi:[0,1]
	v_mov_b32_e32 v110, v111
	v_mov_b32_e32 v111, v103
	v_pk_mov_b32 v[106:107], v[100:101], v[106:107] op_sel:[1,0]
	v_mov_b32_e32 v109, v100
	v_pk_add_f32 v[106:107], v[110:111], v[106:107] neg_lo:[0,1] neg_hi:[0,1]
	v_mov_b32_e32 v116, v114
	v_pk_add_f32 v[100:101], v[108:109], v[106:107] neg_lo:[0,1] neg_hi:[0,1]
	v_mov_b32_e32 v115, v103
	v_pk_add_f32 v[106:107], v[116:117], v[100:101]
	v_mul_f32_e32 v57, 0x3fb8aa3b, v57
	v_pk_add_f32 v[108:109], v[106:107], v[106:107] op_sel:[0,1] op_sel_hi:[1,0]
	v_exp_f32_e32 v57, v57
	v_pk_add_f32 v[102:103], v[102:103], v[108:109] op_sel:[1,0] op_sel_hi:[0,1]
	v_mov_b32_e32 v107, v102
	v_pk_add_f32 v[110:111], v[106:107], v[114:115] neg_lo:[0,1] neg_hi:[0,1]
	v_mov_b32_e32 v101, v108
	v_sub_f32_e32 v103, v106, v110
	v_pk_add_f32 v[100:101], v[100:101], v[110:111] neg_lo:[0,1] neg_hi:[0,1]
	v_sub_f32_e32 v103, v114, v103
	v_add_f32_e32 v100, v100, v103
	v_add_f32_e32 v100, v100, v101
	v_add_f32_e32 v100, v102, v100
	v_cndmask_b32_e32 v100, v219, v100, vcc
	v_cmp_ngt_f32_e32 vcc, -1.0, v74
	v_add_f32_e32 v102, 1.0, v75
	v_add_f32_e32 v58, v58, v70
	v_cndmask_b32_e32 v100, v220, v100, vcc
	v_cmp_neq_f32_e32 vcc, -1.0, v74
	v_mul_f32_e32 v58, 0xbfb8aa3b, v58
	v_exp_f32_e32 v58, v58
	v_cndmask_b32_e32 v100, v221, v100, vcc
	v_cmp_lt_f32_e64 vcc, |v74|, s79
	v_sub_f32_e32 v57, 1.0, v57
	v_add_f32_e32 v58, 1.0, v58
	v_cndmask_b32_e32 v74, v100, v74, vcc
	v_add_f32_e32 v100, -1.0, v102
	v_sub_f32_e32 v101, v100, v102
	v_add_f32_e32 v101, 1.0, v101
	v_sub_f32_e32 v100, v75, v100
	v_add_f32_e32 v103, v100, v101
	v_frexp_mant_f32_e32 v100, v102
	v_cmp_gt_f32_e32 vcc, s76, v100
	v_cvt_f64_f32_e32 v[100:101], v102
	v_frexp_exp_i32_f64_e32 v100, v[100:101]
	v_subbrev_co_u32_e32 v110, vcc, 0, v100, vcc
	v_sub_u32_e32 v100, 0, v110
	v_ldexp_f32 v101, v102, v100
	v_add_f32_e32 v102, -1.0, v101
	v_add_f32_e32 v106, 1.0, v101
	v_ldexp_f32 v100, v103, v100
	v_add_f32_e32 v103, 1.0, v102
	v_add_f32_e32 v107, -1.0, v106
	v_sub_f32_e32 v103, v101, v103
	v_sub_f32_e32 v101, v101, v107
	v_add_f32_e32 v103, v100, v103
	v_add_f32_e32 v100, v100, v101
	v_add_f32_e32 v111, v106, v100
	v_rcp_f32_e32 v115, v111
	v_sub_f32_e32 v101, v111, v106
	v_sub_f32_e32 v114, v100, v101
	v_add_f32_e32 v101, v102, v103
	v_mul_f32_e32 v117, v101, v115
	v_sub_f32_e32 v100, v101, v102
	v_mul_f32_e32 v102, v111, v117
	v_fma_f32 v106, v117, v111, -v102
	v_fmac_f32_e32 v106, v117, v114
	v_sub_f32_e32 v116, v103, v100
	v_add_f32_e32 v100, v102, v106
	v_sub_f32_e32 v103, v101, v100
	v_pk_add_f32 v[108:109], v[100:101], v[102:103] neg_lo:[0,1] neg_hi:[0,1]
	v_mov_b32_e32 v107, v100
	v_pk_add_f32 v[100:101], v[108:109], v[106:107] neg_lo:[0,1] neg_hi:[0,1]
	v_cmp_neq_f32_e32 vcc, s78, v75
	v_add_f32_e32 v101, v116, v101
	v_add_f32_e32 v100, v100, v101
	v_add_f32_e32 v101, v103, v100
	v_mul_f32_e32 v116, v115, v101
	v_mul_f32_e32 v102, v111, v116
	v_fma_f32 v106, v116, v111, -v102
	v_fmac_f32_e32 v106, v116, v114
	v_sub_f32_e32 v103, v103, v101
	v_add_f32_e32 v111, v100, v103
	v_add_f32_e32 v100, v102, v106
	v_sub_f32_e32 v103, v101, v100
	v_pk_add_f32 v[108:109], v[100:101], v[102:103] neg_lo:[0,1] neg_hi:[0,1]
	v_mov_b32_e32 v107, v100
	v_pk_add_f32 v[100:101], v[108:109], v[106:107] neg_lo:[0,1] neg_hi:[0,1]
	v_rcp_f32_e32 v58, v58
	v_add_f32_e32 v101, v111, v101
	v_add_f32_e32 v100, v100, v101
	v_add_f32_e32 v101, v117, v116
; __device__ __forceinline__ unsigned cvt_pk_bf16(float lo, float hi) { const bf16x2_t r = __builtin_convertvector((f32x2){lo, hi}, bf16x2_t); return __builtin_bit_cast(unsigned, r); }
; __device__ __forceinline__ float bf_lo(unsigned w) { return __uint_as_float(w << 16); }
; __device__ __forceinline__ float bf_hi(unsigned w) { return __uint_as_float(w & 0xffff0000u); }
;     __device__ __forceinline__ void operator()(const AccT& acc, const Unit& u, int wr, int wc, int fr, int fq) const {
;     ...
;                     const f32x4 rp = acc[ai][0][m][n] + bra, ip = acc[ai][1][m][n] + bri;
;                     const u32x2 w = xw[ai][m]; const float xv[4] = {bf_lo(w.x), bf_hi(w.x), bf_lo(w.y), bf_hi(w.y)};
;                     u32x4 o;
; #pragma unroll
;                     for (int j = 0; j < 4; ++j) { const float r = __builtin_amdgcn_rcpf(1.0f + __expf(-rp[j])), ig = __builtin_amdgcn_rcpf(1.0f + __expf(-ip[j])); const float la = sp[j] * r; const float d = 1.0f - __expf(la);
;                         o[j] = cvt_pk_bf16(d, __builtin_amdgcn_sqrtf(fmaxf(d * (2.0f - d), 0.f)) * (ig * xv[j])); }
;                     *(u32x4*)(AU + off) = o; }
	v_add_f32_e32 v100, v103, v100
	v_sub_f32_e32 v102, v101, v117
	v_mul_f32_e32 v100, v115, v100
	v_sub_f32_e32 v102, v116, v102
	v_add_f32_e32 v102, v102, v100
	v_add_f32_e32 v106, v101, v102
	v_mul_f32_e32 v107, v106, v106
	v_fmamk_f32 v100, v107, 0x3e9b6dac, v218
	v_fmaak_f32 v153, v107, v100, 0x3f2aaada
	v_cvt_f32_i32_e32 v100, v110
	v_sub_f32_e32 v101, v106, v101
	v_sub_f32_e32 v101, v102, v101
	v_ldexp_f32 v108, v101, 1
	v_mul_f32_e32 v101, v106, v107
	v_ldexp_f32 v103, v106, 1
	v_pk_mul_f32 v[106:107], v[100:101], v[152:153]
	v_mul_f32_e32 v74, 0xc1000000, v74
	v_fma_f32 v102, v100, s77, -v106
	v_fmac_f32_e32 v102, 0xb102e308, v100
	v_pk_add_f32 v[100:101], v[106:107], v[102:103]
	v_mul_f32_e32 v58, v58, v74
	v_sub_f32_e32 v103, v101, v103
	v_sub_f32_e32 v103, v107, v103
	v_add_f32_e32 v109, v108, v103
	v_mov_b32_e32 v108, v106
	v_pk_add_f32 v[106:107], v[100:101], v[106:107] neg_lo:[0,1] neg_hi:[0,1]
	v_pk_add_f32 v[110:111], v[100:101], v[108:109]
	v_mov_b32_e32 v103, v100
	v_mov_b32_e32 v107, v111
	v_pk_add_f32 v[114:115], v[102:103], v[106:107] neg_lo:[0,1] neg_hi:[0,1]
	v_pk_add_f32 v[102:103], v[102:103], v[106:107]
	v_mov_b32_e32 v108, v109
	v_pk_add_f32 v[106:107], v[102:103], v[100:101] op_sel:[1,0] op_sel_hi:[0,1] neg_lo:[0,1] neg_hi:[0,1]
	v_pk_add_f32 v[116:117], v[110:111], v[106:107] op_sel_hi:[1,0] neg_lo:[0,1] neg_hi:[0,1]
	v_mov_b32_e32 v110, v111
	v_mov_b32_e32 v111, v103
	v_pk_mov_b32 v[106:107], v[100:101], v[106:107] op_sel:[1,0]
	v_mov_b32_e32 v109, v100
	v_pk_add_f32 v[106:107], v[110:111], v[106:107] neg_lo:[0,1] neg_hi:[0,1]
	v_mov_b32_e32 v116, v114
	v_pk_add_f32 v[100:101], v[108:109], v[106:107] neg_lo:[0,1] neg_hi:[0,1]
	v_mov_b32_e32 v115, v103
	v_pk_add_f32 v[106:107], v[116:117], v[100:101]
	v_mul_f32_e32 v58, 0x3fb8aa3b, v58
	v_pk_add_f32 v[108:109], v[106:107], v[106:107] op_sel:[0,1] op_sel_hi:[1,0]
	v_exp_f32_e32 v58, v58
	v_pk_add_f32 v[102:103], v[102:103], v[108:109] op_sel:[1,0] op_sel_hi:[0,1]
	v_mov_b32_e32 v107, v102
	v_pk_add_f32 v[110:111], v[106:107], v[114:115] neg_lo:[0,1] neg_hi:[0,1]
	v_mov_b32_e32 v101, v108
	v_sub_f32_e32 v103, v106, v110
	v_pk_add_f32 v[100:101], v[100:101], v[110:111] neg_lo:[0,1] neg_hi:[0,1]
	v_sub_f32_e32 v103, v114, v103
	v_add_f32_e32 v100, v100, v103
	v_add_f32_e32 v100, v100, v101
	v_add_f32_e32 v100, v102, v100
	v_sub_f32_e32 v102, 2.0, v56
	v_mul_f32_e32 v102, v56, v102
	v_cndmask_b32_e32 v100, v219, v100, vcc
	v_cmp_ngt_f32_e32 vcc, -1.0, v75
	v_max_f32_e32 v102, 0, v102
	v_sqrt_f32_e32 v102, v102
	v_cndmask_b32_e32 v100, v220, v100, vcc
	v_cmp_neq_f32_e32 vcc, -1.0, v75
	v_add_f32_e32 v59, v59, v71
	v_mul_f32_e32 v59, 0xbfb8aa3b, v59
	v_cndmask_b32_e32 v100, v221, v100, vcc
	v_cmp_lt_f32_e64 vcc, |v75|, s79
	v_exp_f32_e32 v59, v59
	v_sub_f32_e32 v58, 1.0, v58
	v_cndmask_b32_e32 v75, v100, v75, vcc
	v_lshlrev_b32_e32 v100, 16, v98
	v_mul_f32_e32 v60, v60, v100
	v_mul_f32_e32 v60, v60, v102
	v_cvt_pk_bf16_f32 v56, v56, v60
	v_add_f32_e32 v60, v61, v65
	v_mul_f32_e32 v60, 0xbfb8aa3b, v60
	v_exp_f32_e32 v60, v60
	v_sub_f32_e32 v61, 2.0, v57
	v_mul_f32_e32 v61, v57, v61
	v_max_f32_e32 v61, 0, v61
	v_add_f32_e32 v60, 1.0, v60
	v_rcp_f32_e32 v60, v60
	v_sqrt_f32_e32 v61, v61
	v_and_b32_e32 v98, 0xffff0000, v98
	v_add_f32_e32 v59, 1.0, v59
	v_mul_f32_e32 v60, v60, v98
	v_mul_f32_e32 v60, v60, v61
	v_cvt_pk_bf16_f32 v57, v57, v60
	v_add_f32_e32 v60, v62, v66
	v_mul_f32_e32 v60, 0xbfb8aa3b, v60
	v_exp_f32_e32 v60, v60
	v_sub_f32_e32 v61, 2.0, v58
	v_mul_f32_e32 v61, v58, v61
	v_max_f32_e32 v61, 0, v61
	v_add_f32_e32 v60, 1.0, v60
	v_rcp_f32_e32 v60, v60
	v_rcp_f32_e32 v59, v59
	v_sqrt_f32_e32 v61, v61
	v_add_f32_e32 v48, v48, v68
	v_mul_f32_e32 v48, 0xbfb8aa3b, v48
	v_mul_f32_e32 v75, 0xc1000000, v75
	v_lshlrev_b32_e32 v101, 16, v99
	v_exp_f32_e32 v48, v48
	v_mul_f32_e32 v60, v60, v101
	v_mul_f32_e32 v59, v59, v75
	v_mul_f32_e32 v60, v60, v61
	v_mul_f32_e32 v59, 0x3fb8aa3b, v59
	v_cvt_pk_bf16_f32 v58, v58, v60
	v_add_f32_e32 v60, v63, v67
	v_exp_f32_e32 v59, v59
	v_mul_f32_e32 v60, 0xbfb8aa3b, v60
	v_add_f32_e32 v48, 1.0, v48
	v_exp_f32_e32 v60, v60
	v_rcp_f32_e32 v48, v48
	v_sub_f32_e32 v59, 1.0, v59
	v_sub_f32_e32 v61, 2.0, v59
	v_add_f32_e32 v60, 1.0, v60
	v_mul_f32_e32 v61, v59, v61
	v_mul_f32_e32 v48, v48, v72
	v_rcp_f32_e32 v60, v60
	v_max_f32_e32 v61, 0, v61
	v_mul_f32_e32 v48, 0x3fb8aa3b, v48
	v_sqrt_f32_e32 v61, v61
	v_add_f32_e32 v52, v52, v64
	v_exp_f32_e32 v48, v48
	v_add_f32_e32 v49, v49, v69
	v_mul_f32_e32 v52, 0xbfb8aa3b, v52
	v_mul_f32_e32 v49, 0xbfb8aa3b, v49
	v_and_b32_e32 v99, 0xffff0000, v99
	v_exp_f32_e32 v52, v52
	v_exp_f32_e32 v49, v49
	v_mul_f32_e32 v60, v60, v99
	v_mul_f32_e32 v60, v60, v61
	v_sub_f32_e32 v48, 1.0, v48
	v_cvt_pk_bf16_f32 v59, v59, v60
	v_sub_f32_e32 v60, 2.0, v48
	v_add_f32_e32 v52, 1.0, v52
	v_mul_f32_e32 v60, v48, v60
	v_add_f32_e32 v49, 1.0, v49
	v_rcp_f32_e32 v52, v52
	v_max_f32_e32 v60, 0, v60
	v_rcp_f32_e32 v49, v49
	v_sqrt_f32_e32 v60, v60
	global_store_dwordx4 v[128:129], v[56:59], off offset:64
	v_add_f32_e32 v50, v50, v70
	v_mul_f32_e32 v49, v49, v73
	v_lshlrev_b32_e32 v56, 16, v94
	v_mul_f32_e32 v52, v52, v56
	v_mul_f32_e32 v52, v52, v60
	v_mul_f32_e32 v49, 0x3fb8aa3b, v49
	v_cvt_pk_bf16_f32 v48, v48, v52
	v_add_f32_e32 v52, v53, v65
	v_exp_f32_e32 v49, v49
	v_mul_f32_e32 v52, 0xbfb8aa3b, v52
	v_mul_f32_e32 v50, 0xbfb8aa3b, v50
	v_exp_f32_e32 v52, v52
	v_exp_f32_e32 v50, v50
	v_sub_f32_e32 v49, 1.0, v49
	v_sub_f32_e32 v53, 2.0, v49
	v_add_f32_e32 v52, 1.0, v52
	v_mul_f32_e32 v53, v49, v53
	v_add_f32_e32 v50, 1.0, v50
	v_rcp_f32_e32 v52, v52
	v_max_f32_e32 v53, 0, v53
	v_rcp_f32_e32 v50, v50
	v_sqrt_f32_e32 v53, v53
; __device__ __forceinline__ unsigned cvt_pk_bf16(float lo, float hi) { const bf16x2_t r = __builtin_convertvector((f32x2){lo, hi}, bf16x2_t); return __builtin_bit_cast(unsigned, r); }
; __device__ __forceinline__ float bf_lo(unsigned w) { return __uint_as_float(w << 16); }
; __device__ __forceinline__ float bf_hi(unsigned w) { return __uint_as_float(w & 0xffff0000u); }
;     __device__ __forceinline__ void operator()(const AccT& acc, const Unit& u, int wr, int wc, int fr, int fq) const {
;     ...
;                 for (int m = 0; m < 4; ++m) { const size_t off = (size_t)(row0 + ai * HALF + m * 16) * DM + ch0 + 16 * n;
;                     const f32x4 rp = acc[ai][0][m][n] + bra, ip = acc[ai][1][m][n] + bri;
;                     const u32x2 w = xw[ai][m]; const float xv[4] = {bf_lo(w.x), bf_hi(w.x), bf_lo(w.y), bf_hi(w.y)};
;                     u32x4 o;
; #pragma unroll
;                     for (int j = 0; j < 4; ++j) { const float r = __builtin_amdgcn_rcpf(1.0f + __expf(-rp[j])), ig = __builtin_amdgcn_rcpf(1.0f + __expf(-ip[j])); const float la = sp[j] * r; const float d = 1.0f - __expf(la);
;                         o[j] = cvt_pk_bf16(d, __builtin_amdgcn_sqrtf(fmaxf(d * (2.0f - d), 0.f)) * (ig * xv[j])); }
;                     *(u32x4*)(AU + off) = o; }
	v_and_b32_e32 v57, 0xffff0000, v94
	v_mul_f32_e32 v52, v52, v57
	v_mul_f32_e32 v50, v50, v74
	v_mul_f32_e32 v52, v52, v53
	v_mul_f32_e32 v50, 0x3fb8aa3b, v50
	v_cvt_pk_bf16_f32 v49, v49, v52
	v_add_f32_e32 v52, v54, v66
	v_exp_f32_e32 v50, v50
	v_add_f32_e32 v51, v51, v71
	v_mul_f32_e32 v52, 0xbfb8aa3b, v52
	v_mul_f32_e32 v51, 0xbfb8aa3b, v51
	v_exp_f32_e32 v52, v52
	v_exp_f32_e32 v51, v51
	v_sub_f32_e32 v50, 1.0, v50
	v_sub_f32_e32 v53, 2.0, v50
	v_add_f32_e32 v52, 1.0, v52
	v_mul_f32_e32 v53, v50, v53
	v_add_f32_e32 v51, 1.0, v51
	v_rcp_f32_e32 v52, v52
	v_max_f32_e32 v53, 0, v53
	v_rcp_f32_e32 v51, v51
	v_sqrt_f32_e32 v53, v53
	v_add_f32_e32 v40, v40, v68
	v_mul_f32_e32 v40, 0xbfb8aa3b, v40
	v_lshlrev_b32_e32 v58, 16, v95
	v_exp_f32_e32 v40, v40
	v_mul_f32_e32 v52, v52, v58
	v_mul_f32_e32 v51, v51, v75
	v_mul_f32_e32 v52, v52, v53
	v_mul_f32_e32 v51, 0x3fb8aa3b, v51
	v_cvt_pk_bf16_f32 v50, v50, v52
	v_add_f32_e32 v52, v55, v67
	v_exp_f32_e32 v51, v51
	v_mul_f32_e32 v52, 0xbfb8aa3b, v52
	v_add_f32_e32 v40, 1.0, v40
	v_exp_f32_e32 v52, v52
	v_rcp_f32_e32 v40, v40
	v_sub_f32_e32 v51, 1.0, v51
	v_sub_f32_e32 v53, 2.0, v51
	v_add_f32_e32 v52, 1.0, v52
	v_mul_f32_e32 v53, v51, v53
	v_mul_f32_e32 v40, v40, v72
	v_rcp_f32_e32 v52, v52
	v_max_f32_e32 v53, 0, v53
	v_mul_f32_e32 v40, 0x3fb8aa3b, v40
	v_sqrt_f32_e32 v53, v53
	v_add_f32_e32 v44, v44, v64
	v_exp_f32_e32 v40, v40
	v_add_f32_e32 v41, v41, v69
	v_mul_f32_e32 v44, 0xbfb8aa3b, v44
	v_mul_f32_e32 v41, 0xbfb8aa3b, v41
	v_and_b32_e32 v59, 0xffff0000, v95
	v_exp_f32_e32 v44, v44
	v_exp_f32_e32 v41, v41
	v_mul_f32_e32 v52, v52, v59
	v_mul_f32_e32 v52, v52, v53
	v_sub_f32_e32 v40, 1.0, v40
	v_cvt_pk_bf16_f32 v51, v51, v52
	v_sub_f32_e32 v52, 2.0, v40
	v_add_f32_e32 v44, 1.0, v44
	v_mul_f32_e32 v52, v40, v52
	v_add_f32_e32 v41, 1.0, v41
	v_rcp_f32_e32 v44, v44
	v_max_f32_e32 v52, 0, v52
	v_rcp_f32_e32 v41, v41
	v_sqrt_f32_e32 v52, v52
	global_store_dwordx4 v[120:121], v[48:51], off offset:64
	v_add_f32_e32 v42, v42, v70
	v_mul_f32_e32 v41, v41, v73
	v_lshlrev_b32_e32 v48, 16, v92
	v_mul_f32_e32 v44, v44, v48
	v_mul_f32_e32 v44, v44, v52
	v_mul_f32_e32 v41, 0x3fb8aa3b, v41
	v_cvt_pk_bf16_f32 v40, v40, v44
	v_add_f32_e32 v44, v45, v65
	v_exp_f32_e32 v41, v41
	v_mul_f32_e32 v44, 0xbfb8aa3b, v44
	v_mul_f32_e32 v42, 0xbfb8aa3b, v42
	v_exp_f32_e32 v44, v44
	v_exp_f32_e32 v42, v42
	v_sub_f32_e32 v41, 1.0, v41
	v_sub_f32_e32 v45, 2.0, v41
	v_add_f32_e32 v44, 1.0, v44
	v_mul_f32_e32 v45, v41, v45
	v_add_f32_e32 v42, 1.0, v42
	v_rcp_f32_e32 v44, v44
	v_max_f32_e32 v45, 0, v45
	v_rcp_f32_e32 v42, v42
	v_sqrt_f32_e32 v45, v45
	v_and_b32_e32 v49, 0xffff0000, v92
	v_mul_f32_e32 v44, v44, v49
	v_mul_f32_e32 v42, v42, v74
	v_mul_f32_e32 v44, v44, v45
	v_mul_f32_e32 v42, 0x3fb8aa3b, v42
	v_cvt_pk_bf16_f32 v41, v41, v44
	v_add_f32_e32 v44, v46, v66
	v_exp_f32_e32 v42, v42
	v_add_f32_e32 v43, v43, v71
	v_mul_f32_e32 v44, 0xbfb8aa3b, v44
	v_mul_f32_e32 v43, 0xbfb8aa3b, v43
	v_exp_f32_e32 v44, v44
	v_exp_f32_e32 v43, v43
	v_sub_f32_e32 v42, 1.0, v42
	v_sub_f32_e32 v45, 2.0, v42
	v_add_f32_e32 v44, 1.0, v44
	v_mul_f32_e32 v45, v42, v45
	v_add_f32_e32 v43, 1.0, v43
	v_rcp_f32_e32 v44, v44
	v_max_f32_e32 v45, 0, v45
	v_rcp_f32_e32 v43, v43
	v_sqrt_f32_e32 v45, v45
	v_add_f32_e32 v32, v32, v68
	v_mul_f32_e32 v32, 0xbfb8aa3b, v32
	v_lshlrev_b32_e32 v50, 16, v93
	v_exp_f32_e32 v32, v32
	v_mul_f32_e32 v44, v44, v50
	v_mul_f32_e32 v43, v43, v75
	v_mul_f32_e32 v44, v44, v45
	v_mul_f32_e32 v43, 0x3fb8aa3b, v43
	v_cvt_pk_bf16_f32 v42, v42, v44
	v_add_f32_e32 v44, v47, v67
	v_exp_f32_e32 v43, v43
	v_mul_f32_e32 v44, 0xbfb8aa3b, v44
	v_add_f32_e32 v32, 1.0, v32
	v_exp_f32_e32 v44, v44
	v_rcp_f32_e32 v32, v32
	v_sub_f32_e32 v43, 1.0, v43
	v_sub_f32_e32 v45, 2.0, v43
	v_add_f32_e32 v44, 1.0, v44
	v_mul_f32_e32 v45, v43, v45
	v_mul_f32_e32 v32, v32, v72
	v_rcp_f32_e32 v44, v44
	v_max_f32_e32 v45, 0, v45
	v_mul_f32_e32 v32, 0x3fb8aa3b, v32
	v_sqrt_f32_e32 v45, v45
	v_add_f32_e32 v36, v36, v64
	v_exp_f32_e32 v32, v32
	v_add_f32_e32 v33, v33, v69
	v_mul_f32_e32 v36, 0xbfb8aa3b, v36
	v_mul_f32_e32 v33, 0xbfb8aa3b, v33
	v_and_b32_e32 v51, 0xffff0000, v93
	v_exp_f32_e32 v36, v36
	v_exp_f32_e32 v33, v33
	v_mul_f32_e32 v44, v44, v51
	v_mul_f32_e32 v44, v44, v45
	v_sub_f32_e32 v32, 1.0, v32
	v_cvt_pk_bf16_f32 v43, v43, v44
	v_sub_f32_e32 v44, 2.0, v32
	v_add_f32_e32 v36, 1.0, v36
	v_mul_f32_e32 v44, v32, v44
	v_add_f32_e32 v33, 1.0, v33
	v_rcp_f32_e32 v36, v36
	v_max_f32_e32 v44, 0, v44
	v_rcp_f32_e32 v33, v33
	v_sqrt_f32_e32 v44, v44
	global_store_dwordx4 v[112:113], v[40:43], off offset:64
	v_add_f32_e32 v34, v34, v70
	v_mul_f32_e32 v33, v33, v73
	v_lshlrev_b32_e32 v40, 16, v90
	v_mul_f32_e32 v36, v36, v40
	v_mul_f32_e32 v36, v36, v44
	v_mul_f32_e32 v33, 0x3fb8aa3b, v33
	v_cvt_pk_bf16_f32 v32, v32, v36
	v_add_f32_e32 v36, v37, v65
	v_exp_f32_e32 v33, v33
	v_mul_f32_e32 v36, 0xbfb8aa3b, v36
	v_mul_f32_e32 v34, 0xbfb8aa3b, v34
	v_exp_f32_e32 v36, v36
	v_exp_f32_e32 v34, v34
	v_sub_f32_e32 v33, 1.0, v33
	v_sub_f32_e32 v37, 2.0, v33
	v_add_f32_e32 v36, 1.0, v36
	v_mul_f32_e32 v37, v33, v37
	v_add_f32_e32 v34, 1.0, v34
	v_rcp_f32_e32 v36, v36
	v_max_f32_e32 v37, 0, v37
	v_rcp_f32_e32 v34, v34
	v_sqrt_f32_e32 v37, v37
	v_and_b32_e32 v41, 0xffff0000, v90
	v_mul_f32_e32 v36, v36, v41
	v_mul_f32_e32 v34, v34, v74
	v_mul_f32_e32 v36, v36, v37
	v_mul_f32_e32 v34, 0x3fb8aa3b, v34
	v_cvt_pk_bf16_f32 v33, v33, v36
	v_add_f32_e32 v36, v38, v66
	v_exp_f32_e32 v34, v34
	v_add_f32_e32 v35, v35, v71
	v_mul_f32_e32 v36, 0xbfb8aa3b, v36
	v_mul_f32_e32 v35, 0xbfb8aa3b, v35
	v_exp_f32_e32 v36, v36
	v_exp_f32_e32 v35, v35
	v_sub_f32_e32 v34, 1.0, v34
; __device__ __forceinline__ unsigned cvt_pk_bf16(float lo, float hi) { const bf16x2_t r = __builtin_convertvector((f32x2){lo, hi}, bf16x2_t); return __builtin_bit_cast(unsigned, r); }
; __device__ __forceinline__ float bf_lo(unsigned w) { return __uint_as_float(w << 16); }
; __device__ __forceinline__ float bf_hi(unsigned w) { return __uint_as_float(w & 0xffff0000u); }
;     __device__ __forceinline__ void operator()(const AccT& acc, const Unit& u, int wr, int wc, int fr, int fq) const {
;     ...
;                 for (int m = 0; m < 4; ++m) { const size_t off = (size_t)(row0 + ai * HALF + m * 16) * DM + ch0 + 16 * n;
;                     const f32x4 rp = acc[ai][0][m][n] + bra, ip = acc[ai][1][m][n] + bri;
;                     const u32x2 w = xw[ai][m]; const float xv[4] = {bf_lo(w.x), bf_hi(w.x), bf_lo(w.y), bf_hi(w.y)};
;                     u32x4 o;
; #pragma unroll
;                     for (int j = 0; j < 4; ++j) { const float r = __builtin_amdgcn_rcpf(1.0f + __expf(-rp[j])), ig = __builtin_amdgcn_rcpf(1.0f + __expf(-ip[j])); const float la = sp[j] * r; const float d = 1.0f - __expf(la);
;                         o[j] = cvt_pk_bf16(d, __builtin_amdgcn_sqrtf(fmaxf(d * (2.0f - d), 0.f)) * (ig * xv[j])); }
;                     *(u32x4*)(AU + off) = o; }
	v_sub_f32_e32 v37, 2.0, v34
	v_add_f32_e32 v36, 1.0, v36
	v_mul_f32_e32 v37, v34, v37
	v_add_f32_e32 v35, 1.0, v35
	v_rcp_f32_e32 v36, v36
	v_max_f32_e32 v37, 0, v37
	v_rcp_f32_e32 v35, v35
	v_sqrt_f32_e32 v37, v37
	v_add_f32_e32 v24, v24, v68
	v_mul_f32_e32 v24, 0xbfb8aa3b, v24
	v_lshlrev_b32_e32 v42, 16, v91
	v_exp_f32_e32 v24, v24
	v_mul_f32_e32 v36, v36, v42
	v_mul_f32_e32 v35, v35, v75
	v_mul_f32_e32 v36, v36, v37
	v_mul_f32_e32 v35, 0x3fb8aa3b, v35
	v_cvt_pk_bf16_f32 v34, v34, v36
	v_add_f32_e32 v36, v39, v67
	v_exp_f32_e32 v35, v35
	v_mul_f32_e32 v36, 0xbfb8aa3b, v36
	v_add_f32_e32 v24, 1.0, v24
	v_exp_f32_e32 v36, v36
	v_rcp_f32_e32 v24, v24
	v_sub_f32_e32 v35, 1.0, v35
	v_sub_f32_e32 v37, 2.0, v35
	v_add_f32_e32 v36, 1.0, v36
	v_mul_f32_e32 v37, v35, v37
	v_mul_f32_e32 v24, v24, v72
	v_rcp_f32_e32 v36, v36
	v_max_f32_e32 v37, 0, v37
	v_mul_f32_e32 v24, 0x3fb8aa3b, v24
	v_sqrt_f32_e32 v37, v37
	v_add_f32_e32 v28, v28, v64
	v_exp_f32_e32 v24, v24
	v_add_f32_e32 v25, v25, v69
	v_mul_f32_e32 v28, 0xbfb8aa3b, v28
	v_mul_f32_e32 v25, 0xbfb8aa3b, v25
	v_and_b32_e32 v43, 0xffff0000, v91
	v_exp_f32_e32 v28, v28
	v_exp_f32_e32 v25, v25
	v_mul_f32_e32 v36, v36, v43
	v_mul_f32_e32 v36, v36, v37
	v_sub_f32_e32 v24, 1.0, v24
	v_cvt_pk_bf16_f32 v35, v35, v36
	v_sub_f32_e32 v36, 2.0, v24
	v_add_f32_e32 v28, 1.0, v28
	v_mul_f32_e32 v36, v24, v36
	v_add_f32_e32 v25, 1.0, v25
	v_rcp_f32_e32 v28, v28
	v_max_f32_e32 v36, 0, v36
	v_rcp_f32_e32 v25, v25
	v_sqrt_f32_e32 v36, v36
	global_store_dwordx4 v[104:105], v[32:35], off offset:64
	v_add_f32_e32 v26, v26, v70
	v_mul_f32_e32 v25, v25, v73
	v_lshlrev_b32_e32 v32, 16, v86
	v_mul_f32_e32 v28, v28, v32
	v_mul_f32_e32 v28, v28, v36
	v_mul_f32_e32 v25, 0x3fb8aa3b, v25
	v_cvt_pk_bf16_f32 v24, v24, v28
	v_add_f32_e32 v28, v29, v65
	v_exp_f32_e32 v25, v25
	v_mul_f32_e32 v28, 0xbfb8aa3b, v28
	v_mul_f32_e32 v26, 0xbfb8aa3b, v26
	v_exp_f32_e32 v28, v28
	v_exp_f32_e32 v26, v26
	v_sub_f32_e32 v25, 1.0, v25
	v_sub_f32_e32 v29, 2.0, v25
	v_add_f32_e32 v28, 1.0, v28
	v_mul_f32_e32 v29, v25, v29
	v_add_f32_e32 v26, 1.0, v26
	v_rcp_f32_e32 v28, v28
	v_max_f32_e32 v29, 0, v29
	v_rcp_f32_e32 v26, v26
	v_sqrt_f32_e32 v29, v29
	v_and_b32_e32 v33, 0xffff0000, v86
	v_mul_f32_e32 v28, v28, v33
	v_mul_f32_e32 v26, v26, v74
	v_mul_f32_e32 v28, v28, v29
	v_mul_f32_e32 v26, 0x3fb8aa3b, v26
	v_cvt_pk_bf16_f32 v25, v25, v28
	v_add_f32_e32 v28, v30, v66
	v_exp_f32_e32 v26, v26
	v_add_f32_e32 v27, v27, v71
	v_mul_f32_e32 v28, 0xbfb8aa3b, v28
	v_mul_f32_e32 v27, 0xbfb8aa3b, v27
	v_exp_f32_e32 v28, v28
	v_exp_f32_e32 v27, v27
	v_sub_f32_e32 v26, 1.0, v26
	v_sub_f32_e32 v29, 2.0, v26
	v_add_f32_e32 v28, 1.0, v28
	v_mul_f32_e32 v29, v26, v29
	v_add_f32_e32 v27, 1.0, v27
	v_rcp_f32_e32 v28, v28
	v_max_f32_e32 v29, 0, v29
	v_rcp_f32_e32 v27, v27
	v_sqrt_f32_e32 v29, v29
	v_add_f32_e32 v16, v16, v68
	v_mul_f32_e32 v16, 0xbfb8aa3b, v16
	v_lshlrev_b32_e32 v34, 16, v87
	v_exp_f32_e32 v16, v16
	v_mul_f32_e32 v28, v28, v34
	v_mul_f32_e32 v27, v27, v75
	v_mul_f32_e32 v28, v28, v29
	v_mul_f32_e32 v27, 0x3fb8aa3b, v27
	v_cvt_pk_bf16_f32 v26, v26, v28
	v_add_f32_e32 v28, v31, v67
	v_exp_f32_e32 v27, v27
	v_mul_f32_e32 v28, 0xbfb8aa3b, v28
	v_add_f32_e32 v16, 1.0, v16
	v_exp_f32_e32 v28, v28
	v_rcp_f32_e32 v16, v16
	v_sub_f32_e32 v27, 1.0, v27
	v_sub_f32_e32 v29, 2.0, v27
	v_add_f32_e32 v28, 1.0, v28
	v_mul_f32_e32 v29, v27, v29
	v_mul_f32_e32 v16, v16, v72
	v_rcp_f32_e32 v28, v28
	v_max_f32_e32 v29, 0, v29
	v_mul_f32_e32 v16, 0x3fb8aa3b, v16
	v_sqrt_f32_e32 v29, v29
	v_add_f32_e32 v20, v20, v64
	v_exp_f32_e32 v16, v16
	v_add_f32_e32 v17, v17, v69
	v_mul_f32_e32 v20, 0xbfb8aa3b, v20
	v_mul_f32_e32 v17, 0xbfb8aa3b, v17
	v_and_b32_e32 v35, 0xffff0000, v87
	v_exp_f32_e32 v20, v20
	v_exp_f32_e32 v17, v17
	v_mul_f32_e32 v28, v28, v35
	v_mul_f32_e32 v28, v28, v29
	v_sub_f32_e32 v16, 1.0, v16
	v_cvt_pk_bf16_f32 v27, v27, v28
	v_sub_f32_e32 v28, 2.0, v16
	v_add_f32_e32 v20, 1.0, v20
	v_mul_f32_e32 v28, v16, v28
	v_add_f32_e32 v17, 1.0, v17
	v_rcp_f32_e32 v20, v20
	v_max_f32_e32 v28, 0, v28
	v_rcp_f32_e32 v17, v17
	v_sqrt_f32_e32 v28, v28
	global_store_dwordx4 v[96:97], v[24:27], off offset:64
	v_add_f32_e32 v18, v18, v70
	v_mul_f32_e32 v17, v17, v73
	v_lshlrev_b32_e32 v24, 16, v84
	v_mul_f32_e32 v20, v20, v24
	v_mul_f32_e32 v20, v20, v28
	v_mul_f32_e32 v17, 0x3fb8aa3b, v17
	v_cvt_pk_bf16_f32 v16, v16, v20
	v_add_f32_e32 v20, v21, v65
	v_exp_f32_e32 v17, v17
	v_mul_f32_e32 v20, 0xbfb8aa3b, v20
	v_mul_f32_e32 v18, 0xbfb8aa3b, v18
	v_exp_f32_e32 v20, v20
	v_exp_f32_e32 v18, v18
	v_sub_f32_e32 v17, 1.0, v17
	v_sub_f32_e32 v21, 2.0, v17
	v_add_f32_e32 v20, 1.0, v20
	v_mul_f32_e32 v21, v17, v21
	v_add_f32_e32 v18, 1.0, v18
	v_rcp_f32_e32 v20, v20
	v_max_f32_e32 v21, 0, v21
	v_rcp_f32_e32 v18, v18
	v_sqrt_f32_e32 v21, v21
	v_and_b32_e32 v25, 0xffff0000, v84
	v_mul_f32_e32 v20, v20, v25
	v_mul_f32_e32 v18, v18, v74
	v_mul_f32_e32 v20, v20, v21
	v_mul_f32_e32 v18, 0x3fb8aa3b, v18
	v_cvt_pk_bf16_f32 v17, v17, v20
	v_add_f32_e32 v20, v22, v66
	v_exp_f32_e32 v18, v18
	v_add_f32_e32 v19, v19, v71
	v_mul_f32_e32 v20, 0xbfb8aa3b, v20
	v_mul_f32_e32 v19, 0xbfb8aa3b, v19
	v_exp_f32_e32 v20, v20
	v_exp_f32_e32 v19, v19
	v_sub_f32_e32 v18, 1.0, v18
	v_sub_f32_e32 v21, 2.0, v18
	v_add_f32_e32 v20, 1.0, v20
	v_mul_f32_e32 v21, v18, v21
	v_add_f32_e32 v19, 1.0, v19
	v_rcp_f32_e32 v20, v20
	v_max_f32_e32 v21, 0, v21
	v_rcp_f32_e32 v19, v19
	v_sqrt_f32_e32 v21, v21
	v_add_f32_e32 v8, v8, v68
	v_mul_f32_e32 v8, 0xbfb8aa3b, v8
	v_lshlrev_b32_e32 v26, 16, v85
	v_exp_f32_e32 v8, v8
	v_mul_f32_e32 v20, v20, v26
; __device__ __forceinline__ unsigned cvt_pk_bf16(float lo, float hi) { const bf16x2_t r = __builtin_convertvector((f32x2){lo, hi}, bf16x2_t); return __builtin_bit_cast(unsigned, r); }
; __device__ __forceinline__ float bf_lo(unsigned w) { return __uint_as_float(w << 16); }
; __device__ __forceinline__ float bf_hi(unsigned w) { return __uint_as_float(w & 0xffff0000u); }
; template <class Epi>
; __device__ __forceinline__ void gemm_phase(LAS unsigned char* lds, const bf16_t* A, int lda, const bf16_t* Bt, int ldb, int M, int N, int K, int asel, const Epi& E, const int fixed_round = -1) {
;     ...
;         if (!has_next) break;
;     __device__ __forceinline__ void operator()(const AccT& acc, const Unit& u, int wr, int wc, int fr, int fq) const {
;     ...
;                 for (int m = 0; m < 4; ++m) { const size_t off = (size_t)(row0 + ai * HALF + m * 16) * DM + ch0 + 16 * n;
;                     const f32x4 rp = acc[ai][0][m][n] + bra, ip = acc[ai][1][m][n] + bri;
;                     const u32x2 w = xw[ai][m]; const float xv[4] = {bf_lo(w.x), bf_hi(w.x), bf_lo(w.y), bf_hi(w.y)};
;                     u32x4 o;
; #pragma unroll
;                     for (int j = 0; j < 4; ++j) { const float r = __builtin_amdgcn_rcpf(1.0f + __expf(-rp[j])), ig = __builtin_amdgcn_rcpf(1.0f + __expf(-ip[j])); const float la = sp[j] * r; const float d = 1.0f - __expf(la);
;                         o[j] = cvt_pk_bf16(d, __builtin_amdgcn_sqrtf(fmaxf(d * (2.0f - d), 0.f)) * (ig * xv[j])); }
;                     *(u32x4*)(AU + off) = o; }
	v_mul_f32_e32 v19, v19, v75
	v_mul_f32_e32 v20, v20, v21
	v_mul_f32_e32 v19, 0x3fb8aa3b, v19
	v_cvt_pk_bf16_f32 v18, v18, v20
	v_add_f32_e32 v20, v23, v67
	v_exp_f32_e32 v19, v19
	v_mul_f32_e32 v20, 0xbfb8aa3b, v20
	v_add_f32_e32 v8, 1.0, v8
	v_exp_f32_e32 v20, v20
	v_rcp_f32_e32 v8, v8
	v_sub_f32_e32 v19, 1.0, v19
	v_sub_f32_e32 v21, 2.0, v19
	v_add_f32_e32 v20, 1.0, v20
	v_mul_f32_e32 v21, v19, v21
	v_mul_f32_e32 v8, v8, v72
	v_rcp_f32_e32 v20, v20
	v_max_f32_e32 v21, 0, v21
	v_mul_f32_e32 v8, 0x3fb8aa3b, v8
	v_sqrt_f32_e32 v21, v21
	v_add_f32_e32 v12, v12, v64
	v_exp_f32_e32 v8, v8
	v_add_f32_e32 v9, v9, v69
	v_mul_f32_e32 v12, 0xbfb8aa3b, v12
	v_mul_f32_e32 v9, 0xbfb8aa3b, v9
	v_and_b32_e32 v27, 0xffff0000, v85
	v_exp_f32_e32 v12, v12
	v_exp_f32_e32 v9, v9
	v_mul_f32_e32 v20, v20, v27
	v_mul_f32_e32 v20, v20, v21
	v_sub_f32_e32 v8, 1.0, v8
	v_cvt_pk_bf16_f32 v19, v19, v20
	v_sub_f32_e32 v20, 2.0, v8
	v_add_f32_e32 v12, 1.0, v12
	v_mul_f32_e32 v20, v8, v20
	v_add_f32_e32 v9, 1.0, v9
	v_rcp_f32_e32 v12, v12
	v_max_f32_e32 v20, 0, v20
	v_rcp_f32_e32 v9, v9
	v_sqrt_f32_e32 v20, v20
	global_store_dwordx4 v[88:89], v[16:19], off offset:64
	v_add_f32_e32 v10, v10, v70
	v_mul_f32_e32 v9, v9, v73
	v_lshlrev_b32_e32 v16, 16, v82
	v_mul_f32_e32 v12, v12, v16
	v_mul_f32_e32 v12, v12, v20
	v_mul_f32_e32 v9, 0x3fb8aa3b, v9
	v_cvt_pk_bf16_f32 v8, v8, v12
	v_add_f32_e32 v12, v13, v65
	v_exp_f32_e32 v9, v9
	v_mul_f32_e32 v12, 0xbfb8aa3b, v12
	v_mul_f32_e32 v10, 0xbfb8aa3b, v10
	v_exp_f32_e32 v12, v12
	v_exp_f32_e32 v10, v10
	v_sub_f32_e32 v9, 1.0, v9
	v_sub_f32_e32 v13, 2.0, v9
	v_add_f32_e32 v12, 1.0, v12
	v_mul_f32_e32 v13, v9, v13
	v_add_f32_e32 v10, 1.0, v10
	v_rcp_f32_e32 v12, v12
	v_max_f32_e32 v13, 0, v13
	v_rcp_f32_e32 v10, v10
	v_sqrt_f32_e32 v13, v13
	v_and_b32_e32 v17, 0xffff0000, v82
	v_mul_f32_e32 v12, v12, v17
	v_mul_f32_e32 v10, v10, v74
	v_mul_f32_e32 v12, v12, v13
	v_mul_f32_e32 v10, 0x3fb8aa3b, v10
	v_cvt_pk_bf16_f32 v9, v9, v12
	v_add_f32_e32 v12, v14, v66
	v_exp_f32_e32 v10, v10
	v_add_f32_e32 v11, v11, v71
	v_mul_f32_e32 v12, 0xbfb8aa3b, v12
	v_mul_f32_e32 v11, 0xbfb8aa3b, v11
	v_exp_f32_e32 v12, v12
	v_exp_f32_e32 v11, v11
	v_sub_f32_e32 v10, 1.0, v10
	v_sub_f32_e32 v13, 2.0, v10
	v_add_f32_e32 v12, 1.0, v12
	v_mul_f32_e32 v13, v10, v13
	v_add_f32_e32 v11, 1.0, v11
	v_rcp_f32_e32 v12, v12
	v_max_f32_e32 v13, 0, v13
	v_rcp_f32_e32 v11, v11
	v_sqrt_f32_e32 v13, v13
	v_add_f32_e32 v0, v0, v68
	v_mul_f32_e32 v0, 0xbfb8aa3b, v0
	v_lshlrev_b32_e32 v18, 16, v83
	v_exp_f32_e32 v0, v0
	v_mul_f32_e32 v12, v12, v18
	v_mul_f32_e32 v11, v11, v75
	v_mul_f32_e32 v12, v12, v13
	v_mul_f32_e32 v11, 0x3fb8aa3b, v11
	v_cvt_pk_bf16_f32 v10, v10, v12
	v_add_f32_e32 v12, v15, v67
	v_exp_f32_e32 v11, v11
	v_mul_f32_e32 v12, 0xbfb8aa3b, v12
	v_add_f32_e32 v0, 1.0, v0
	v_exp_f32_e32 v12, v12
	v_rcp_f32_e32 v0, v0
	v_sub_f32_e32 v11, 1.0, v11
	v_sub_f32_e32 v13, 2.0, v11
	v_add_f32_e32 v12, 1.0, v12
	v_mul_f32_e32 v13, v11, v13
	v_mul_f32_e32 v0, v0, v72
	v_rcp_f32_e32 v12, v12
	v_max_f32_e32 v13, 0, v13
	v_mul_f32_e32 v0, 0x3fb8aa3b, v0
	v_sqrt_f32_e32 v13, v13
	v_add_f32_e32 v4, v4, v64
	v_exp_f32_e32 v0, v0
	v_add_f32_e32 v1, v1, v69
	v_mul_f32_e32 v4, 0xbfb8aa3b, v4
	v_mul_f32_e32 v1, 0xbfb8aa3b, v1
	v_and_b32_e32 v19, 0xffff0000, v83
	v_exp_f32_e32 v4, v4
	v_exp_f32_e32 v1, v1
	v_mul_f32_e32 v12, v12, v19
	v_mul_f32_e32 v12, v12, v13
	v_sub_f32_e32 v0, 1.0, v0
	v_cvt_pk_bf16_f32 v11, v11, v12
	v_sub_f32_e32 v12, 2.0, v0
	v_add_f32_e32 v4, 1.0, v4
	v_mul_f32_e32 v12, v0, v12
	v_add_f32_e32 v1, 1.0, v1
	v_rcp_f32_e32 v4, v4
	v_max_f32_e32 v12, 0, v12
	v_rcp_f32_e32 v1, v1
	v_sqrt_f32_e32 v12, v12
	global_store_dwordx4 v[80:81], v[8:11], off offset:64
	v_add_f32_e32 v2, v2, v70
	v_mul_f32_e32 v1, v1, v73
	v_lshlrev_b32_e32 v8, 16, v78
	v_mul_f32_e32 v4, v4, v8
	v_mul_f32_e32 v4, v4, v12
	v_mul_f32_e32 v1, 0x3fb8aa3b, v1
	v_cvt_pk_bf16_f32 v0, v0, v4
	v_add_f32_e32 v4, v5, v65
	v_exp_f32_e32 v1, v1
	v_mul_f32_e32 v4, 0xbfb8aa3b, v4
	v_mul_f32_e32 v2, 0xbfb8aa3b, v2
	v_exp_f32_e32 v4, v4
	v_exp_f32_e32 v2, v2
	v_sub_f32_e32 v1, 1.0, v1
	v_sub_f32_e32 v5, 2.0, v1
	v_add_f32_e32 v4, 1.0, v4
	v_mul_f32_e32 v5, v1, v5
	v_add_f32_e32 v2, 1.0, v2
	v_rcp_f32_e32 v4, v4
	v_max_f32_e32 v5, 0, v5
	v_rcp_f32_e32 v2, v2
	v_sqrt_f32_e32 v5, v5
	v_and_b32_e32 v9, 0xffff0000, v78
	v_mul_f32_e32 v4, v4, v9
	v_mul_f32_e32 v2, v2, v74
	v_mul_f32_e32 v4, v4, v5
	v_mul_f32_e32 v2, 0x3fb8aa3b, v2
	v_cvt_pk_bf16_f32 v1, v1, v4
	v_add_f32_e32 v4, v6, v66
	v_exp_f32_e32 v2, v2
	v_add_f32_e32 v3, v3, v71
	v_mul_f32_e32 v4, 0xbfb8aa3b, v4
	v_mul_f32_e32 v3, 0xbfb8aa3b, v3
	v_exp_f32_e32 v4, v4
	v_exp_f32_e32 v3, v3
	v_sub_f32_e32 v2, 1.0, v2
	v_sub_f32_e32 v5, 2.0, v2
	v_add_f32_e32 v4, 1.0, v4
	v_mul_f32_e32 v5, v2, v5
	v_add_f32_e32 v3, 1.0, v3
	v_rcp_f32_e32 v4, v4
	v_max_f32_e32 v5, 0, v5
	v_rcp_f32_e32 v3, v3
	v_sqrt_f32_e32 v5, v5
	v_lshlrev_b32_e32 v10, 16, v79
	v_mul_f32_e32 v4, v4, v10
	v_mul_f32_e32 v3, v3, v75
	v_mul_f32_e32 v4, v4, v5
	v_mul_f32_e32 v3, 0x3fb8aa3b, v3
	v_cvt_pk_bf16_f32 v2, v2, v4
	v_add_f32_e32 v4, v7, v67
	v_exp_f32_e32 v3, v3
	v_mul_f32_e32 v4, 0xbfb8aa3b, v4
	v_exp_f32_e32 v4, v4
	v_and_b32_e32 v11, 0xffff0000, v79
	v_sub_f32_e32 v3, 1.0, v3
	v_sub_f32_e32 v5, 2.0, v3
	v_add_f32_e32 v4, 1.0, v4
	v_mul_f32_e32 v5, v3, v5
	v_rcp_f32_e32 v4, v4
	v_max_f32_e32 v5, 0, v5
	v_sqrt_f32_e32 v5, v5
	s_andn2_b64 vcc, exec, s[4:5]
	v_mul_f32_e32 v4, v4, v11
	v_mul_f32_e32 v4, v4, v5
	v_cvt_pk_bf16_f32 v3, v3, v4
	global_store_dwordx4 v[76:77], v[0:3], off offset:64
	s_cbranch_vccz .LBB0_946
